# attention loop: half of the waves take the per-step barrier between QK and PV (4-slot V ring); LDS-DMA blocks without m0 save/restore and s_nop 0
# speedup vs baseline: 1.0086x; 1.0086x over previous
.LBB0_200:
	s_lshl_b32 s1, s90, 10
	v_lshlrev_b32_e32 v1, 4, v0
	v_add_u32_e32 v2, s1, v1
	v_ashrrev_i32_e32 v3, 31, v2
	v_lshrrev_b32_e32 v3, 22, v3
	v_add_u32_e32 v3, v2, v3
	v_ashrrev_i32_e32 v3, 10, v3
	v_mul_i32_i24_e32 v4, 0x400, v3
	v_sub_u32_e32 v4, v2, v4
	v_lshrrev_b32_e32 v5, 4, v4
	v_bitop3_b32 v4, v5, v4, 32 bitop3:0x6c
	v_ashrrev_i32_e32 v6, 31, v4
	v_lshrrev_b32_e32 v6, 26, v6
	v_lshlrev_b32_e32 v5, 3, v3
	v_add_u32_e32 v6, v4, v6
	v_and_b32_e32 v5, -16, v5
	v_ashrrev_i32_e32 v7, 6, v6
	v_and_b32_e32 v6, 0xc0, v6
	v_add_u32_e32 v5, v7, v5
	v_sub_u32_e32 v4, v4, v6
	v_mov_b32_e32 v6, 1
	v_lshlrev_b32_e32 v3, 5, v3
	v_ashrrev_i16_sdwa v4, v6, sext(v4) dst_sel:DWORD dst_unused:UNUSED_PAD src0_sel:DWORD src1_sel:BYTE_0
	v_lshlrev_b32_e32 v8, 1, v5
	v_lshrrev_b32_e32 v9, 2, v5
	v_and_b32_e32 v7, 3, v7
	s_mov_b32 s0, 0x1fffe0
	v_and_b32_e32 v3, 32, v3
	v_bfe_i32 v4, v4, 0, 16
	v_and_b32_e32 v8, 24, v8
	v_and_b32_e32 v9, 4, v9
	v_and_or_b32 v7, v5, s0, v7
	v_or3_b32 v7, v7, v9, v8
	v_add_lshl_u32 v3, v3, v4, 1
	v_add_u32_e32 v2, 0x2000, v2
	v_lshl_add_u32 v142, v5, 11, v3
	v_lshl_add_u32 v143, v7, 11, v3
	v_ashrrev_i32_e32 v3, 31, v2
	v_lshrrev_b32_e32 v3, 22, v3
	v_add_u32_e32 v3, v2, v3
	v_ashrrev_i32_e32 v3, 10, v3
	v_mul_i32_i24_e32 v4, 0x400, v3
	v_sub_u32_e32 v2, v2, v4
	v_lshrrev_b32_e32 v4, 4, v2
	v_bitop3_b32 v2, v4, v2, 32 bitop3:0x6c
	v_ashrrev_i32_e32 v5, 31, v2
	v_lshrrev_b32_e32 v5, 26, v5
	v_lshlrev_b32_e32 v4, 3, v3
	v_add_u32_e32 v5, v2, v5
	v_and_b32_e32 v4, -16, v4
	v_ashrrev_i32_e32 v7, 6, v5
	v_add_u32_e32 v4, v7, v4
	v_and_b32_e32 v7, 3, v7
	v_and_or_b32 v7, v4, s0, v7
	s_lshr_b32 s0, s91, 8
	v_and_b32_e32 v5, 0xffc0, v5
	s_add_u32 s55, s22, 0x1800000
	v_sub_u32_e32 v2, v2, v5
	s_addc_u32 s56, s23, 0
	v_lshrrev_b16_e32 v5, 7, v2
	s_add_u32 s57, s22, 0x800000
	v_and_b32_e32 v5, 1, v5
	s_addc_u32 s58, s23, 0
	s_ashr_i32 s3, s2, 31
	s_ashr_i32 s43, s42, 31
	v_add_u16_e32 v2, v2, v5
	s_lshl_b64 s[4:5], s[2:3], 19
	s_lshl_b64 s[6:7], s[42:43], 19
	v_lshlrev_b32_e32 v3, 5, v3
	v_ashrrev_i16_sdwa v2, v6, sext(v2) dst_sel:DWORD dst_unused:UNUSED_PAD src0_sel:DWORD src1_sel:BYTE_0
	v_lshlrev_b32_e32 v5, 1, v4
	v_lshrrev_b32_e32 v6, 2, v4
	s_add_u32 s44, s57, s6
	v_and_b32_e32 v3, 32, v3
	v_bfe_i32 v2, v2, 0, 16
	v_and_b32_e32 v5, 24, v5
	v_and_b32_e32 v6, 4, v6
	s_addc_u32 s45, s58, s7
	s_add_i32 s43, s1, 0
	v_or3_b32 v5, v7, v6, v5
	v_add_lshl_u32 v2, v3, v2, 1
	s_add_i32 s60, s43, 0x10000
	s_mov_b32 m0, s60
	s_nop 0
	global_load_lds_dwordx4 v143, s[44:45]
	s_add_i32 s61, s43, 0x12000
	v_lshl_add_u32 v145, v5, 11, v2
	s_mov_b32 m0, s61
	s_nop 0
	global_load_lds_dwordx4 v145, s[44:45]
	s_add_u32 s6, s44, 0x40000
	s_addc_u32 s7, s45, 0
	s_add_i32 s62, s43, 0x14000
	s_mov_b32 m0, s62
	s_nop 0
	global_load_lds_dwordx4 v143, s[6:7]
	s_add_i32 s63, s43, 0x16000
	s_mov_b32 m0, s63
	s_nop 0
	global_load_lds_dwordx4 v145, s[6:7]
	s_add_u32 s4, s55, s4
	s_addc_u32 s5, s56, s5
	s_mov_b32 m0, s43
	s_nop 0
	global_load_lds_dwordx4 v142, s[4:5]
	s_add_i32 s64, s43, 0x2000
	v_lshl_add_u32 v144, v4, 11, v2
	s_mov_b32 m0, s64
	s_nop 0
	global_load_lds_dwordx4 v144, s[4:5]
	s_add_u32 s8, s4, 0x40000
	s_addc_u32 s9, s5, 0
	s_add_i32 s65, s43, 0x4000
	s_mov_b32 m0, s65
	s_nop 0
	global_load_lds_dwordx4 v142, s[8:9]
	s_add_i32 s66, s43, 0x6000
	s_mov_b32 m0, s66
	s_nop 0
	global_load_lds_dwordx4 v144, s[8:9]
	s_cmp_eq_u32 s0, 1
	s_mov_b32 s37, s73
	s_mov_b32 s59, 0
	s_cselect_b64 s[6:7], -1, 0
	s_cmp_lg_u32 s0, 1
	s_cbranch_scc1 .LBB0_202
	s_barrier
.LBB0_202:
	s_bfe_u32 s3, s91, 0x20006
	s_lshl_b32 s67, s0, 6
	s_lshl_b32 s68, s3, 5
	s_add_u32 s8, s22, 0x3800000
	s_addc_u32 s9, s23, 0
	s_add_u32 s10, s22, 0x3800300
	s_addc_u32 s11, s23, 0
	s_add_u32 s12, s22, 0xc00000
	s_addc_u32 s13, s23, 0
	s_add_u32 s14, s22, 0xb000000
	s_addc_u32 s15, s23, 0
	v_and_b32_e32 v1, 0xfffffc00, v1
	s_add_u32 s16, s22, 0xd000000
	v_and_b32_e32 v2, 48, v0
	v_lshl_add_u32 v3, s0, 13, v1
	v_lshlrev_b32_e32 v4, 6, v0
	s_movk_i32 s0, 0x3c0
	s_addc_u32 s17, s23, 0
	v_and_or_b32 v2, v4, s0, v2
	s_add_u32 s0, s44, 0x80
	s_waitcnt vmcnt(2)
	s_barrier
	s_addc_u32 s1, s45, 0
	s_add_i32 s69, s43, 0x18000
	s_mov_b32 m0, s69
	s_nop 0
	global_load_lds_dwordx4 v143, s[0:1]
	s_add_i32 s70, s43, 0x1a000
	s_mov_b32 m0, s70
	s_nop 0
	global_load_lds_dwordx4 v145, s[0:1]
	s_add_u32 s0, s4, 0x80
	s_addc_u32 s1, s5, 0
	s_add_i32 s71, s43, 0x8000
	s_mov_b32 m0, s71
	s_nop 0
	global_load_lds_dwordx4 v142, s[0:1]
	s_add_i32 s72, s43, 0xa000
	s_mov_b32 m0, s72
	s_nop 0
	global_load_lds_dwordx4 v144, s[0:1]
	s_add_u32 s0, s44, 0x40080
	s_addc_u32 s1, s45, 0
	s_add_i32 s73, s43, 0x1c000
	s_mov_b32 m0, s73
	s_nop 0
	global_load_lds_dwordx4 v143, s[0:1]
	s_add_i32 s74, s43, 0x1e000
	s_add_i32 s75, s43, 0xc000
	s_mov_b32 m0, s74
	s_nop 0
	global_load_lds_dwordx4 v145, s[0:1]
	s_cmpk_lt_u32 s91, 0x100
	s_cselect_b64 s[18:19], -1, 0
	s_cmp_eq_u32 s3, 0
	s_cselect_b64 s[20:21], -1, 0
	s_or_b32 s76, s68, 0xfffffd00
	s_add_i32 s77, s43, 0xe000
	s_lshl_b32 s0, s3, 2
	s_add_u32 s0, s22, s0
	v_lshlrev_b32_e32 v0, 2, v0
	s_addc_u32 s1, s23, 0
	v_and_b32_e32 v0, 32, v0
	v_lshl_add_u32 v1, s3, 12, v1
	s_add_u32 s22, s0, 0x300000
	v_bitop3_b32 v3, v2, v3, v0 bitop3:0xde
	v_bitop3_b32 v0, v2, v1, v0 bitop3:0xde
	s_waitcnt vmcnt(6)
	s_addc_u32 s23, s1, 0
	s_add_u32 s24, s0, 0x400000
	v_add_u32_e32 v0, 0, v0
	s_addc_u32 s25, s1, 0
	v_mov_b64_e32 v[128:129], 0x200
	v_mov_b64_e32 v[130:131], 0x1ff
	s_mov_b64 s[26:27], 0x100
	v_add_u32_e32 v146, 0x10000, v0
	v_add_u32_e32 v147, 0x14000, v0
	v_add_u32_e32 v148, 0, v3
	v_add_u32_e32 v149, 0x18000, v0
	v_add_u32_e32 v150, 0x1c000, v0
	s_movk_i32 s78, 0x500
	s_mov_b32 s28, 0x3e38aa3b
	s_mov_b32 s30, 0xbfb8aa3b
	s_barrier
	s_branch .LBB0_205

.LBB0_212:
	ds_read_b128 v[132:135], v146
	ds_read_b128 v[136:139], v146 offset:1024
	ds_read_b128 v[152:155], v146 offset:2048
	ds_read_b128 v[156:159], v146 offset:3072
	ds_read_b128 v[160:163], v147
	ds_read_b128 v[164:167], v147 offset:1024
	ds_read_b128 v[168:171], v147 offset:2048
	ds_read_b128 v[172:175], v147 offset:3072
	s_add_u32 s44, s4, 0x100
	s_addc_u32 s45, s5, 0
	s_cmp_eq_u32 s82, 12
	s_cselect_b32 s52, s37, s44
	s_cselect_b32 s53, s3, s45
	s_cselect_b32 s48, s79, s80
	s_cselect_b32 s49, s35, s81
	s_add_u32 s46, s52, 0x80
	s_addc_u32 s47, s53, 0
	ds_read_b128 v[176:179], v148
	ds_read_b128 v[180:183], v148 offset:1024
	ds_read_b128 v[184:187], v148 offset:2048
	ds_read_b128 v[188:191], v148 offset:3072
	ds_read_b128 v[192:195], v148 offset:4096
	ds_read_b128 v[196:199], v148 offset:5120
	ds_read_b128 v[200:203], v148 offset:6144
	ds_read_b128 v[204:207], v148 offset:7168
	s_add_u32 s4, s4, 0x40080
	s_addc_u32 s5, s5, 0
	s_mov_b32 m0, s75
	s_nop 0
	global_load_lds_dwordx4 v142, s[4:5]
	s_nop 0
	s_mov_b32 m0, s77
	s_nop 0
	global_load_lds_dwordx4 v144, s[4:5]
	s_waitcnt vmcnt(8)
	s_waitcnt lgkmcnt(0)
	s_barrier
	s_setprio 1
	s_waitcnt lgkmcnt(7)
	v_mfma_f32_16x16x32_f16 v[124:127], v[132:135], v[176:179], v[124:127]
	v_mfma_f32_16x16x32_f16 v[120:123], v[152:155], v[176:179], v[120:123]
	s_waitcnt lgkmcnt(5)
	v_mfma_f32_16x16x32_f16 v[108:111], v[132:135], v[184:187], v[108:111]
	v_mfma_f32_16x16x32_f16 v[104:107], v[152:155], v[184:187], v[104:107]
	s_waitcnt lgkmcnt(3)
	v_mfma_f32_16x16x32_f16 v[92:95], v[132:135], v[192:195], v[92:95]
	v_mfma_f32_16x16x32_f16 v[88:91], v[152:155], v[192:195], v[88:91]
	s_waitcnt lgkmcnt(1)
	v_mfma_f32_16x16x32_f16 v[76:79], v[132:135], v[200:203], v[76:79]
	v_mfma_f32_16x16x32_f16 v[72:75], v[152:155], v[200:203], v[72:75]
	v_mfma_f32_16x16x32_f16 v[124:127], v[136:139], v[180:183], v[124:127]
	v_mfma_f32_16x16x32_f16 v[120:123], v[156:159], v[180:183], v[120:123]
	v_mfma_f32_16x16x32_f16 v[108:111], v[136:139], v[188:191], v[108:111]
	v_mfma_f32_16x16x32_f16 v[104:107], v[156:159], v[188:191], v[104:107]
	v_mfma_f32_16x16x32_f16 v[92:95], v[136:139], v[196:199], v[92:95]
	v_mfma_f32_16x16x32_f16 v[88:91], v[156:159], v[196:199], v[88:91]
	s_waitcnt lgkmcnt(0)
	v_mfma_f32_16x16x32_f16 v[76:79], v[136:139], v[204:207], v[76:79]
	v_mfma_f32_16x16x32_f16 v[72:75], v[156:159], v[204:207], v[72:75]
	s_setprio 0
	s_setprio 1
	v_mfma_f32_16x16x32_f16 v[116:119], v[160:163], v[176:179], v[116:119]
	v_mfma_f32_16x16x32_f16 v[112:115], v[168:171], v[176:179], v[112:115]
	v_mfma_f32_16x16x32_f16 v[100:103], v[160:163], v[184:187], v[100:103]
	v_mfma_f32_16x16x32_f16 v[96:99], v[168:171], v[184:187], v[96:99]
	v_mfma_f32_16x16x32_f16 v[84:87], v[160:163], v[192:195], v[84:87]
	v_mfma_f32_16x16x32_f16 v[80:83], v[168:171], v[192:195], v[80:83]
	v_mfma_f32_16x16x32_f16 v[68:71], v[160:163], v[200:203], v[68:71]
	v_mfma_f32_16x16x32_f16 v[64:67], v[168:171], v[200:203], v[64:67]
	v_mfma_f32_16x16x32_f16 v[116:119], v[164:167], v[180:183], v[116:119]
	v_mfma_f32_16x16x32_f16 v[112:115], v[172:175], v[180:183], v[112:115]
	v_mfma_f32_16x16x32_f16 v[100:103], v[164:167], v[188:191], v[100:103]
	v_mfma_f32_16x16x32_f16 v[96:99], v[172:175], v[188:191], v[96:99]
	v_mfma_f32_16x16x32_f16 v[84:87], v[164:167], v[196:199], v[84:87]
	v_mfma_f32_16x16x32_f16 v[80:83], v[172:175], v[196:199], v[80:83]
	v_mfma_f32_16x16x32_f16 v[68:71], v[164:167], v[204:207], v[68:71]
	v_mfma_f32_16x16x32_f16 v[64:67], v[172:175], v[204:207], v[64:67]
	s_setprio 0
	s_barrier
	ds_read_b128 v[176:179], v148 offset:16384
	ds_read_b128 v[180:183], v148 offset:17408
	ds_read_b128 v[184:187], v148 offset:18432
	ds_read_b128 v[188:191], v148 offset:19456
	ds_read_b128 v[192:195], v148 offset:20480
	ds_read_b128 v[196:199], v148 offset:21504
	ds_read_b128 v[200:203], v148 offset:22528
	ds_read_b128 v[204:207], v148 offset:23552
	s_mov_b32 m0, s60
	s_nop 0
	global_load_lds_dwordx4 v143, s[48:49]
	s_nop 0
	s_mov_b32 m0, s61
	s_nop 0
	global_load_lds_dwordx4 v145, s[48:49]
	s_add_u32 s4, s48, 0x40000
	s_addc_u32 s5, s49, 0
	s_mov_b32 m0, s62
	s_nop 0
	global_load_lds_dwordx4 v143, s[4:5]
	s_nop 0
	s_mov_b32 m0, s63
	s_nop 0
	global_load_lds_dwordx4 v145, s[4:5]
	s_mov_b32 m0, s43
	s_nop 0
	global_load_lds_dwordx4 v142, s[52:53]
	s_nop 0
	s_mov_b32 m0, s64
	s_nop 0
	global_load_lds_dwordx4 v144, s[52:53]
	s_waitcnt vmcnt(8)
	s_waitcnt lgkmcnt(0)
	s_barrier
	s_setprio 1
	s_waitcnt lgkmcnt(7)
	v_mfma_f32_16x16x32_f16 v[60:63], v[132:135], v[176:179], v[60:63]
	v_mfma_f32_16x16x32_f16 v[56:59], v[152:155], v[176:179], v[56:59]
	s_waitcnt lgkmcnt(5)
	v_mfma_f32_16x16x32_f16 v[44:47], v[132:135], v[184:187], v[44:47]
	v_mfma_f32_16x16x32_f16 v[40:43], v[152:155], v[184:187], v[40:43]
	s_waitcnt lgkmcnt(3)
	v_mfma_f32_16x16x32_f16 v[28:31], v[132:135], v[192:195], v[28:31]
	v_mfma_f32_16x16x32_f16 v[24:27], v[152:155], v[192:195], v[24:27]
	s_waitcnt lgkmcnt(1)
	v_mfma_f32_16x16x32_f16 v[12:15], v[132:135], v[200:203], v[12:15]
	v_mfma_f32_16x16x32_f16 v[8:11], v[152:155], v[200:203], v[8:11]
	v_mfma_f32_16x16x32_f16 v[60:63], v[136:139], v[180:183], v[60:63]
	v_mfma_f32_16x16x32_f16 v[56:59], v[156:159], v[180:183], v[56:59]
	v_mfma_f32_16x16x32_f16 v[44:47], v[136:139], v[188:191], v[44:47]
	v_mfma_f32_16x16x32_f16 v[40:43], v[156:159], v[188:191], v[40:43]
	v_mfma_f32_16x16x32_f16 v[28:31], v[136:139], v[196:199], v[28:31]
	v_mfma_f32_16x16x32_f16 v[24:27], v[156:159], v[196:199], v[24:27]
	s_waitcnt lgkmcnt(0)
	v_mfma_f32_16x16x32_f16 v[12:15], v[136:139], v[204:207], v[12:15]
	v_mfma_f32_16x16x32_f16 v[8:11], v[156:159], v[204:207], v[8:11]
	s_setprio 0
	s_setprio 1
	v_mfma_f32_16x16x32_f16 v[52:55], v[160:163], v[176:179], v[52:55]
	v_mfma_f32_16x16x32_f16 v[48:51], v[168:171], v[176:179], v[48:51]
	v_mfma_f32_16x16x32_f16 v[36:39], v[160:163], v[184:187], v[36:39]
	v_mfma_f32_16x16x32_f16 v[32:35], v[168:171], v[184:187], v[32:35]
	v_mfma_f32_16x16x32_f16 v[20:23], v[160:163], v[192:195], v[20:23]
	v_mfma_f32_16x16x32_f16 v[16:19], v[168:171], v[192:195], v[16:19]
	v_mfma_f32_16x16x32_f16 v[4:7], v[160:163], v[200:203], v[4:7]
	v_mfma_f32_16x16x32_f16 v[0:3], v[168:171], v[200:203], v[0:3]
	v_mfma_f32_16x16x32_f16 v[52:55], v[164:167], v[180:183], v[52:55]
	v_mfma_f32_16x16x32_f16 v[48:51], v[172:175], v[180:183], v[48:51]
	v_mfma_f32_16x16x32_f16 v[36:39], v[164:167], v[188:191], v[36:39]
	v_mfma_f32_16x16x32_f16 v[32:35], v[172:175], v[188:191], v[32:35]
	v_mfma_f32_16x16x32_f16 v[20:23], v[164:167], v[196:199], v[20:23]
	v_mfma_f32_16x16x32_f16 v[16:19], v[172:175], v[196:199], v[16:19]
	v_mfma_f32_16x16x32_f16 v[4:7], v[164:167], v[204:207], v[4:7]
	v_mfma_f32_16x16x32_f16 v[0:3], v[172:175], v[204:207], v[0:3]
	s_setprio 0
	s_barrier
	ds_read_b128 v[132:135], v149
	ds_read_b128 v[136:139], v149 offset:1024
	ds_read_b128 v[152:155], v149 offset:2048
	ds_read_b128 v[156:159], v149 offset:3072
	ds_read_b128 v[160:163], v150
	ds_read_b128 v[164:167], v150 offset:1024
	ds_read_b128 v[168:171], v150 offset:2048
	ds_read_b128 v[172:175], v150 offset:3072
	ds_read_b128 v[176:179], v148 offset:32768
	ds_read_b128 v[180:183], v148 offset:33792
	ds_read_b128 v[184:187], v148 offset:34816
	ds_read_b128 v[188:191], v148 offset:35840
	ds_read_b128 v[192:195], v148 offset:36864
	ds_read_b128 v[196:199], v148 offset:37888
	ds_read_b128 v[200:203], v148 offset:38912
	ds_read_b128 v[204:207], v148 offset:39936
	s_add_u32 s4, s52, 0x40000
	s_addc_u32 s5, s53, 0
	s_mov_b32 m0, s65
	s_nop 0
	global_load_lds_dwordx4 v142, s[4:5]
	s_nop 0
	s_mov_b32 m0, s66
	s_nop 0
	global_load_lds_dwordx4 v144, s[4:5]
	s_waitcnt vmcnt(8)
	s_waitcnt lgkmcnt(0)
	s_barrier
	s_setprio 1
	s_waitcnt lgkmcnt(7)
	v_mfma_f32_16x16x32_f16 v[124:127], v[132:135], v[176:179], v[124:127]
	v_mfma_f32_16x16x32_f16 v[120:123], v[152:155], v[176:179], v[120:123]
	s_waitcnt lgkmcnt(5)
	v_mfma_f32_16x16x32_f16 v[108:111], v[132:135], v[184:187], v[108:111]
	v_mfma_f32_16x16x32_f16 v[104:107], v[152:155], v[184:187], v[104:107]
	s_waitcnt lgkmcnt(3)
	v_mfma_f32_16x16x32_f16 v[92:95], v[132:135], v[192:195], v[92:95]
	v_mfma_f32_16x16x32_f16 v[88:91], v[152:155], v[192:195], v[88:91]
	s_waitcnt lgkmcnt(1)
	v_mfma_f32_16x16x32_f16 v[76:79], v[132:135], v[200:203], v[76:79]
	v_mfma_f32_16x16x32_f16 v[72:75], v[152:155], v[200:203], v[72:75]
	v_mfma_f32_16x16x32_f16 v[124:127], v[136:139], v[180:183], v[124:127]
	v_mfma_f32_16x16x32_f16 v[120:123], v[156:159], v[180:183], v[120:123]
	v_mfma_f32_16x16x32_f16 v[108:111], v[136:139], v[188:191], v[108:111]
	v_mfma_f32_16x16x32_f16 v[104:107], v[156:159], v[188:191], v[104:107]
	v_mfma_f32_16x16x32_f16 v[92:95], v[136:139], v[196:199], v[92:95]
	v_mfma_f32_16x16x32_f16 v[88:91], v[156:159], v[196:199], v[88:91]
	s_waitcnt lgkmcnt(0)
	v_mfma_f32_16x16x32_f16 v[76:79], v[136:139], v[204:207], v[76:79]
	v_mfma_f32_16x16x32_f16 v[72:75], v[156:159], v[204:207], v[72:75]
	s_setprio 0
	s_setprio 1
	v_mfma_f32_16x16x32_f16 v[116:119], v[160:163], v[176:179], v[116:119]
	v_mfma_f32_16x16x32_f16 v[112:115], v[168:171], v[176:179], v[112:115]
	v_mfma_f32_16x16x32_f16 v[100:103], v[160:163], v[184:187], v[100:103]
	v_mfma_f32_16x16x32_f16 v[96:99], v[168:171], v[184:187], v[96:99]
	v_mfma_f32_16x16x32_f16 v[84:87], v[160:163], v[192:195], v[84:87]
	v_mfma_f32_16x16x32_f16 v[80:83], v[168:171], v[192:195], v[80:83]
	v_mfma_f32_16x16x32_f16 v[68:71], v[160:163], v[200:203], v[68:71]
	v_mfma_f32_16x16x32_f16 v[64:67], v[168:171], v[200:203], v[64:67]
	v_mfma_f32_16x16x32_f16 v[116:119], v[164:167], v[180:183], v[116:119]
	v_mfma_f32_16x16x32_f16 v[112:115], v[172:175], v[180:183], v[112:115]
	v_mfma_f32_16x16x32_f16 v[100:103], v[164:167], v[188:191], v[100:103]
	v_mfma_f32_16x16x32_f16 v[96:99], v[172:175], v[188:191], v[96:99]
	v_mfma_f32_16x16x32_f16 v[84:87], v[164:167], v[196:199], v[84:87]
	v_mfma_f32_16x16x32_f16 v[80:83], v[172:175], v[196:199], v[80:83]
	v_mfma_f32_16x16x32_f16 v[68:71], v[164:167], v[204:207], v[68:71]
	v_mfma_f32_16x16x32_f16 v[64:67], v[172:175], v[204:207], v[64:67]
	s_setprio 0
	s_barrier
	ds_read_b128 v[176:179], v148 offset:49152
	ds_read_b128 v[180:183], v148 offset:50176
	ds_read_b128 v[184:187], v148 offset:51200
	ds_read_b128 v[188:191], v148 offset:52224
	ds_read_b128 v[192:195], v148 offset:53248
	ds_read_b128 v[196:199], v148 offset:54272
	ds_read_b128 v[200:203], v148 offset:55296
	ds_read_b128 v[204:207], v148 offset:56320
	s_add_u32 s4, s48, 0x80
	s_addc_u32 s5, s49, 0
	s_mov_b32 m0, s69
	s_nop 0
	global_load_lds_dwordx4 v143, s[4:5]
	s_nop 0
	s_mov_b32 m0, s70
	s_nop 0
	global_load_lds_dwordx4 v145, s[4:5]
	s_add_u32 s4, s48, 0x40080
	s_addc_u32 s5, s49, 0
	s_mov_b32 m0, s73
	s_nop 0
	global_load_lds_dwordx4 v143, s[4:5]
	s_nop 0
	s_mov_b32 m0, s74
	s_nop 0
	global_load_lds_dwordx4 v145, s[4:5]
	s_mov_b32 m0, s71
	s_nop 0
	global_load_lds_dwordx4 v142, s[46:47]
	s_nop 0
	s_mov_b32 m0, s72
	s_nop 0
	global_load_lds_dwordx4 v144, s[46:47]
	s_waitcnt vmcnt(8)
	s_waitcnt lgkmcnt(0)
	s_barrier
	s_setprio 1
	s_waitcnt lgkmcnt(7)
	v_mfma_f32_16x16x32_f16 v[60:63], v[132:135], v[176:179], v[60:63]
	v_mfma_f32_16x16x32_f16 v[56:59], v[152:155], v[176:179], v[56:59]
	s_waitcnt lgkmcnt(5)
	v_mfma_f32_16x16x32_f16 v[44:47], v[132:135], v[184:187], v[44:47]
	v_mfma_f32_16x16x32_f16 v[40:43], v[152:155], v[184:187], v[40:43]
	s_waitcnt lgkmcnt(3)
	v_mfma_f32_16x16x32_f16 v[28:31], v[132:135], v[192:195], v[28:31]
	v_mfma_f32_16x16x32_f16 v[24:27], v[152:155], v[192:195], v[24:27]
	s_waitcnt lgkmcnt(1)
	v_mfma_f32_16x16x32_f16 v[12:15], v[132:135], v[200:203], v[12:15]
	v_mfma_f32_16x16x32_f16 v[8:11], v[152:155], v[200:203], v[8:11]
	v_mfma_f32_16x16x32_f16 v[60:63], v[136:139], v[180:183], v[60:63]
	v_mfma_f32_16x16x32_f16 v[56:59], v[156:159], v[180:183], v[56:59]
	v_mfma_f32_16x16x32_f16 v[44:47], v[136:139], v[188:191], v[44:47]
	v_mfma_f32_16x16x32_f16 v[40:43], v[156:159], v[188:191], v[40:43]
	v_mfma_f32_16x16x32_f16 v[28:31], v[136:139], v[196:199], v[28:31]
	v_mfma_f32_16x16x32_f16 v[24:27], v[156:159], v[196:199], v[24:27]
	s_waitcnt lgkmcnt(0)
	v_mfma_f32_16x16x32_f16 v[12:15], v[136:139], v[204:207], v[12:15]
	v_mfma_f32_16x16x32_f16 v[8:11], v[156:159], v[204:207], v[8:11]
	s_setprio 0
	s_setprio 1
	v_mfma_f32_16x16x32_f16 v[52:55], v[160:163], v[176:179], v[52:55]
	v_mfma_f32_16x16x32_f16 v[48:51], v[168:171], v[176:179], v[48:51]
	v_mfma_f32_16x16x32_f16 v[36:39], v[160:163], v[184:187], v[36:39]
	v_mfma_f32_16x16x32_f16 v[32:35], v[168:171], v[184:187], v[32:35]
	v_mfma_f32_16x16x32_f16 v[20:23], v[160:163], v[192:195], v[20:23]
	v_mfma_f32_16x16x32_f16 v[16:19], v[168:171], v[192:195], v[16:19]
	v_mfma_f32_16x16x32_f16 v[4:7], v[160:163], v[200:203], v[4:7]
	v_mfma_f32_16x16x32_f16 v[0:3], v[168:171], v[200:203], v[0:3]
	v_mfma_f32_16x16x32_f16 v[52:55], v[164:167], v[180:183], v[52:55]
	v_mfma_f32_16x16x32_f16 v[48:51], v[172:175], v[180:183], v[48:51]
	v_mfma_f32_16x16x32_f16 v[36:39], v[164:167], v[188:191], v[36:39]
	v_mfma_f32_16x16x32_f16 v[32:35], v[172:175], v[188:191], v[32:35]
	v_mfma_f32_16x16x32_f16 v[20:23], v[164:167], v[196:199], v[20:23]
	v_mfma_f32_16x16x32_f16 v[16:19], v[172:175], v[196:199], v[16:19]
	v_mfma_f32_16x16x32_f16 v[4:7], v[164:167], v[204:207], v[4:7]
	v_mfma_f32_16x16x32_f16 v[0:3], v[172:175], v[204:207], v[0:3]
	s_setprio 0
	s_barrier
	s_add_i32 s82, s82, 2
	s_add_u32 s80, s80, 0x100
	s_addc_u32 s81, s81, 0
	s_cmp_gt_u32 s82, 13
	s_mov_b64 s[4:5], s[44:45]
	s_cbranch_scc0 .LBB0_212
	s_and_b64 vcc, exec, s[18:19]
	s_cbranch_vccz .LBB0_215
	s_barrier

.LBB0_405:
	s_mov_b32 s50, s73
	s_or_b64 exec, exec, s[0:1]
	s_add_u32 s7, s4, 0x3800000
	s_addc_u32 s33, s5, 0
	s_add_u32 s34, s4, 0xfc00000
	s_addc_u32 s35, s5, 0
	s_barrier
	v_mbcnt_lo_u32_b32 v0, -1, 0
	v_mbcnt_hi_u32_b32 v0, -1, v0
	s_lshl_b32 s12, s90, 10
	v_lshlrev_b32_e32 v1, 4, v0
	v_add_u32_e32 v2, s12, v1
	v_ashrrev_i32_e32 v3, 31, v2
	v_lshrrev_b32_e32 v3, 22, v3
	v_add_u32_e32 v3, v2, v3
	v_ashrrev_i32_e32 v3, 10, v3
	v_mul_i32_i24_e32 v4, 0x400, v3
	v_sub_u32_e32 v4, v2, v4
	v_lshrrev_b32_e32 v5, 4, v4
	v_bitop3_b32 v4, v5, v4, 32 bitop3:0x6c
	v_ashrrev_i32_e32 v6, 31, v4
	v_lshrrev_b32_e32 v6, 26, v6
	v_add_u32_e32 v6, v4, v6
	v_lshlrev_b32_e32 v5, 3, v3
	v_ashrrev_i32_e32 v7, 6, v6
	v_and_b32_e32 v6, 0xc0, v6
	v_and_b32_e32 v5, -16, v5
	v_lshlrev_b32_e32 v3, 5, v3
	v_sub_u32_e32 v4, v4, v6
	v_mov_b32_e32 v6, 1
	v_add_u32_e32 v5, v7, v5
	v_and_b32_e32 v3, 32, v3
	v_ashrrev_i16_sdwa v4, v6, sext(v4) dst_sel:DWORD dst_unused:UNUSED_PAD src0_sel:DWORD src1_sel:BYTE_0
	v_add_u32_sdwa v3, v3, sext(v4) dst_sel:DWORD dst_unused:UNUSED_PAD src0_sel:DWORD src1_sel:WORD_0
	v_lshlrev_b32_e32 v4, 1, v5
	v_lshrrev_b32_e32 v8, 2, v5
	v_and_b32_e32 v7, 3, v7
	s_mov_b32 s0, 0x1ffffe0
	v_and_b32_e32 v4, 24, v4
	v_and_b32_e32 v8, 4, v8
	v_and_or_b32 v7, v5, s0, v7
	v_or3_b32 v4, v7, v8, v4
	s_movk_i32 s1, 0x280
	v_mul_lo_u32 v5, v5, s1
	v_mul_lo_u32 v4, v4, s1
	v_add_u32_e32 v2, 0x2000, v2
	v_add_lshl_u32 v150, v3, v5, 1
	v_add_lshl_u32 v151, v4, v3, 1
	v_ashrrev_i32_e32 v3, 31, v2
	v_lshrrev_b32_e32 v3, 22, v3
	v_add_u32_e32 v3, v2, v3
	v_ashrrev_i32_e32 v3, 10, v3
	v_mul_i32_i24_e32 v4, 0x400, v3
	v_sub_u32_e32 v2, v2, v4
	v_lshrrev_b32_e32 v4, 4, v2
	v_bitop3_b32 v2, v4, v2, 32 bitop3:0x6c
	v_ashrrev_i32_e32 v5, 31, v2
	v_lshrrev_b32_e32 v5, 26, v5
	v_add_u32_e32 v5, v2, v5
	v_ashrrev_i32_e32 v7, 6, v5
	v_and_b32_e32 v5, 0xffc0, v5
	v_sub_u32_e32 v2, v2, v5
	v_lshrrev_b16_e32 v5, 7, v2
	v_lshlrev_b32_e32 v4, 3, v3
	v_and_b32_e32 v5, 1, v5
	v_and_b32_e32 v4, -16, v4
	v_lshlrev_b32_e32 v3, 5, v3
	v_add_u16_e32 v2, v2, v5
	v_add_u32_e32 v4, v7, v4
	v_and_b32_e32 v3, 32, v3
	v_ashrrev_i16_sdwa v2, v6, sext(v2) dst_sel:DWORD dst_unused:UNUSED_PAD src0_sel:DWORD src1_sel:BYTE_0
	v_add_u32_sdwa v2, v3, sext(v2) dst_sel:DWORD dst_unused:UNUSED_PAD src0_sel:DWORD src1_sel:WORD_0
	v_lshlrev_b32_e32 v3, 1, v4
	v_lshrrev_b32_e32 v5, 2, v4
	v_and_b32_e32 v6, 3, v7
	v_and_b32_e32 v3, 24, v3
	v_and_b32_e32 v5, 4, v5
	v_and_or_b32 v6, v4, s0, v6
	v_or3_b32 v3, v6, v5, v3
	v_mul_lo_u32 v4, v4, s1
	v_mul_lo_u32 v3, v3, s1
	s_lshr_b32 s0, s91, 8
	s_add_i32 s1, s31, -2
	s_add_i32 s2, s31, -3
	s_cmp_lt_u32 s1, 3
	s_cselect_b32 s13, s31, s2
	s_and_b64 s[2:3], s[8:9], exec
	s_cselect_b32 s72, 0, s13
	s_mul_i32 s2, s72, 0x50000
	s_add_u32 s2, s34, s2
	s_addc_u32 s3, s35, 0
	s_add_i32 s36, s12, 0
	s_add_i32 s37, s36, 0x10000
	s_mov_b32 m0, s37
	s_nop 0
	global_load_lds_dwordx4 v151, s[2:3]
	v_add_lshl_u32 v153, v3, v2, 1
	s_add_i32 s38, s36, 0x12000
	s_mov_b32 m0, s38
	s_nop 0
	global_load_lds_dwordx4 v153, s[2:3]
	s_add_u32 s12, s2, 0x28000
	s_mul_i32 s16, s6, 0x50000
	s_addc_u32 s13, s3, 0
	s_add_i32 s39, s36, 0x14000
	s_mov_b32 m0, s39
	s_nop 0
	global_load_lds_dwordx4 v151, s[12:13]
	s_add_i32 s40, s36, 0x16000
	s_mul_hi_i32 s15, s6, 0x50000
	s_mov_b32 m0, s40
	s_nop 0
	global_load_lds_dwordx4 v153, s[12:13]
	s_add_u32 s26, s7, s16
	s_addc_u32 s27, s33, s15
	s_mov_b32 m0, s36
	s_nop 0
	global_load_lds_dwordx4 v150, s[26:27]
	s_add_i32 s41, s36, 0x2000
	v_add_lshl_u32 v152, v2, v4, 1
	s_mov_b32 m0, s41
	s_nop 0
	global_load_lds_dwordx4 v152, s[26:27]
	s_add_u32 s16, s26, 0x28000
	s_addc_u32 s17, s27, 0
	s_add_i32 s42, s36, 0x4000
	s_mov_b32 m0, s42
	s_nop 0
	global_load_lds_dwordx4 v150, s[16:17]
	s_add_i32 s43, s36, 0x6000
	s_mov_b32 m0, s43
	s_nop 0
	global_load_lds_dwordx4 v152, s[16:17]
	s_cmp_eq_u32 s0, 1
	s_mov_b32 s14, 6
	s_cselect_b64 s[12:13], -1, 0
	s_cmp_lg_u32 s0, 1
	s_cbranch_scc1 .LBB0_407
	s_barrier
.LBB0_407:
	s_bfe_u32 s20, s91, 0x20006
	s_lshl_b32 s44, s0, 6
	s_lshl_b32 s22, s20, 5
	s_add_u32 s45, s4, 0x4c00000
	s_addc_u32 s46, s5, 0
	s_add_u32 s47, s4, 0x480000
	s_addc_u32 s48, s5, 0
	s_add_u32 s16, s2, 0x80
	s_waitcnt vmcnt(2)
	s_barrier
	s_addc_u32 s17, s3, 0
	s_add_i32 s49, s36, 0x18000
	s_mov_b32 m0, s49
	s_nop 0
	global_load_lds_dwordx4 v151, s[16:17]
	s_add_i32 s52, s36, 0x1a000
	s_mov_b32 m0, s52
	s_nop 0
	global_load_lds_dwordx4 v153, s[16:17]
	s_add_u32 s16, s26, 0x80
	s_addc_u32 s17, s27, 0
	s_add_i32 s53, s36, 0x8000
	s_mov_b32 m0, s53
	s_nop 0
	global_load_lds_dwordx4 v150, s[16:17]
	s_add_i32 s54, s36, 0xa000
	s_mov_b32 m0, s54
	s_nop 0
	global_load_lds_dwordx4 v152, s[16:17]
	s_add_u32 s16, s2, 0x28080
	s_addc_u32 s17, s3, 0
	s_add_i32 s55, s36, 0x1c000
	s_mov_b32 m0, s55
	s_nop 0
	global_load_lds_dwordx4 v151, s[16:17]
	s_add_i32 s56, s36, 0x1e000
	s_mov_b32 m0, s56
	s_nop 0
	global_load_lds_dwordx4 v153, s[16:17]
	s_mul_hi_u32 s16, s1, 0xaaaaaaab
	s_lshr_b32 s16, s16, 1
	s_mul_i32 s16, s16, 3
	s_sub_i32 s1, s1, s16
	s_lshl_b32 s57, s1, 1
	s_add_i32 s57, s57, 5
	s_add_i32 s58, s36, 0xc000
	s_cmpk_lt_u32 s91, 0x100
	s_cselect_b64 s[16:17], -1, 0
	s_cmp_lt_u32 s20, 2
	v_and_b32_e32 v1, 0xfffffc00, v1
	s_cselect_b64 s[18:19], -1, 0
	s_lshl_b32 s1, s20, 6
	v_lshl_add_u32 v3, s0, 13, v1
	s_add_i32 s59, s1, s0
	s_lshl_b32 s0, s0, 8
	s_add_i32 s62, s0, 0
	s_add_i32 s60, s36, 0xe000
	s_add_i32 s61, s62, 0x20c00
	s_add_i32 s62, s62, 0x20400
	s_add_u32 s0, s4, s1
	s_addc_u32 s1, s5, 0
	v_lshl_add_u32 v1, s20, 12, v1
	s_add_u32 s20, s0, 0x93fff80
	s_addc_u32 s21, s1, 0
	v_and_b32_e32 v2, 48, v0
	v_lshlrev_b32_e32 v4, 6, v0
	s_movk_i32 s15, 0x3c0
	v_lshlrev_b32_e32 v0, 2, v0
	s_add_u32 s23, s0, 0x7000000
	v_and_or_b32 v2, v4, s15, v2
	v_and_b32_e32 v0, 32, v0
	s_addc_u32 s24, s1, 0
	v_bitop3_b32 v3, v2, v3, v0 bitop3:0xde
	v_bitop3_b32 v0, v2, v1, v0 bitop3:0xde
	s_waitcnt vmcnt(6)
	s_and_b64 s[0:1], s[18:19], exec
	s_movk_i32 s0, 0x480
	v_add_u32_e32 v0, 0, v0
	s_mov_b32 s15, 0
	s_cselect_b32 s21, s24, s21
	s_cselect_b32 s20, s23, s20
	s_cselect_b32 s63, 0x60, 64
	s_cselect_b32 s64, s0, 0x300
	v_add_u32_e32 v154, 0x10000, v0
	v_add_u32_e32 v155, 0x14000, v0
	v_add_u32_e32 v156, 0, v3
	v_add_u32_e32 v157, 0x18000, v0
	v_add_u32_e32 v158, 0x1c000, v0
	v_mov_b32_e32 v128, 0
	s_lshl_b32 s65, s22, 1
	s_movk_i32 s66, 0x900
	s_mov_b32 s73, s6
	s_mov_b32 s67, 0
	s_barrier
	s_branch .LBB0_410

.LBB0_422:
	s_waitcnt lgkmcnt(0)
	ds_read_b128 v[130:133], v154
	ds_read_b128 v[134:137], v154 offset:1024
	ds_read_b128 v[138:141], v154 offset:2048
	ds_read_b128 v[142:145], v154 offset:3072
	ds_read_b128 v[160:163], v155
	ds_read_b128 v[164:167], v155 offset:1024
	ds_read_b128 v[168:171], v155 offset:2048
	ds_read_b128 v[172:175], v155 offset:3072
	s_add_i32 s79, s2, 2
	s_cmp_eq_u32 s74, s2
	s_cselect_b32 s28, s22, s75
	s_cselect_b32 s29, s23, s76
	s_cselect_b32 s26, s24, s77
	s_cselect_b32 s27, s25, s78
	s_add_u32 s2, s28, 0x80
	s_addc_u32 s3, s29, 0
	ds_read_b128 v[176:179], v156
	ds_read_b128 v[180:183], v156 offset:1024
	ds_read_b128 v[184:187], v156 offset:2048
	ds_read_b128 v[188:191], v156 offset:3072
	ds_read_b128 v[192:195], v156 offset:4096
	ds_read_b128 v[196:199], v156 offset:5120
	ds_read_b128 v[200:203], v156 offset:6144
	ds_read_b128 v[204:207], v156 offset:7168
	s_add_u32 s80, s75, 0x27f80
	s_addc_u32 s81, s76, 0
	s_mov_b32 m0, s58
	s_nop 0
	global_load_lds_dwordx4 v150, s[80:81]
	s_nop 0
	s_mov_b32 m0, s60
	s_nop 0
	global_load_lds_dwordx4 v152, s[80:81]
	s_waitcnt vmcnt(8)
	s_waitcnt lgkmcnt(0)
	s_barrier
	s_setprio 1
	s_waitcnt lgkmcnt(7)
	v_mfma_f32_16x16x32_bf16 v[76:79], v[130:133], v[176:179], v[76:79]
	v_mfma_f32_16x16x32_bf16 v[72:75], v[138:141], v[176:179], v[72:75]
	s_waitcnt lgkmcnt(5)
	v_mfma_f32_16x16x32_bf16 v[60:63], v[130:133], v[184:187], v[60:63]
	v_mfma_f32_16x16x32_bf16 v[56:59], v[138:141], v[184:187], v[56:59]
	s_waitcnt lgkmcnt(3)
	v_mfma_f32_16x16x32_bf16 v[52:55], v[130:133], v[192:195], v[52:55]
	v_mfma_f32_16x16x32_bf16 v[44:47], v[138:141], v[192:195], v[44:47]
	s_waitcnt lgkmcnt(1)
	v_mfma_f32_16x16x32_bf16 v[36:39], v[130:133], v[200:203], v[36:39]
	v_mfma_f32_16x16x32_bf16 v[32:35], v[138:141], v[200:203], v[32:35]
	v_mfma_f32_16x16x32_bf16 v[76:79], v[134:137], v[180:183], v[76:79]
	v_mfma_f32_16x16x32_bf16 v[72:75], v[142:145], v[180:183], v[72:75]
	v_mfma_f32_16x16x32_bf16 v[60:63], v[134:137], v[188:191], v[60:63]
	v_mfma_f32_16x16x32_bf16 v[56:59], v[142:145], v[188:191], v[56:59]
	v_mfma_f32_16x16x32_bf16 v[52:55], v[134:137], v[196:199], v[52:55]
	v_mfma_f32_16x16x32_bf16 v[44:47], v[142:145], v[196:199], v[44:47]
	s_waitcnt lgkmcnt(0)
	v_mfma_f32_16x16x32_bf16 v[36:39], v[134:137], v[204:207], v[36:39]
	v_mfma_f32_16x16x32_bf16 v[32:35], v[142:145], v[204:207], v[32:35]
	s_setprio 0
	s_setprio 1
	v_mfma_f32_16x16x32_bf16 v[124:127], v[160:163], v[176:179], v[124:127]
	v_mfma_f32_16x16x32_bf16 v[120:123], v[168:171], v[176:179], v[120:123]
	v_mfma_f32_16x16x32_bf16 v[116:119], v[160:163], v[184:187], v[116:119]
	v_mfma_f32_16x16x32_bf16 v[112:115], v[168:171], v[184:187], v[112:115]
	v_mfma_f32_16x16x32_bf16 v[108:111], v[160:163], v[192:195], v[108:111]
	v_mfma_f32_16x16x32_bf16 v[104:107], v[168:171], v[192:195], v[104:107]
	v_mfma_f32_16x16x32_bf16 v[100:103], v[160:163], v[200:203], v[100:103]
	v_mfma_f32_16x16x32_bf16 v[96:99], v[168:171], v[200:203], v[96:99]
	v_mfma_f32_16x16x32_bf16 v[124:127], v[164:167], v[180:183], v[124:127]
	v_mfma_f32_16x16x32_bf16 v[120:123], v[172:175], v[180:183], v[120:123]
	v_mfma_f32_16x16x32_bf16 v[116:119], v[164:167], v[188:191], v[116:119]
	v_mfma_f32_16x16x32_bf16 v[112:115], v[172:175], v[188:191], v[112:115]
	v_mfma_f32_16x16x32_bf16 v[108:111], v[164:167], v[196:199], v[108:111]
	v_mfma_f32_16x16x32_bf16 v[104:107], v[172:175], v[196:199], v[104:107]
	v_mfma_f32_16x16x32_bf16 v[100:103], v[164:167], v[204:207], v[100:103]
	v_mfma_f32_16x16x32_bf16 v[96:99], v[172:175], v[204:207], v[96:99]
	s_setprio 0
	s_barrier
	ds_read_b128 v[176:179], v156 offset:16384
	ds_read_b128 v[180:183], v156 offset:17408
	ds_read_b128 v[184:187], v156 offset:18432
	ds_read_b128 v[188:191], v156 offset:19456
	ds_read_b128 v[192:195], v156 offset:20480
	ds_read_b128 v[196:199], v156 offset:21504
	ds_read_b128 v[200:203], v156 offset:22528
	ds_read_b128 v[204:207], v156 offset:23552
	s_mov_b32 m0, s37
	s_nop 0
	global_load_lds_dwordx4 v151, s[26:27]
	s_nop 0
	s_mov_b32 m0, s38
	s_nop 0
	global_load_lds_dwordx4 v153, s[26:27]
	s_add_u32 s80, s26, 0x28000
	s_addc_u32 s81, s27, 0
	s_mov_b32 m0, s39
	s_nop 0
	global_load_lds_dwordx4 v151, s[80:81]
	s_nop 0
	s_mov_b32 m0, s40
	s_nop 0
	global_load_lds_dwordx4 v153, s[80:81]
	s_mov_b32 m0, s36
	s_nop 0
	global_load_lds_dwordx4 v150, s[28:29]
	s_nop 0
	s_mov_b32 m0, s41
	s_nop 0
	global_load_lds_dwordx4 v152, s[28:29]
	s_waitcnt vmcnt(8)
	s_waitcnt lgkmcnt(0)
	s_barrier
	s_setprio 1
	s_waitcnt lgkmcnt(7)
	v_mfma_f32_16x16x32_bf16 v[28:31], v[130:133], v[176:179], v[28:31]
	v_mfma_f32_16x16x32_bf16 v[24:27], v[138:141], v[176:179], v[24:27]
	s_waitcnt lgkmcnt(5)
	v_mfma_f32_16x16x32_bf16 v[20:23], v[130:133], v[184:187], v[20:23]
	v_mfma_f32_16x16x32_bf16 v[16:19], v[138:141], v[184:187], v[16:19]
	s_waitcnt lgkmcnt(3)
	v_mfma_f32_16x16x32_bf16 v[12:15], v[130:133], v[192:195], v[12:15]
	v_mfma_f32_16x16x32_bf16 v[8:11], v[138:141], v[192:195], v[8:11]
	s_waitcnt lgkmcnt(1)
	v_mfma_f32_16x16x32_bf16 v[4:7], v[130:133], v[200:203], v[4:7]
	v_mfma_f32_16x16x32_bf16 v[0:3], v[138:141], v[200:203], v[0:3]
	v_mfma_f32_16x16x32_bf16 v[28:31], v[134:137], v[180:183], v[28:31]
	v_mfma_f32_16x16x32_bf16 v[24:27], v[142:145], v[180:183], v[24:27]
	v_mfma_f32_16x16x32_bf16 v[20:23], v[134:137], v[188:191], v[20:23]
	v_mfma_f32_16x16x32_bf16 v[16:19], v[142:145], v[188:191], v[16:19]
	v_mfma_f32_16x16x32_bf16 v[12:15], v[134:137], v[196:199], v[12:15]
	v_mfma_f32_16x16x32_bf16 v[8:11], v[142:145], v[196:199], v[8:11]
	s_waitcnt lgkmcnt(0)
	v_mfma_f32_16x16x32_bf16 v[4:7], v[134:137], v[204:207], v[4:7]
	v_mfma_f32_16x16x32_bf16 v[0:3], v[142:145], v[204:207], v[0:3]
	s_setprio 0
	s_setprio 1
	v_mfma_f32_16x16x32_bf16 v[92:95], v[160:163], v[176:179], v[92:95]
	v_mfma_f32_16x16x32_bf16 v[88:91], v[168:171], v[176:179], v[88:91]
	v_mfma_f32_16x16x32_bf16 v[84:87], v[160:163], v[184:187], v[84:87]
	v_mfma_f32_16x16x32_bf16 v[80:83], v[168:171], v[184:187], v[80:83]
	v_mfma_f32_16x16x32_bf16 v[68:71], v[160:163], v[192:195], v[68:71]
	v_mfma_f32_16x16x32_bf16 v[64:67], v[168:171], v[192:195], v[64:67]
	v_mfma_f32_16x16x32_bf16 v[48:51], v[160:163], v[200:203], v[48:51]
	v_mfma_f32_16x16x32_bf16 v[40:43], v[168:171], v[200:203], v[40:43]
	v_mfma_f32_16x16x32_bf16 v[92:95], v[164:167], v[180:183], v[92:95]
	v_mfma_f32_16x16x32_bf16 v[88:91], v[172:175], v[180:183], v[88:91]
	v_mfma_f32_16x16x32_bf16 v[84:87], v[164:167], v[188:191], v[84:87]
	v_mfma_f32_16x16x32_bf16 v[80:83], v[172:175], v[188:191], v[80:83]
	v_mfma_f32_16x16x32_bf16 v[68:71], v[164:167], v[196:199], v[68:71]
	v_mfma_f32_16x16x32_bf16 v[64:67], v[172:175], v[196:199], v[64:67]
	v_mfma_f32_16x16x32_bf16 v[48:51], v[164:167], v[204:207], v[48:51]
	v_mfma_f32_16x16x32_bf16 v[40:43], v[172:175], v[204:207], v[40:43]
	s_setprio 0
	s_barrier
	ds_read_b128 v[130:133], v157
	ds_read_b128 v[134:137], v157 offset:1024
	ds_read_b128 v[138:141], v157 offset:2048
	ds_read_b128 v[142:145], v157 offset:3072
	ds_read_b128 v[160:163], v158
	ds_read_b128 v[164:167], v158 offset:1024
	ds_read_b128 v[168:171], v158 offset:2048
	ds_read_b128 v[172:175], v158 offset:3072
	ds_read_b128 v[176:179], v156 offset:32768
	ds_read_b128 v[180:183], v156 offset:33792
	ds_read_b128 v[184:187], v156 offset:34816
	ds_read_b128 v[188:191], v156 offset:35840
	ds_read_b128 v[192:195], v156 offset:36864
	ds_read_b128 v[196:199], v156 offset:37888
	ds_read_b128 v[200:203], v156 offset:38912
	ds_read_b128 v[204:207], v156 offset:39936
	s_add_u32 s28, s28, 0x28000
	s_addc_u32 s29, s29, 0
	s_mov_b32 m0, s42
	s_nop 0
	global_load_lds_dwordx4 v150, s[28:29]
	s_nop 0
	s_mov_b32 m0, s43
	s_nop 0
	global_load_lds_dwordx4 v152, s[28:29]
	s_waitcnt vmcnt(8)
	s_waitcnt lgkmcnt(0)
	s_barrier
	s_setprio 1
	s_waitcnt lgkmcnt(7)
	v_mfma_f32_16x16x32_bf16 v[76:79], v[130:133], v[176:179], v[76:79]
	v_mfma_f32_16x16x32_bf16 v[72:75], v[138:141], v[176:179], v[72:75]
	s_waitcnt lgkmcnt(5)
	v_mfma_f32_16x16x32_bf16 v[60:63], v[130:133], v[184:187], v[60:63]
	v_mfma_f32_16x16x32_bf16 v[56:59], v[138:141], v[184:187], v[56:59]
	s_waitcnt lgkmcnt(3)
	v_mfma_f32_16x16x32_bf16 v[52:55], v[130:133], v[192:195], v[52:55]
	v_mfma_f32_16x16x32_bf16 v[44:47], v[138:141], v[192:195], v[44:47]
	s_waitcnt lgkmcnt(1)
	v_mfma_f32_16x16x32_bf16 v[36:39], v[130:133], v[200:203], v[36:39]
	v_mfma_f32_16x16x32_bf16 v[32:35], v[138:141], v[200:203], v[32:35]
	v_mfma_f32_16x16x32_bf16 v[76:79], v[134:137], v[180:183], v[76:79]
	v_mfma_f32_16x16x32_bf16 v[72:75], v[142:145], v[180:183], v[72:75]
	v_mfma_f32_16x16x32_bf16 v[60:63], v[134:137], v[188:191], v[60:63]
	v_mfma_f32_16x16x32_bf16 v[56:59], v[142:145], v[188:191], v[56:59]
	v_mfma_f32_16x16x32_bf16 v[52:55], v[134:137], v[196:199], v[52:55]
	v_mfma_f32_16x16x32_bf16 v[44:47], v[142:145], v[196:199], v[44:47]
	s_waitcnt lgkmcnt(0)
	v_mfma_f32_16x16x32_bf16 v[36:39], v[134:137], v[204:207], v[36:39]
	v_mfma_f32_16x16x32_bf16 v[32:35], v[142:145], v[204:207], v[32:35]
	s_setprio 0
	s_setprio 1
	v_mfma_f32_16x16x32_bf16 v[124:127], v[160:163], v[176:179], v[124:127]
	v_mfma_f32_16x16x32_bf16 v[120:123], v[168:171], v[176:179], v[120:123]
	v_mfma_f32_16x16x32_bf16 v[116:119], v[160:163], v[184:187], v[116:119]
	v_mfma_f32_16x16x32_bf16 v[112:115], v[168:171], v[184:187], v[112:115]
	v_mfma_f32_16x16x32_bf16 v[108:111], v[160:163], v[192:195], v[108:111]
	v_mfma_f32_16x16x32_bf16 v[104:107], v[168:171], v[192:195], v[104:107]
	v_mfma_f32_16x16x32_bf16 v[100:103], v[160:163], v[200:203], v[100:103]
	v_mfma_f32_16x16x32_bf16 v[96:99], v[168:171], v[200:203], v[96:99]
	v_mfma_f32_16x16x32_bf16 v[124:127], v[164:167], v[180:183], v[124:127]
	v_mfma_f32_16x16x32_bf16 v[120:123], v[172:175], v[180:183], v[120:123]
	v_mfma_f32_16x16x32_bf16 v[116:119], v[164:167], v[188:191], v[116:119]
	v_mfma_f32_16x16x32_bf16 v[112:115], v[172:175], v[188:191], v[112:115]
	v_mfma_f32_16x16x32_bf16 v[108:111], v[164:167], v[196:199], v[108:111]
	v_mfma_f32_16x16x32_bf16 v[104:107], v[172:175], v[196:199], v[104:107]
	v_mfma_f32_16x16x32_bf16 v[100:103], v[164:167], v[204:207], v[100:103]
	v_mfma_f32_16x16x32_bf16 v[96:99], v[172:175], v[204:207], v[96:99]
	s_setprio 0
	s_barrier
	ds_read_b128 v[176:179], v156 offset:49152
	ds_read_b128 v[180:183], v156 offset:50176
	ds_read_b128 v[184:187], v156 offset:51200
	ds_read_b128 v[188:191], v156 offset:52224
	ds_read_b128 v[192:195], v156 offset:53248
	ds_read_b128 v[196:199], v156 offset:54272
	ds_read_b128 v[200:203], v156 offset:55296
	ds_read_b128 v[204:207], v156 offset:56320
	s_add_u32 s28, s26, 0x80
	s_addc_u32 s29, s27, 0
	s_mov_b32 m0, s49
	s_nop 0
	global_load_lds_dwordx4 v151, s[28:29]
	s_add_u32 s26, s26, 0x28080
	s_mov_b32 m0, s52
	s_nop 0
	global_load_lds_dwordx4 v153, s[28:29]
	s_addc_u32 s27, s27, 0
	s_mov_b32 m0, s55
	s_nop 0
	global_load_lds_dwordx4 v151, s[26:27]
	s_nop 0
	s_mov_b32 m0, s56
	s_nop 0
	global_load_lds_dwordx4 v153, s[26:27]
	s_mov_b32 m0, s53
	s_nop 0
	global_load_lds_dwordx4 v150, s[2:3]
	s_nop 0
	s_mov_b32 m0, s54
	s_nop 0
	global_load_lds_dwordx4 v152, s[2:3]
	s_waitcnt vmcnt(8)
	s_waitcnt lgkmcnt(0)
	s_barrier
	s_setprio 1
	s_waitcnt lgkmcnt(7)
	v_mfma_f32_16x16x32_bf16 v[28:31], v[130:133], v[176:179], v[28:31]
	v_mfma_f32_16x16x32_bf16 v[24:27], v[138:141], v[176:179], v[24:27]
	s_waitcnt lgkmcnt(5)
	v_mfma_f32_16x16x32_bf16 v[20:23], v[130:133], v[184:187], v[20:23]
	v_mfma_f32_16x16x32_bf16 v[16:19], v[138:141], v[184:187], v[16:19]
	s_waitcnt lgkmcnt(3)
	v_mfma_f32_16x16x32_bf16 v[12:15], v[130:133], v[192:195], v[12:15]
	v_mfma_f32_16x16x32_bf16 v[8:11], v[138:141], v[192:195], v[8:11]
	s_waitcnt lgkmcnt(1)
	v_mfma_f32_16x16x32_bf16 v[4:7], v[130:133], v[200:203], v[4:7]
	v_mfma_f32_16x16x32_bf16 v[0:3], v[138:141], v[200:203], v[0:3]
	v_mfma_f32_16x16x32_bf16 v[28:31], v[134:137], v[180:183], v[28:31]
	v_mfma_f32_16x16x32_bf16 v[24:27], v[142:145], v[180:183], v[24:27]
	v_mfma_f32_16x16x32_bf16 v[20:23], v[134:137], v[188:191], v[20:23]
	v_mfma_f32_16x16x32_bf16 v[16:19], v[142:145], v[188:191], v[16:19]
	v_mfma_f32_16x16x32_bf16 v[12:15], v[134:137], v[196:199], v[12:15]
	v_mfma_f32_16x16x32_bf16 v[8:11], v[142:145], v[196:199], v[8:11]
	s_waitcnt lgkmcnt(0)
	v_mfma_f32_16x16x32_bf16 v[4:7], v[134:137], v[204:207], v[4:7]
	v_mfma_f32_16x16x32_bf16 v[0:3], v[142:145], v[204:207], v[0:3]
	s_setprio 0
	s_setprio 1
	v_mfma_f32_16x16x32_bf16 v[92:95], v[160:163], v[176:179], v[92:95]
	v_mfma_f32_16x16x32_bf16 v[88:91], v[168:171], v[176:179], v[88:91]
	v_mfma_f32_16x16x32_bf16 v[84:87], v[160:163], v[184:187], v[84:87]
	v_mfma_f32_16x16x32_bf16 v[80:83], v[168:171], v[184:187], v[80:83]
	v_mfma_f32_16x16x32_bf16 v[68:71], v[160:163], v[192:195], v[68:71]
	v_mfma_f32_16x16x32_bf16 v[64:67], v[168:171], v[192:195], v[64:67]
	v_mfma_f32_16x16x32_bf16 v[48:51], v[160:163], v[200:203], v[48:51]
	v_mfma_f32_16x16x32_bf16 v[40:43], v[168:171], v[200:203], v[40:43]
	v_mfma_f32_16x16x32_bf16 v[92:95], v[164:167], v[180:183], v[92:95]
	v_mfma_f32_16x16x32_bf16 v[88:91], v[172:175], v[180:183], v[88:91]
	v_mfma_f32_16x16x32_bf16 v[84:87], v[164:167], v[188:191], v[84:87]
	v_mfma_f32_16x16x32_bf16 v[80:83], v[172:175], v[188:191], v[80:83]
	v_mfma_f32_16x16x32_bf16 v[68:71], v[164:167], v[196:199], v[68:71]
	v_mfma_f32_16x16x32_bf16 v[64:67], v[172:175], v[196:199], v[64:67]
	v_mfma_f32_16x16x32_bf16 v[48:51], v[164:167], v[204:207], v[48:51]
	v_mfma_f32_16x16x32_bf16 v[40:43], v[172:175], v[204:207], v[40:43]
	s_setprio 0
	s_barrier
	s_add_u32 s75, s75, 0x100
	s_addc_u32 s76, s76, 0
	s_add_u32 s77, s77, 0x100
	s_addc_u32 s78, s78, 0
	s_cmp_ge_i32 s79, s14
	s_mov_b32 s2, s79
	s_cbranch_scc0 .LBB0_422
	s_and_b64 vcc, exec, s[16:17]
	s_cbranch_vccz .LBB0_425
	s_barrier

.LBB0_552:
	s_mul_i32 s0, s72, 3
	s_add_i32 s0, s78, s0
	s_mul_hi_i32 s1, s0, 0x2aaaaaab
	s_lshr_b32 s8, s1, 31
	s_ashr_i32 s1, s1, 1
	s_add_i32 s56, s1, s8
	s_mul_i32 s1, s56, 12
	s_sub_i32 s1, s0, s1
	s_mul_hi_i32 s9, s56, 0x900000
	s_mul_i32 s8, s56, 0x900000
	s_mul_i32 s46, s1, 0x60
	s_ashr_i32 s57, s56, 31
	s_ashr_i32 s47, s46, 31
	s_lshl_b64 s[44:45], s[8:9], 1
	v_readlane_b32 s8, v246, 41
	s_add_u32 s8, s8, s44
	v_readlane_b32 s9, v246, 42
	s_addc_u32 s9, s9, s45
	s_lshl_b64 s[48:49], s[46:47], 1
	s_add_u32 s64, s8, s48
	s_addc_u32 s65, s9, s49
	s_lshl_b64 s[8:9], s[56:57], 19
	v_readlane_b32 s46, v246, 49
	s_add_u32 s46, s46, s8
	v_readlane_b32 s8, v246, 50
	s_addc_u32 s47, s8, s9
	s_mov_b32 m0, s55
	s_nop 0
	global_load_lds_dwordx4 v183, s[64:65]
	s_and_saveexec_b64 s[8:9], s[2:3]
	s_cbranch_execz .LBB0_554
	s_mov_b32 m0, s76
	s_nop 0
	global_load_lds_dwordx4 v184, s[46:47]
.LBB0_554:
	s_or_b64 exec, exec, s[8:9]
	s_mul_i32 s9, s56, 0xc00000
	v_readlane_b32 s52, v246, 43
	s_mul_hi_i32 s8, s56, 0xc00000
	s_add_u32 s52, s52, s9
	v_readlane_b32 s9, v246, 44
	s_addc_u32 s60, s9, s8
	s_lshl_b32 s8, s1, 6
	s_ashr_i32 s9, s8, 31
	s_lshl_b64 s[58:59], s[8:9], 1
	s_add_u32 s8, s52, s58
	s_addc_u32 s9, s60, s59
	s_add_u32 s60, s64, 0x24000
	s_addc_u32 s61, s65, 0
	s_mov_b32 m0, s33
	s_nop 0
	global_load_lds_dwordx4 v185, s[8:9]
	s_cmp_lg_u32 0, -1
	s_cselect_b32 s1, 0, 0
	s_add_i32 s1, s1, s73
	s_addk_i32 s1, 0x3000
	s_mov_b32 m0, s1
	s_nop 0
	global_load_lds_dwordx4 v183, s[60:61]
	s_and_saveexec_b64 s[60:61], s[2:3]
	s_cbranch_execz .LBB0_556
	s_add_u32 s66, s46, 0x1000
	s_addc_u32 s67, s47, 0
	s_add_i32 s1, s76, 0x3000
	s_mov_b32 m0, s1
	s_nop 0
	global_load_lds_dwordx4 v184, s[66:67]

.LBB0_559:
	s_add_u32 s0, s64, 0x48000
	s_addc_u32 s1, s65, 0
	s_cmp_lg_u32 0, -1
	s_cselect_b32 s48, 0, 0
	s_add_i32 s48, s48, s73
	s_addk_i32 s48, 0x6000
	s_mov_b32 m0, s48
	s_nop 0
	global_load_lds_dwordx4 v183, s[0:1]
	s_and_saveexec_b64 s[0:1], s[2:3]
	s_cbranch_execz .LBB0_561
	s_add_u32 s48, s46, 0x2000
	s_addc_u32 s49, s47, 0
	s_add_i32 s60, s76, 0x6000
	s_mov_b32 m0, s60
	s_nop 0
	global_load_lds_dwordx4 v184, s[48:49]

.LBB0_567:
	s_add_u32 s48, s64, 0x6c000
	s_addc_u32 s49, s65, 0
	s_cmp_lg_u32 0, -1
	s_cselect_b32 s60, 0, 0
	s_waitcnt vmcnt(0) lgkmcnt(0)
	s_barrier
	s_add_i32 s60, s60, s73
	s_add_i32 s60, s60, 0x9000
	s_mov_b32 m0, s60
	s_nop 0
	global_load_lds_dwordx4 v183, s[48:49]
	s_and_saveexec_b64 s[48:49], s[2:3]
	s_cbranch_execz .LBB0_569
	s_add_u32 s60, s46, 0x3000
	s_addc_u32 s61, s47, 0
	s_add_i32 s66, s76, 0x9000
	s_mov_b32 m0, s66
	s_nop 0
	global_load_lds_dwordx4 v184, s[60:61]
.LBB0_569:
	s_or_b64 exec, exec, s[48:49]
	s_add_i32 s48, s81, 0x100
	s_lshr_b32 s80, s48, 6
	s_add_u32 s66, s8, 0x18000
	s_addc_u32 s67, s9, 0
	s_cmp_lg_u32 0, -1
	s_cselect_b32 s48, 0, 0
	s_add_i32 s48, s48, s73
	s_add_i32 s48, s48, 0xe000
	s_mov_b32 m0, s48
	s_nop 0
	global_load_lds_dwordx4 v185, s[66:67]
	ds_read_b128 v[80:83], v179 offset:12288
	ds_read_b128 v[136:139], v179 offset:12800
	ds_read_b128 v[140:143], v179 offset:14336
	v_exp_f32_e32 v48, v16
	v_exp_f32_e32 v49, v17
	v_exp_f32_e32 v50, v18
	v_exp_f32_e32 v51, v19
	v_exp_f32_e32 v52, v20
	v_exp_f32_e32 v53, v21
	v_exp_f32_e32 v54, v22
	v_exp_f32_e32 v55, v23
	v_exp_f32_e32 v56, v24
	v_exp_f32_e32 v57, v25
	v_exp_f32_e32 v58, v26
	v_exp_f32_e32 v59, v27
	v_exp_f32_e32 v60, v28
	v_exp_f32_e32 v61, v29
	v_exp_f32_e32 v62, v30
	v_exp_f32_e32 v63, v31
	v_exp_f32_e32 v32, v0
	v_exp_f32_e32 v33, v1
	v_exp_f32_e32 v34, v2
	v_exp_f32_e32 v35, v3
	v_exp_f32_e32 v36, v4
	v_exp_f32_e32 v37, v5
	v_exp_f32_e32 v38, v6
	v_exp_f32_e32 v39, v7
	v_exp_f32_e32 v40, v8
	v_exp_f32_e32 v41, v9
	v_exp_f32_e32 v42, v10
	v_exp_f32_e32 v43, v11
	v_exp_f32_e32 v44, v12
	v_exp_f32_e32 v45, v13
	v_exp_f32_e32 v46, v14
	v_exp_f32_e32 v47, v15
	s_mov_b32 s86, 0
	s_andn2_b64 vcc, exec, s[0:1]
	s_mov_b32 s0, 1
	s_cbranch_vccnz .LBB0_595
	s_add_u32 s68, s8, 0x48000
	s_addc_u32 s69, s9, 0
	s_add_u32 s48, s64, 0xb4000
	s_addc_u32 s49, s65, 0
	v_mov_b32_e32 v16, v153
	v_mov_b32_e32 v17, v153
	s_add_u32 s8, s46, 0x5000
	v_mov_b32_e32 v18, v153
	v_mov_b32_e32 v19, v153
	v_mov_b32_e32 v20, v153
	v_mov_b32_e32 v21, v153
	v_mov_b32_e32 v22, v153
	v_mov_b32_e32 v23, v153
	v_mov_b32_e32 v24, v153
	v_mov_b32_e32 v25, v153
	v_mov_b32_e32 v26, v153
	v_mov_b32_e32 v27, v153
	v_mov_b32_e32 v28, v153
	v_mov_b32_e32 v29, v153
	v_mov_b32_e32 v30, v153
	v_mov_b32_e32 v31, v153
	v_mov_b64_e32 v[0:1], v[16:17]
	s_addc_u32 s9, s47, 0
	s_mov_b32 s0, 0
	s_movk_i32 s83, 0x6000
	s_movk_i32 s82, 0x3000
	s_movk_i32 s86, 0x4000
	s_movk_i32 s79, 0x2000
	s_mov_b64 s[60:61], 0
	v_mov_b32_e32 v166, 0
	s_mov_b32 s87, 6
	v_mov_b64_e32 v[2:3], v[18:19]
	v_mov_b64_e32 v[4:5], v[20:21]
	v_mov_b64_e32 v[6:7], v[22:23]
	v_mov_b64_e32 v[8:9], v[24:25]
	v_mov_b64_e32 v[10:11], v[26:27]
	v_mov_b64_e32 v[12:13], v[28:29]
	v_mov_b64_e32 v[14:15], v[30:31]
	s_mov_b32 s84, 0
.LBB0_571:
	v_cvt_pk_bf16_f32 v128, v56, v57
	v_cvt_pk_bf16_f32 v132, v48, v49
	v_add_u32_e32 v120, s82, v179
	ds_read_b128 v[220:223], v120 offset:2560
	v_add_u32_e32 v167, s0, v180
	v_add_f32_e32 v48, v48, v49
	s_waitcnt lgkmcnt(3)
	v_mfma_f32_32x32x16_bf16 v[80:95], v[80:83], v[116:119], 0
	v_add_f32_e32 v48, v50, v48
	v_add_f32_e32 v48, v51, v48
	v_add_f32_e32 v48, v52, v48
	ds_read_b128 v[224:227], v120 offset:4096
	s_waitcnt lgkmcnt(3)
	v_mfma_f32_32x32x16_bf16 v[64:79], v[136:139], v[116:119], 0
	v_add_f32_e32 v48, v53, v48
	v_add_f32_e32 v48, v54, v48
	v_add_f32_e32 v121, v55, v48
	v_cvt_pk_bf16_f32 v133, v50, v51
	ds_read_b128 v[48:51], v120 offset:4608
	s_waitcnt lgkmcnt(3)
	v_mfma_f32_32x32x16_bf16 v[80:95], v[140:143], v[112:115], v[80:95]
	v_add_f32_e32 v56, v56, v121
	v_add_f32_e32 v56, v57, v56
	v_add_f32_e32 v56, v58, v56
	v_cvt_pk_bf16_f32 v134, v52, v53
	ds_read_b128 v[136:139], v120 offset:6144
	s_waitcnt lgkmcnt(3)
	v_mfma_f32_32x32x16_bf16 v[64:79], v[220:223], v[112:115], v[64:79]
	v_add_f32_e32 v52, v59, v56
	v_add_f32_e32 v52, v60, v52
	v_add_f32_e32 v56, v61, v52
	v_cvt_pk_bf16_f32 v135, v54, v55
	ds_read_b128 v[52:55], v120 offset:6656
	s_waitcnt lgkmcnt(3)
	v_mfma_f32_32x32x16_bf16 v[80:95], v[224:227], v[104:107], v[80:95]
	v_add_f32_e32 v56, v62, v56
	v_add_f32_e32 v56, v63, v56
	v_add_f32_e32 v56, v32, v56
	ds_read_b128 v[140:143], v120 offset:8192
	s_waitcnt lgkmcnt(3)
	v_mfma_f32_32x32x16_bf16 v[64:79], v[48:51], v[104:107], v[64:79]
	v_add_f32_e32 v48, v33, v56
	v_add_f32_e32 v48, v34, v48
	v_add_f32_e32 v56, v35, v48
	v_cvt_pk_bf16_f32 v129, v58, v59
	ds_read_b128 v[48:51], v120 offset:8704
	s_waitcnt lgkmcnt(3)
	v_mfma_f32_32x32x16_bf16 v[80:95], v[136:139], v[96:99], v[80:95]
	v_add_f32_e32 v56, v36, v56
	v_add_f32_e32 v56, v37, v56
	v_add_f32_e32 v121, v38, v56
	v_cvt_pk_bf16_f32 v130, v60, v61
	ds_read_b128 v[56:59], v120 offset:10240
	s_waitcnt lgkmcnt(3)
	v_mfma_f32_32x32x16_bf16 v[64:79], v[52:55], v[96:99], v[64:79]
	v_add_f32_e32 v52, v39, v121
	v_add_f32_e32 v52, v40, v52
	v_add_f32_e32 v60, v41, v52
	v_cvt_pk_bf16_f32 v131, v62, v63
	ds_read_b128 v[52:55], v120 offset:10752
	s_waitcnt lgkmcnt(3)
	v_mfma_f32_32x32x16_bf16 v[80:95], v[140:143], v[108:111], v[80:95]
	v_add_f32_e32 v60, v42, v60
	v_add_f32_e32 v60, v43, v60
	v_cvt_pk_bf16_f32 v124, v32, v33
	v_cvt_pk_bf16_f32 v125, v34, v35
	ds_read_b64_tr_b16 v[32:33], v167 offset:49152
	ds_read_b64_tr_b16 v[34:35], v167 offset:49664
	s_waitcnt lgkmcnt(4)
	v_mfma_f32_32x32x16_bf16 v[64:79], v[48:51], v[108:111], v[64:79]
	v_add_f32_e32 v48, v44, v60
	v_add_f32_e32 v60, v45, v48
	v_cvt_pk_bf16_f32 v126, v36, v37
	v_cvt_pk_bf16_f32 v127, v38, v39
	ds_read_b64_tr_b16 v[48:49], v167 offset:53248
	ds_read_b64_tr_b16 v[50:51], v167 offset:53760
	s_waitcnt lgkmcnt(5)
	v_mfma_f32_32x32x16_bf16 v[80:95], v[56:59], v[100:103], v[80:95]
	v_add_f32_e32 v56, v46, v60
	v_cvt_pk_bf16_f32 v120, v40, v41
	v_cvt_pk_bf16_f32 v121, v42, v43
	ds_read_b64_tr_b16 v[36:37], v167 offset:50176
	ds_read_b64_tr_b16 v[38:39], v167 offset:50688
	s_waitcnt lgkmcnt(6)
	v_mfma_f32_32x32x16_bf16 v[64:79], v[52:55], v[100:103], v[64:79]
	v_add_f32_e32 v40, v47, v56
	v_cvt_pk_bf16_f32 v122, v44, v45
	v_cvt_pk_bf16_f32 v123, v46, v47
	s_add_u32 s0, s48, 0xfffdc000
	s_addc_u32 s1, s49, -1
	s_add_i32 s85, s84, s55
	s_mov_b32 m0, s85
	s_nop 0
	global_load_lds_dwordx4 v183, s[0:1]
	s_and_saveexec_b64 s[0:1], s[2:3]
	s_cbranch_execz .LBB0_573
	s_add_u32 s88, s8, 0xfffff000
	s_addc_u32 s89, s9, -1
	s_add_i32 s84, s84, s76
	s_mov_b32 m0, s84
	s_nop 0
	global_load_lds_dwordx4 v184, s[88:89]
.LBB0_573:
	s_or_b64 exec, exec, s[0:1]
	s_add_u32 s0, s68, 0xfffe8000
	s_addc_u32 s1, s69, -1
	s_add_i32 s84, s86, s33
	s_mov_b32 m0, s84
	s_nop 0
	global_load_lds_dwordx4 v185, s[0:1]
	v_add_f32_e32 v140, v166, v40
	s_and_b64 vcc, exec, s[44:45]
	s_cbranch_vccnz .LBB0_577
	v_max_f32_e32 v40, v81, v81
	v_max_f32_e32 v41, v80, v80
	v_max_f32_e32 v40, v41, v40
	v_max3_f32 v41, v82, v83, v65
	v_max3_f32 v40, v40, v64, v66
	v_max3_f32 v40, v40, v67, v84
	v_max3_f32 v41, v41, v86, v87
	v_max3_f32 v40, v40, v85, v68
	v_max3_f32 v41, v41, v70, v71
	v_max3_f32 v40, v40, v69, v88
	v_max3_f32 v41, v41, v90, v91
	v_max3_f32 v40, v40, v89, v72
	v_max3_f32 v41, v41, v74, v75
	v_max3_f32 v40, v40, v73, v92
	v_max3_f32 v41, v41, v94, v95
	v_max3_f32 v40, v40, v93, v76
	v_max3_f32 v41, v41, v78, v79
	v_max3_f32 v40, v40, v77, v41
	v_sub_f32_e32 v41, v40, v145
	v_cmp_lt_f32_e32 vcc, s77, v41
	s_cmp_lg_u64 vcc, 0
	s_cselect_b64 s[60:61], -1, 0
	s_cbranch_vccnz .LBB0_589
	s_andn2_b64 vcc, exec, s[62:63]
	s_mov_b64 s[62:63], 0
	s_cbranch_vccnz .LBB0_577

.LBB0_577:
	s_cmp_lt_u32 s90, 4
	s_cbranch_scc1 .Lstg_mid1
	s_waitcnt vmcnt(3) lgkmcnt(0)
	s_barrier
.Lstg_mid1:
	ds_read_b64_tr_b16 v[40:41], v167 offset:54272
	ds_read_b64_tr_b16 v[42:43], v167 offset:54784
	s_waitcnt lgkmcnt(6)
	v_mfma_f32_32x32x16_bf16 v[16:31], v[132:135], v[32:35], v[16:31]
	v_exp_f32_e32 v80, v80
	v_exp_f32_e32 v81, v81
	v_exp_f32_e32 v82, v82
	v_exp_f32_e32 v83, v83
	ds_read_b64_tr_b16 v[32:33], v167 offset:51200
	ds_read_b64_tr_b16 v[34:35], v167 offset:51712
	s_waitcnt lgkmcnt(6)
	v_mfma_f32_32x32x16_bf16 v[0:15], v[132:135], v[48:51], v[0:15]
	v_exp_f32_e32 v84, v84
	v_exp_f32_e32 v85, v85
	v_exp_f32_e32 v86, v86
	v_exp_f32_e32 v87, v87
	ds_read_b64_tr_b16 v[44:45], v167 offset:55296
	ds_read_b64_tr_b16 v[46:47], v167 offset:55808
	s_waitcnt lgkmcnt(6)
	v_mfma_f32_32x32x16_bf16 v[16:31], v[128:131], v[36:39], v[16:31]
	v_exp_f32_e32 v88, v88
	v_exp_f32_e32 v89, v89
	v_exp_f32_e32 v90, v90
	v_exp_f32_e32 v91, v91
	ds_read_b64_tr_b16 v[48:49], v167 offset:52224
	ds_read_b64_tr_b16 v[50:51], v167 offset:52736
	s_waitcnt lgkmcnt(6)
	v_mfma_f32_32x32x16_bf16 v[0:15], v[128:131], v[40:43], v[0:15]
	v_exp_f32_e32 v92, v92
	v_exp_f32_e32 v93, v93
	v_exp_f32_e32 v94, v94
	v_exp_f32_e32 v95, v95
	ds_read_b64_tr_b16 v[40:41], v167 offset:56320
	ds_read_b64_tr_b16 v[42:43], v167 offset:56832
	s_waitcnt lgkmcnt(6)
	v_mfma_f32_32x32x16_bf16 v[16:31], v[124:127], v[32:35], v[16:31]
	v_exp_f32_e32 v64, v64
	v_exp_f32_e32 v65, v65
	v_exp_f32_e32 v66, v66
	v_exp_f32_e32 v67, v67
	v_add_u32_e32 v142, s83, v179
	ds_read_b128 v[32:35], v142
	s_waitcnt lgkmcnt(5)
	v_mfma_f32_32x32x16_bf16 v[0:15], v[124:127], v[44:47], v[0:15]
	v_exp_f32_e32 v68, v68
	v_exp_f32_e32 v69, v69
	v_exp_f32_e32 v70, v70
	v_exp_f32_e32 v71, v71
	ds_read_b128 v[36:39], v142 offset:512
	s_waitcnt lgkmcnt(4)
	v_mfma_f32_32x32x16_bf16 v[16:31], v[120:123], v[48:51], v[16:31]
	v_exp_f32_e32 v72, v72
	v_exp_f32_e32 v73, v73
	v_exp_f32_e32 v74, v74
	v_exp_f32_e32 v75, v75
	ds_read_b128 v[136:139], v142 offset:2048
	s_waitcnt lgkmcnt(3)
	v_mfma_f32_32x32x16_bf16 v[0:15], v[120:123], v[40:43], v[0:15]
	v_exp_f32_e32 v76, v76
	v_exp_f32_e32 v77, v77
	v_exp_f32_e32 v78, v78
	v_exp_f32_e32 v79, v79
	s_cmp_lt_u32 s90, 4
	s_cbranch_scc0 .Lstg_end1
	s_waitcnt vmcnt(3) lgkmcnt(0)
	s_barrier
.Lstg_end1:
	s_andn2_b64 vcc, exec, s[60:61]
	s_cbranch_vccnz .LBB0_579
	s_waitcnt lgkmcnt(0)
	v_add_u32_e32 v52, s54, v146
	ds_read_b128 v[40:43], v52 offset:96
	ds_read_b128 v[44:47], v52 offset:64
	ds_read_b128 v[48:51], v52 offset:32
	ds_read_b128 v[52:55], v52
	s_waitcnt lgkmcnt(3)
	v_pk_mul_f32 v[28:29], v[28:29], v[40:41]
	s_waitcnt lgkmcnt(2)
	v_pk_mul_f32 v[24:25], v[24:25], v[44:45]
	s_waitcnt lgkmcnt(1)
	v_pk_mul_f32 v[20:21], v[20:21], v[48:49]
	v_pk_mul_f32 v[30:31], v[30:31], v[42:43]
	v_pk_mul_f32 v[26:27], v[26:27], v[46:47]
	v_pk_mul_f32 v[22:23], v[22:23], v[50:51]
	s_waitcnt lgkmcnt(0)
	v_pk_mul_f32 v[18:19], v[18:19], v[54:55]
	v_pk_mul_f32 v[16:17], v[16:17], v[52:53]
	v_pk_mul_f32 v[12:13], v[12:13], v[40:41]
	v_pk_mul_f32 v[8:9], v[8:9], v[44:45]
	v_pk_mul_f32 v[4:5], v[4:5], v[48:49]
	v_pk_mul_f32 v[14:15], v[14:15], v[42:43]
	v_pk_mul_f32 v[10:11], v[10:11], v[46:47]
	v_pk_mul_f32 v[6:7], v[6:7], v[50:51]
	v_pk_mul_f32 v[2:3], v[2:3], v[54:55]
	v_pk_mul_f32 v[0:1], v[0:1], v[52:53]
.LBB0_579:
	ds_read_b128 v[166:169], v142 offset:2560
	v_add_u32_e32 v141, s79, v180
	v_add_f32_e32 v40, v80, v81
	s_waitcnt lgkmcnt(3)
	v_mfma_f32_32x32x16_bf16 v[48:63], v[32:35], v[116:119], 0
	v_add_f32_e32 v40, v82, v40
	v_add_f32_e32 v40, v83, v40
	v_add_f32_e32 v40, v84, v40
	v_cvt_pk_bf16_f32 v132, v80, v81
	ds_read_b128 v[220:223], v142 offset:4096
	v_add_f32_e32 v32, v85, v40
	v_add_f32_e32 v32, v86, v32
	v_add_f32_e32 v120, v87, v32
	s_waitcnt lgkmcnt(3)
	v_mfma_f32_32x32x16_bf16 v[32:47], v[36:39], v[116:119], 0
	v_cvt_pk_bf16_f32 v133, v82, v83
	ds_read_b128 v[80:83], v142 offset:4608
	s_waitcnt lgkmcnt(3)
	v_mfma_f32_32x32x16_bf16 v[48:63], v[136:139], v[112:115], v[48:63]
	v_add_f32_e32 v120, v88, v120
	v_add_f32_e32 v120, v89, v120
	v_add_f32_e32 v120, v90, v120
	v_cvt_pk_bf16_f32 v134, v84, v85
	ds_read_b128 v[136:139], v142 offset:6144
	s_waitcnt lgkmcnt(3)
	v_mfma_f32_32x32x16_bf16 v[32:47], v[166:169], v[112:115], v[32:47]
	v_add_f32_e32 v84, v91, v120
	v_add_f32_e32 v84, v92, v84
	v_add_f32_e32 v120, v93, v84
	v_cvt_pk_bf16_f32 v135, v86, v87
	ds_read_b128 v[84:87], v142 offset:6656
	s_waitcnt lgkmcnt(3)
	v_mfma_f32_32x32x16_bf16 v[48:63], v[220:223], v[104:107], v[48:63]
	v_add_f32_e32 v120, v94, v120
	v_add_f32_e32 v120, v95, v120
	v_add_f32_e32 v120, v64, v120
	v_cvt_pk_bf16_f32 v128, v88, v89
	ds_read_b128 v[166:169], v142 offset:8192
	s_waitcnt lgkmcnt(3)
	v_mfma_f32_32x32x16_bf16 v[32:47], v[80:83], v[104:107], v[32:47]
	v_add_f32_e32 v80, v65, v120
	v_add_f32_e32 v80, v66, v80
	v_add_f32_e32 v88, v67, v80
	v_cvt_pk_bf16_f32 v129, v90, v91
	ds_read_b128 v[80:83], v142 offset:8704
	s_waitcnt lgkmcnt(3)
	v_mfma_f32_32x32x16_bf16 v[48:63], v[136:139], v[96:99], v[48:63]
	v_add_f32_e32 v88, v68, v88
	v_add_f32_e32 v88, v69, v88
	v_add_f32_e32 v120, v70, v88
	v_cvt_pk_bf16_f32 v130, v92, v93
	ds_read_b128 v[88:91], v142 offset:10240
	s_waitcnt lgkmcnt(3)
	v_mfma_f32_32x32x16_bf16 v[32:47], v[84:87], v[96:99], v[32:47]
	v_add_f32_e32 v84, v71, v120
	v_add_f32_e32 v84, v72, v84
	v_add_f32_e32 v92, v73, v84
	v_cvt_pk_bf16_f32 v131, v94, v95
	ds_read_b128 v[84:87], v142 offset:10752
	s_waitcnt lgkmcnt(3)
	v_mfma_f32_32x32x16_bf16 v[48:63], v[166:169], v[108:111], v[48:63]
	v_add_f32_e32 v92, v74, v92
	v_add_f32_e32 v92, v75, v92
	v_cvt_pk_bf16_f32 v124, v64, v65
	v_cvt_pk_bf16_f32 v125, v66, v67
	ds_read_b64_tr_b16 v[64:65], v141 offset:49152
	ds_read_b64_tr_b16 v[66:67], v141 offset:49664
	s_waitcnt lgkmcnt(4)
	v_mfma_f32_32x32x16_bf16 v[32:47], v[80:83], v[108:111], v[32:47]
	v_add_f32_e32 v80, v76, v92
	v_add_f32_e32 v92, v77, v80
	v_cvt_pk_bf16_f32 v126, v68, v69
	v_cvt_pk_bf16_f32 v127, v70, v71
	ds_read_b64_tr_b16 v[80:81], v141 offset:53248
	ds_read_b64_tr_b16 v[82:83], v141 offset:53760
	s_waitcnt lgkmcnt(5)
	v_mfma_f32_32x32x16_bf16 v[48:63], v[88:91], v[100:103], v[48:63]
	v_add_f32_e32 v88, v78, v92
	v_cvt_pk_bf16_f32 v120, v72, v73
	v_cvt_pk_bf16_f32 v121, v74, v75
	ds_read_b64_tr_b16 v[68:69], v141 offset:50176
	ds_read_b64_tr_b16 v[70:71], v141 offset:50688
	s_waitcnt lgkmcnt(6)
	v_mfma_f32_32x32x16_bf16 v[32:47], v[84:87], v[100:103], v[32:47]
	v_add_f32_e32 v72, v79, v88
	v_cvt_pk_bf16_f32 v122, v76, v77
	v_cvt_pk_bf16_f32 v123, v78, v79
	s_add_i32 s0, s82, s55
	s_mov_b32 m0, s0
	s_nop 0
	global_load_lds_dwordx4 v183, s[48:49]
	s_and_saveexec_b64 s[0:1], s[2:3]
	s_cbranch_execz .LBB0_581
	s_add_i32 s79, s82, s76
	s_mov_b32 m0, s79
	s_nop 0
	global_load_lds_dwordx4 v184, s[8:9]
.LBB0_581:
	s_or_b64 exec, exec, s[0:1]
	s_add_i32 s0, s86, 0x2000
	s_cmpk_lg_i32 s86, 0x4000
	s_cselect_b32 s0, s0, 0xe800
	s_cmpk_lg_u32 s86, 0xe800
	s_cselect_b32 s79, s0, 0
	s_add_i32 s0, s79, s33
	s_mov_b32 m0, s0
	s_nop 0
	global_load_lds_dwordx4 v185, s[68:69]
	v_add_f32_e32 v166, v140, v72
	s_and_b64 vcc, exec, s[44:45]
	s_cbranch_vccnz .LBB0_585
	v_max_f32_e32 v72, v49, v49
	v_max_f32_e32 v73, v48, v48
	v_max_f32_e32 v72, v73, v72
	v_max3_f32 v73, v50, v51, v33
	v_max3_f32 v72, v72, v32, v34
	v_max3_f32 v72, v72, v35, v52
	v_max3_f32 v73, v73, v54, v55
	v_max3_f32 v72, v72, v53, v36
	v_max3_f32 v73, v73, v38, v39
	v_max3_f32 v72, v72, v37, v56
	v_max3_f32 v73, v73, v58, v59
	v_max3_f32 v72, v72, v57, v40
	v_max3_f32 v73, v73, v42, v43
	v_max3_f32 v72, v72, v41, v60
	v_max3_f32 v73, v73, v62, v63
	v_max3_f32 v72, v72, v61, v44
	v_max3_f32 v73, v73, v46, v47
	v_max3_f32 v72, v72, v45, v73
	v_sub_f32_e32 v73, v72, v145
	v_cmp_lt_f32_e32 vcc, s77, v73
	s_cmp_lg_u64 vcc, 0
	s_cselect_b64 s[60:61], -1, 0
	s_cbranch_vccnz .LBB0_592
	s_andn2_b64 vcc, exec, s[62:63]
	s_mov_b64 s[62:63], 0
	s_cbranch_vccnz .LBB0_585

.Lstg_mid2:
	s_add_i32 s0, s83, 0x3000
	s_cmpk_lg_u32 s83, 0x9000
	s_cselect_b32 s82, s0, 0
	ds_read_b64_tr_b16 v[72:73], v141 offset:54272
	ds_read_b64_tr_b16 v[74:75], v141 offset:54784
	s_waitcnt lgkmcnt(6)
	v_mfma_f32_32x32x16_bf16 v[16:31], v[132:135], v[64:67], v[16:31]
	v_exp_f32_e32 v48, v48
	v_exp_f32_e32 v49, v49
	v_exp_f32_e32 v50, v50
	v_exp_f32_e32 v51, v51
	ds_read_b64_tr_b16 v[64:65], v141 offset:51200
	ds_read_b64_tr_b16 v[66:67], v141 offset:51712
	s_waitcnt lgkmcnt(6)
	v_mfma_f32_32x32x16_bf16 v[0:15], v[132:135], v[80:83], v[0:15]
	v_exp_f32_e32 v52, v52
	v_exp_f32_e32 v53, v53
	v_exp_f32_e32 v54, v54
	v_exp_f32_e32 v55, v55
	ds_read_b64_tr_b16 v[76:77], v141 offset:55296
	ds_read_b64_tr_b16 v[78:79], v141 offset:55808
	s_waitcnt lgkmcnt(6)
	v_mfma_f32_32x32x16_bf16 v[16:31], v[128:131], v[68:71], v[16:31]
	v_exp_f32_e32 v56, v56
	v_exp_f32_e32 v57, v57
	v_exp_f32_e32 v58, v58
	v_exp_f32_e32 v59, v59
	ds_read_b64_tr_b16 v[68:69], v141 offset:52224
	ds_read_b64_tr_b16 v[70:71], v141 offset:52736
	s_waitcnt lgkmcnt(6)
	v_mfma_f32_32x32x16_bf16 v[0:15], v[128:131], v[72:75], v[0:15]
	v_exp_f32_e32 v60, v60
	v_exp_f32_e32 v61, v61
	v_exp_f32_e32 v62, v62
	v_exp_f32_e32 v63, v63
	ds_read_b64_tr_b16 v[72:73], v141 offset:56320
	ds_read_b64_tr_b16 v[74:75], v141 offset:56832
	s_waitcnt lgkmcnt(6)
	v_mfma_f32_32x32x16_bf16 v[16:31], v[124:127], v[64:67], v[16:31]
	v_exp_f32_e32 v32, v32
	v_exp_f32_e32 v33, v33
	v_exp_f32_e32 v34, v34
	v_exp_f32_e32 v35, v35
	v_add_u32_e32 v64, s82, v179
	ds_read_b128 v[80:83], v64
	s_waitcnt lgkmcnt(5)
	v_mfma_f32_32x32x16_bf16 v[0:15], v[124:127], v[76:79], v[0:15]
	v_exp_f32_e32 v36, v36
	v_exp_f32_e32 v37, v37
	v_exp_f32_e32 v38, v38
	v_exp_f32_e32 v39, v39
	ds_read_b128 v[136:139], v64 offset:512
	s_waitcnt lgkmcnt(4)
	v_mfma_f32_32x32x16_bf16 v[16:31], v[120:123], v[68:71], v[16:31]
	v_exp_f32_e32 v40, v40
	v_exp_f32_e32 v41, v41
	v_exp_f32_e32 v42, v42
	v_exp_f32_e32 v43, v43
	ds_read_b128 v[140:143], v64 offset:2048
	s_waitcnt lgkmcnt(3)
	v_mfma_f32_32x32x16_bf16 v[0:15], v[120:123], v[72:75], v[0:15]
	v_exp_f32_e32 v44, v44
	v_exp_f32_e32 v45, v45
	v_exp_f32_e32 v46, v46
	v_exp_f32_e32 v47, v47
	s_cmp_lt_u32 s90, 4
	s_cbranch_scc0 .Lstg_end2
	s_waitcnt vmcnt(3) lgkmcnt(0)
	s_barrier
.Lstg_end2:
	s_andn2_b64 vcc, exec, s[60:61]
	s_cbranch_vccnz .LBB0_587
	s_waitcnt lgkmcnt(0)
	v_add_u32_e32 v76, s54, v146
	ds_read_b128 v[64:67], v76 offset:96
	ds_read_b128 v[68:71], v76 offset:64
	ds_read_b128 v[72:75], v76 offset:32
	ds_read_b128 v[76:79], v76
	s_waitcnt lgkmcnt(3)
	v_pk_mul_f32 v[28:29], v[28:29], v[64:65]
	s_waitcnt lgkmcnt(2)
	v_pk_mul_f32 v[24:25], v[24:25], v[68:69]
	s_waitcnt lgkmcnt(1)
	v_pk_mul_f32 v[20:21], v[20:21], v[72:73]
	v_pk_mul_f32 v[30:31], v[30:31], v[66:67]
	v_pk_mul_f32 v[26:27], v[26:27], v[70:71]
	v_pk_mul_f32 v[22:23], v[22:23], v[74:75]
	s_waitcnt lgkmcnt(0)
	v_pk_mul_f32 v[18:19], v[18:19], v[78:79]
	v_pk_mul_f32 v[16:17], v[16:17], v[76:77]
	v_pk_mul_f32 v[12:13], v[12:13], v[64:65]
	v_pk_mul_f32 v[8:9], v[8:9], v[68:69]
	v_pk_mul_f32 v[4:5], v[4:5], v[72:73]
	v_pk_mul_f32 v[14:15], v[14:15], v[66:67]
	v_pk_mul_f32 v[10:11], v[10:11], v[70:71]
	v_pk_mul_f32 v[6:7], v[6:7], v[74:75]
	v_pk_mul_f32 v[2:3], v[2:3], v[78:79]
	v_pk_mul_f32 v[0:1], v[0:1], v[76:77]
.LBB0_587:
	s_add_i32 s0, s79, 0x2000
	s_cmpk_lg_i32 s79, 0x4000
	s_cselect_b32 s0, s0, 0xe800
	s_cmpk_lg_u32 s79, 0xe800
	s_cselect_b32 s84, s0, 0
	s_add_i32 s0, s82, 0x3000
	s_cmpk_lg_u32 s82, 0x9000
	s_cselect_b32 s85, s0, 0
	s_add_i32 s0, s87, 2
	s_add_u32 s68, s68, 0x30000
	s_addc_u32 s69, s69, 0
	s_add_u32 s48, s48, 0x48000
	s_addc_u32 s49, s49, 0
	s_add_u32 s8, s8, 0x2000
	s_addc_u32 s9, s9, 0
	s_cmp_ge_u32 s0, s80
	s_cbranch_scc1 .LBB0_597
	s_mov_b32 s87, s0
	s_mov_b32 s0, s86
	s_mov_b32 s86, s84
	s_mov_b32 s84, s83
	s_mov_b32 s83, s85
	s_branch .LBB0_571

.LBB0_599:
	v_add_u32_e32 v120, s82, v179
	ds_read_b128 v[220:223], v120 offset:2560
	v_add_u32_e32 v168, s86, v180
	v_add_f32_e32 v64, v48, v49
	s_waitcnt lgkmcnt(3)
	v_mfma_f32_32x32x16_bf16 v[80:95], v[80:83], v[116:119], 0
	v_add_f32_e32 v64, v50, v64
	v_add_f32_e32 v64, v51, v64
	v_add_f32_e32 v64, v52, v64
	v_cvt_pk_bf16_f32 v132, v48, v49
	ds_read_b128 v[224:227], v120 offset:4096
	v_add_f32_e32 v48, v53, v64
	s_waitcnt lgkmcnt(3)
	v_mfma_f32_32x32x16_bf16 v[64:79], v[136:139], v[116:119], 0
	v_add_f32_e32 v48, v54, v48
	v_add_f32_e32 v121, v55, v48
	v_cvt_pk_bf16_f32 v133, v50, v51
	ds_read_b128 v[48:51], v120 offset:4608
	s_waitcnt lgkmcnt(3)
	v_mfma_f32_32x32x16_bf16 v[80:95], v[140:143], v[112:115], v[80:95]
	v_add_f32_e32 v121, v56, v121
	v_add_f32_e32 v121, v57, v121
	v_add_f32_e32 v121, v58, v121
	v_cvt_pk_bf16_f32 v134, v52, v53
	ds_read_b128 v[136:139], v120 offset:6144
	s_waitcnt lgkmcnt(3)
	v_mfma_f32_32x32x16_bf16 v[64:79], v[220:223], v[112:115], v[64:79]
	v_add_f32_e32 v52, v59, v121
	v_add_f32_e32 v52, v60, v52
	v_add_f32_e32 v121, v61, v52
	v_cvt_pk_bf16_f32 v135, v54, v55
	ds_read_b128 v[52:55], v120 offset:6656
	s_waitcnt lgkmcnt(3)
	v_mfma_f32_32x32x16_bf16 v[80:95], v[224:227], v[104:107], v[80:95]
	v_add_f32_e32 v121, v62, v121
	v_add_f32_e32 v121, v63, v121
	v_add_f32_e32 v121, v32, v121
	v_cvt_pk_bf16_f32 v128, v56, v57
	ds_read_b128 v[140:143], v120 offset:8192
	s_waitcnt lgkmcnt(3)
	v_mfma_f32_32x32x16_bf16 v[64:79], v[48:51], v[104:107], v[64:79]
	v_add_f32_e32 v48, v33, v121
	v_add_f32_e32 v48, v34, v48
	v_add_f32_e32 v56, v35, v48
	v_cvt_pk_bf16_f32 v129, v58, v59
	ds_read_b128 v[48:51], v120 offset:8704
	s_waitcnt lgkmcnt(3)
	v_mfma_f32_32x32x16_bf16 v[80:95], v[136:139], v[96:99], v[80:95]
	v_add_f32_e32 v56, v36, v56
	v_add_f32_e32 v56, v37, v56
	v_add_f32_e32 v121, v38, v56
	v_cvt_pk_bf16_f32 v130, v60, v61
	ds_read_b128 v[56:59], v120 offset:10240
	s_waitcnt lgkmcnt(3)
	v_mfma_f32_32x32x16_bf16 v[64:79], v[52:55], v[96:99], v[64:79]
	v_add_f32_e32 v52, v39, v121
	v_add_f32_e32 v52, v40, v52
	v_add_f32_e32 v60, v41, v52
	v_cvt_pk_bf16_f32 v131, v62, v63
	ds_read_b128 v[52:55], v120 offset:10752
	s_waitcnt lgkmcnt(3)
	v_mfma_f32_32x32x16_bf16 v[80:95], v[140:143], v[108:111], v[80:95]
	v_add_f32_e32 v60, v42, v60
	v_add_f32_e32 v60, v43, v60
	v_cvt_pk_bf16_f32 v124, v32, v33
	v_cvt_pk_bf16_f32 v125, v34, v35
	ds_read_b64_tr_b16 v[32:33], v168 offset:49152
	ds_read_b64_tr_b16 v[34:35], v168 offset:49664
	s_waitcnt lgkmcnt(4)
	v_mfma_f32_32x32x16_bf16 v[64:79], v[48:51], v[108:111], v[64:79]
	v_add_f32_e32 v48, v44, v60
	v_add_f32_e32 v60, v45, v48
	v_cvt_pk_bf16_f32 v126, v36, v37
	v_cvt_pk_bf16_f32 v127, v38, v39
	ds_read_b64_tr_b16 v[48:49], v168 offset:53248
	ds_read_b64_tr_b16 v[50:51], v168 offset:53760
	s_waitcnt lgkmcnt(5)
	v_mfma_f32_32x32x16_bf16 v[80:95], v[56:59], v[100:103], v[80:95]
	v_add_f32_e32 v56, v46, v60
	v_cvt_pk_bf16_f32 v120, v40, v41
	v_cvt_pk_bf16_f32 v121, v42, v43
	ds_read_b64_tr_b16 v[36:37], v168 offset:50176
	ds_read_b64_tr_b16 v[38:39], v168 offset:50688
	s_waitcnt lgkmcnt(6)
	v_mfma_f32_32x32x16_bf16 v[64:79], v[52:55], v[100:103], v[64:79]
	v_add_f32_e32 v40, v47, v56
	v_cvt_pk_bf16_f32 v122, v44, v45
	v_cvt_pk_bf16_f32 v123, v46, v47
	s_add_i32 s0, s87, 1
	s_cmp_ge_u32 s0, s80
	s_cselect_b64 s[8:9], -1, 0
	s_and_b64 vcc, exec, s[8:9]
	s_cbranch_vccnz .LBB0_603
	s_add_u32 s0, s64, 0xfffdc000
	s_addc_u32 s1, s65, -1
	s_add_i32 s46, s83, s55
	s_mov_b32 m0, s46
	s_nop 0
	global_load_lds_dwordx4 v183, s[0:1]
	s_and_saveexec_b64 s[0:1], s[2:3]
	s_cbranch_execz .LBB0_602
	s_add_u32 s46, s68, 0xfffff000
	s_addc_u32 s47, s69, -1
	s_add_i32 s48, s83, s76
	s_mov_b32 m0, s48
	s_nop 0
	global_load_lds_dwordx4 v184, s[46:47]

.LBB0_603:
	s_add_i32 s0, s84, s33
	s_mov_b32 m0, s0
	s_nop 0
	global_load_lds_dwordx4 v185, s[66:67]
	s_add_i32 s46, s81, s87
	s_add_i32 s0, s46, 2
	s_cmp_lt_i32 s0, 0
	s_cbranch_scc1 .LBB0_605
	v_subrev_u32_e32 v41, 64, v167
	v_cmp_le_i32_e32 vcc, v41, v187
	v_subrev_u32_e32 v42, 62, v167
	s_nop 0
	v_cndmask_b32_e32 v64, v218, v64, vcc
	v_cmp_lt_i32_e32 vcc, v41, v186
	s_nop 1
	v_cndmask_b32_e32 v81, v218, v81, vcc
	v_cmp_le_i32_e32 vcc, v41, v186
	s_nop 1
	v_cndmask_b32_e32 v80, v218, v80, vcc
	v_cmp_le_i32_e32 vcc, v41, v188
	s_nop 1
	v_cndmask_b32_e32 v65, v218, v65, vcc
	v_cmp_le_i32_e32 vcc, v42, v186
	v_subrev_u32_e32 v42, 61, v167
	s_nop 0
	v_cndmask_b32_e32 v82, v218, v82, vcc
	v_cmp_le_i32_e32 vcc, v41, v189
	s_nop 1
	v_cndmask_b32_e32 v66, v218, v66, vcc
	v_cmp_le_i32_e32 vcc, v42, v186
	s_nop 1
	v_cndmask_b32_e32 v83, v218, v83, vcc
	v_cmp_le_i32_e32 vcc, v41, v190
	s_nop 1
	v_cndmask_b32_e32 v67, v218, v67, vcc
	v_cmp_le_i32_e32 vcc, v41, v191
	s_nop 1
	v_cndmask_b32_e32 v84, v218, v84, vcc
	v_cmp_le_i32_e32 vcc, v41, v192
	s_nop 1
	v_cndmask_b32_e32 v68, v218, v68, vcc
	v_cmp_le_i32_e32 vcc, v41, v193
	s_nop 1
	v_cndmask_b32_e32 v85, v218, v85, vcc
	v_cmp_le_i32_e32 vcc, v41, v194
	s_nop 1
	v_cndmask_b32_e32 v69, v218, v69, vcc
	v_cmp_le_i32_e32 vcc, v41, v195
	s_nop 1
	v_cndmask_b32_e32 v86, v218, v86, vcc
	v_cmp_le_i32_e32 vcc, v41, v196
	s_nop 1
	v_cndmask_b32_e32 v70, v218, v70, vcc
	v_cmp_le_i32_e32 vcc, v41, v197
	s_nop 1
	v_cndmask_b32_e32 v87, v218, v87, vcc
	v_cmp_le_i32_e32 vcc, v41, v198
	s_nop 1
	v_cndmask_b32_e32 v71, v218, v71, vcc
	v_cmp_le_i32_e32 vcc, v41, v199
	s_nop 1
	v_cndmask_b32_e32 v88, v218, v88, vcc
	v_cmp_le_i32_e32 vcc, v41, v200
	s_nop 1
	v_cndmask_b32_e32 v72, v218, v72, vcc
	v_cmp_le_i32_e32 vcc, v41, v201
	s_nop 1
	v_cndmask_b32_e32 v89, v218, v89, vcc
	v_cmp_le_i32_e32 vcc, v41, v202
	s_nop 1
	v_cndmask_b32_e32 v73, v218, v73, vcc
	v_cmp_le_i32_e32 vcc, v41, v203
	s_nop 1
	v_cndmask_b32_e32 v90, v218, v90, vcc
	v_cmp_le_i32_e32 vcc, v41, v204
	s_nop 1
	v_cndmask_b32_e32 v74, v218, v74, vcc
	v_cmp_le_i32_e32 vcc, v41, v205
	s_nop 1
	v_cndmask_b32_e32 v91, v218, v91, vcc
	v_cmp_le_i32_e32 vcc, v41, v206
	s_nop 1
	v_cndmask_b32_e32 v75, v218, v75, vcc
	v_cmp_le_i32_e32 vcc, v41, v207
	s_nop 1
	v_cndmask_b32_e32 v92, v218, v92, vcc
	v_cmp_le_i32_e32 vcc, v41, v208
	s_nop 1
	v_cndmask_b32_e32 v76, v218, v76, vcc
	v_cmp_le_i32_e32 vcc, v41, v209
	s_nop 1
	v_cndmask_b32_e32 v93, v218, v93, vcc
	v_cmp_le_i32_e32 vcc, v41, v210
	s_nop 1
	v_cndmask_b32_e32 v77, v218, v77, vcc
	v_cmp_le_i32_e32 vcc, v41, v211
	s_nop 1
	v_cndmask_b32_e32 v94, v218, v94, vcc
	v_cmp_le_i32_e32 vcc, v41, v212
	s_nop 1
	v_cndmask_b32_e32 v78, v218, v78, vcc
	v_cmp_le_i32_e32 vcc, v41, v213
	s_nop 1
	v_cndmask_b32_e32 v95, v218, v95, vcc
	v_cmp_le_i32_e32 vcc, v41, v214
	s_nop 1
	v_cndmask_b32_e32 v79, v218, v79, vcc

.LBB0_617:
	ds_read_b128 v[140:143], v169 offset:2560
	v_add_u32_e32 v168, s79, v180
	v_add_f32_e32 v40, v80, v81
	s_waitcnt lgkmcnt(3)
	v_mfma_f32_32x32x16_bf16 v[48:63], v[32:35], v[116:119], 0
	v_add_f32_e32 v40, v82, v40
	v_add_f32_e32 v40, v83, v40
	v_add_f32_e32 v40, v84, v40
	v_cvt_pk_bf16_f32 v132, v80, v81
	ds_read_b128 v[220:223], v169 offset:4096
	v_add_f32_e32 v32, v85, v40
	v_add_f32_e32 v32, v86, v32
	v_add_f32_e32 v80, v87, v32
	s_waitcnt lgkmcnt(3)
	v_mfma_f32_32x32x16_bf16 v[32:47], v[36:39], v[116:119], 0
	v_cvt_pk_bf16_f32 v133, v82, v83
	ds_read_b128 v[224:227], v169 offset:4608
	s_waitcnt lgkmcnt(3)
	v_mfma_f32_32x32x16_bf16 v[48:63], v[136:139], v[112:115], v[48:63]
	v_add_f32_e32 v80, v88, v80
	v_add_f32_e32 v80, v89, v80
	v_add_f32_e32 v80, v90, v80
	v_cvt_pk_bf16_f32 v134, v84, v85
	ds_read_b128 v[228:231], v169 offset:6144
	s_waitcnt lgkmcnt(3)
	v_mfma_f32_32x32x16_bf16 v[32:47], v[140:143], v[112:115], v[32:47]
	v_add_f32_e32 v80, v91, v80
	v_add_f32_e32 v80, v92, v80
	v_add_f32_e32 v80, v93, v80
	v_cvt_pk_bf16_f32 v135, v86, v87
	ds_read_b128 v[84:87], v169 offset:6656
	s_waitcnt lgkmcnt(3)
	v_mfma_f32_32x32x16_bf16 v[48:63], v[220:223], v[104:107], v[48:63]
	v_add_f32_e32 v80, v94, v80
	v_add_f32_e32 v80, v95, v80
	v_add_f32_e32 v120, v64, v80
	v_cvt_pk_bf16_f32 v128, v88, v89
	ds_read_b128 v[80:83], v169 offset:8192
	s_waitcnt lgkmcnt(3)
	v_mfma_f32_32x32x16_bf16 v[32:47], v[224:227], v[104:107], v[32:47]
	v_add_f32_e32 v88, v65, v120
	v_add_f32_e32 v88, v66, v88
	v_add_f32_e32 v88, v67, v88
	v_cvt_pk_bf16_f32 v129, v90, v91
	ds_read_b128 v[136:139], v169 offset:8704
	s_waitcnt lgkmcnt(3)
	v_mfma_f32_32x32x16_bf16 v[48:63], v[228:231], v[96:99], v[48:63]
	v_add_f32_e32 v88, v68, v88
	v_add_f32_e32 v88, v69, v88
	v_add_f32_e32 v88, v70, v88
	v_cvt_pk_bf16_f32 v130, v92, v93
	ds_read_b128 v[140:143], v169 offset:10240
	s_waitcnt lgkmcnt(3)
	v_mfma_f32_32x32x16_bf16 v[32:47], v[84:87], v[96:99], v[32:47]
	v_add_f32_e32 v84, v71, v88
	v_add_f32_e32 v84, v72, v84
	v_add_f32_e32 v84, v73, v84
	v_cvt_pk_bf16_f32 v131, v94, v95
	ds_read_b128 v[88:91], v169 offset:10752
	s_waitcnt lgkmcnt(3)
	v_mfma_f32_32x32x16_bf16 v[48:63], v[80:83], v[108:111], v[48:63]
	v_add_f32_e32 v84, v74, v84
	v_add_f32_e32 v92, v75, v84
	v_cvt_pk_bf16_f32 v124, v64, v65
	v_cvt_pk_bf16_f32 v125, v66, v67
	ds_read_b64_tr_b16 v[84:85], v168 offset:49152
	ds_read_b64_tr_b16 v[86:87], v168 offset:49664
	s_waitcnt lgkmcnt(4)
	v_mfma_f32_32x32x16_bf16 v[32:47], v[136:139], v[108:111], v[32:47]
	v_add_f32_e32 v64, v76, v92
	v_add_f32_e32 v64, v77, v64
	v_cvt_pk_bf16_f32 v126, v68, v69
	v_cvt_pk_bf16_f32 v127, v70, v71
	ds_read_b64_tr_b16 v[68:69], v168 offset:53248
	ds_read_b64_tr_b16 v[70:71], v168 offset:53760
	s_waitcnt lgkmcnt(5)
	v_mfma_f32_32x32x16_bf16 v[48:63], v[140:143], v[100:103], v[48:63]
	v_add_f32_e32 v92, v78, v64
	v_cvt_pk_bf16_f32 v120, v72, v73
	v_cvt_pk_bf16_f32 v121, v74, v75
	ds_read_b64_tr_b16 v[64:65], v168 offset:50176
	ds_read_b64_tr_b16 v[66:67], v168 offset:50688
	s_waitcnt lgkmcnt(6)
	v_mfma_f32_32x32x16_bf16 v[32:47], v[88:91], v[100:103], v[32:47]
	v_add_f32_e32 v72, v79, v92
	v_cvt_pk_bf16_f32 v122, v76, v77
	v_cvt_pk_bf16_f32 v123, v78, v79
	s_add_i32 s83, s87, 2
	s_cmp_ge_u32 s83, s80
	s_cselect_b64 s[48:49], -1, 0
	s_and_b64 vcc, exec, s[48:49]
	s_cbranch_vccnz .LBB0_621
	s_add_i32 s0, s82, s55
	s_mov_b32 m0, s0
	s_nop 0
	global_load_lds_dwordx4 v183, s[64:65]
	s_and_saveexec_b64 s[0:1], s[2:3]
	s_cbranch_execz .LBB0_620
	s_add_i32 s47, s82, s76
	s_mov_b32 m0, s47
	s_nop 0
	global_load_lds_dwordx4 v184, s[68:69]

.LBB0_621:
	s_add_i32 s0, s84, 0x2000
	s_cmpk_lg_i32 s84, 0x4000
	s_cselect_b32 s0, s0, 0xe800
	s_cmpk_lg_u32 s84, 0xe800
	s_cselect_b32 s79, s0, 0
	s_cmp_lt_u32 s87, s80
	s_cselect_b64 s[0:1], -1, 0
	s_cmp_ge_u32 s87, s80
	s_cbranch_scc1 .LBB0_623
	s_add_u32 s86, s66, 0x18000
	s_addc_u32 s87, s67, 0
	s_add_i32 s47, s79, s33
	s_mov_b32 m0, s47
	s_nop 0
	global_load_lds_dwordx4 v185, s[86:87]

.LBB0_643:
	s_add_i32 s0, s79, 0x2000
	s_cmpk_lg_i32 s79, 0x4000
	s_cselect_b32 s0, s0, 0xe800
	s_cmpk_lg_u32 s79, 0xe800
	s_cselect_b32 s0, s0, 0
	s_add_i32 s1, s82, 0x3000
	s_cmpk_lg_u32 s82, 0x9000
	s_cselect_b32 s1, s1, 0
	s_add_u32 s66, s66, 0x30000
	s_addc_u32 s67, s67, 0
	s_add_u32 s64, s64, 0x48000
	s_addc_u32 s65, s65, 0
	s_add_u32 s68, s68, 0x2000
	s_addc_u32 s69, s69, 0
	s_add_i32 s8, s83, -1
	s_cmp_lt_u32 s8, s80
	v_add_u32_e32 v167, 0x80, v167
	s_cbranch_scc0 .LBB0_655
	s_mov_b32 s87, s83
	s_mov_b32 s86, s84
	s_mov_b32 s84, s0
	s_mov_b32 s83, s85
	s_mov_b32 s85, s1
	s_branch .LBB0_599

.LBB0_668:
	v_readlane_b32 s94, v246, 53
	s_ashr_i32 s4, s94, 7
	s_ashr_i32 s5, s4, 31
	s_lshl_b64 s[0:1], s[4:5], 22
	v_readlane_b32 s6, v244, 19
	v_readlane_b32 s7, v244, 20
	s_add_u32 s0, s6, s0
	s_addc_u32 s1, s7, s1
	s_lshl_b32 s2, s72, 6
	s_and_b32 s2, s2, 0xc0
	s_lshl_b32 s12, s2, 1
	s_add_u32 s10, s0, s12
	s_addc_u32 s11, s1, 0
	s_lshl_b64 s[0:1], s[4:5], 17
	s_add_u32 s0, s6, s0
	s_addc_u32 s1, s7, s1
	s_add_u32 s13, s0, s12
	s_addc_u32 s14, s1, 0
	s_add_u32 s0, s13, 0x600000
	s_addc_u32 s1, s14, 0
	s_add_u32 s8, s13, 0x640000
	s_addc_u32 s9, s14, 0
	s_lshl_b32 s2, s70, 8
	s_mov_b32 s3, 0
	s_add_i32 s2, s2, s71
	s_lshl_b64 s[6:7], s[2:3], 9
	s_add_u32 s6, s10, s6
	s_addc_u32 s7, s11, s7
	v_readlane_b32 s10, v246, 55
	s_cmp_lg_u32 0, -1
	v_mov_b32_e32 v149, 0
	v_lshl_add_u32 v33, v148, 9, s10
	v_readlane_b32 s10, v246, 56
	v_lshlrev_b32_e32 v148, 9, v170
	s_nop 0
	v_add_lshl_u32 v0, v181, s10, 9
	s_cselect_b32 s10, 0, 0
	v_lshl_add_u32 v96, v182, 1, v0
	s_add_i32 s15, s73, s10
	s_mov_b32 m0, s15
	s_nop 0
	global_load_lds_dwordx4 v33, s[0:1]
	v_lshl_add_u64 v[0:1], s[6:7], 0, v[148:149]
	s_mov_b32 m0, s33
	s_nop 0
	global_load_lds_dwordx4 v96, s[8:9]
	v_lshl_add_u64 v[0:1], v[150:151], 1, v[0:1]
	s_mov_b32 s6, 0xd000000
	s_add_u32 s10, s13, 0x608000
	v_add_co_u32_e32 v2, vcc, s6, v0
	s_addc_u32 s11, s14, 0
	s_add_i32 s16, s15, 0x3000
	s_mov_b32 m0, s16
	s_nop 0
	global_load_lds_dwordx4 v33, s[10:11]
	v_addc_co_u32_e32 v3, vcc, 0, v1, vcc
	global_load_dwordx4 v[136:139], v[2:3], off
	s_mov_b64 s[6:7], 0xd000000
	v_lshl_add_u64 v[0:1], v[0:1], 0, s[6:7]
	global_load_dwordx4 v[132:135], v[0:1], off offset:32
	global_load_dwordx4 v[128:131], v[0:1], off offset:64
	global_load_dwordx4 v[124:127], v[0:1], off offset:96
	s_add_u32 s6, s13, 0x610000
	s_addc_u32 s7, s14, 0
	s_addk_i32 s15, 0x6000
	s_mov_b32 m0, s15
	s_nop 0
	global_load_lds_dwordx4 v33, s[6:7]
	s_waitcnt vmcnt(3) lgkmcnt(0)
	s_barrier
	ds_read_b128 v[0:3], v179
	ds_read_b128 v[34:37], v179 offset:2048
	s_mov_b32 s10, 0x41400000
	s_waitcnt vmcnt(3) lgkmcnt(1)
	v_mfma_f32_32x32x16_bf16 v[16:31], v[0:3], v[136:139], 0
	ds_read_b128 v[0:3], v179 offset:512
	s_waitcnt vmcnt(2) lgkmcnt(1)
	v_mfma_f32_32x32x16_bf16 v[16:31], v[34:37], v[132:135], v[16:31]
	ds_read_b128 v[34:37], v179 offset:2560
	s_waitcnt lgkmcnt(1)
	v_mfma_f32_32x32x16_bf16 v[0:15], v[0:3], v[136:139], 0
	s_waitcnt lgkmcnt(0)
	v_mfma_f32_32x32x16_bf16 v[0:15], v[34:37], v[132:135], v[0:15]
	ds_read_b128 v[34:37], v179 offset:4096
	s_waitcnt vmcnt(1) lgkmcnt(0)
	v_mfma_f32_32x32x16_bf16 v[16:31], v[34:37], v[128:131], v[16:31]
	ds_read_b128 v[34:37], v179 offset:4608
	s_waitcnt lgkmcnt(0)
	v_mfma_f32_32x32x16_bf16 v[0:15], v[34:37], v[128:131], v[0:15]
	ds_read_b128 v[34:37], v179 offset:6144
	s_waitcnt vmcnt(0) lgkmcnt(0)
	v_mfma_f32_32x32x16_bf16 v[16:31], v[34:37], v[124:127], v[16:31]
	ds_read_b128 v[34:37], v179 offset:6656
	s_waitcnt lgkmcnt(0)
	v_mfma_f32_32x32x16_bf16 v[0:15], v[34:37], v[124:127], v[0:15]
	s_nop 8
	v_max_f32_e32 v32, v17, v17
	v_max_f32_e32 v34, v16, v16
	v_max_f32_e32 v32, v34, v32
	v_max3_f32 v35, v18, v19, v1
	v_max3_f32 v32, v32, v0, v2
	v_max3_f32 v34, v35, v22, v23
	v_max3_f32 v32, v32, v3, v20
	v_max3_f32 v34, v34, v6, v7
	v_max3_f32 v32, v32, v21, v4
	v_max3_f32 v34, v34, v26, v27
	v_max3_f32 v32, v32, v5, v24
	v_max3_f32 v34, v34, v10, v11
	v_max3_f32 v32, v32, v25, v8
	v_max3_f32 v34, v34, v30, v31
	v_max3_f32 v32, v32, v9, v28
	v_max3_f32 v34, v34, v14, v15
	v_max3_f32 v32, v32, v29, v12
	v_max3_f32 v32, v32, v13, v34
	v_mov_b32_e32 v34, v32
	s_nop 1
	v_permlane32_swap_b32_e32 v32, v34
	v_max_f32_e32 v34, v34, v34
	v_max_f32_e32 v32, v32, v32
	v_max_f32_e32 v32, v32, v34
	v_cmp_gt_f32_e64 vcc, |v32|, s10
	s_cmp_lg_u64 vcc, 0
	s_cselect_b64 s[6:7], -1, 0
	s_cbranch_vccnz .LBB0_1425
.LBB0_669:
	s_add_u32 s14, s0, 0x18000
	s_addc_u32 s15, s1, 0
	s_cmp_lg_u32 0, -1
	s_cselect_b32 s0, 0, 0
	s_add_i32 s0, s0, s73
	s_waitcnt vmcnt(0) lgkmcnt(0)
	s_barrier
	s_add_i32 s1, s0, 0x9000
	s_mov_b32 m0, s1
	s_nop 0
	global_load_lds_dwordx4 v33, s[14:15]
	s_add_u32 s14, s8, 0x8000
	s_addc_u32 s15, s9, 0
	s_add_i32 s1, s0, 0xe000
	s_mov_b32 m0, s1
	s_nop 0
	global_load_lds_dwordx4 v96, s[14:15]
	v_exp_f32_e32 v48, v0
	v_exp_f32_e32 v49, v1
	v_exp_f32_e32 v50, v2
	v_exp_f32_e32 v51, v3
	v_exp_f32_e32 v52, v4
	v_exp_f32_e32 v53, v5
	v_exp_f32_e32 v54, v6
	v_exp_f32_e32 v55, v7
	v_exp_f32_e32 v56, v8
	v_exp_f32_e32 v57, v9
	v_exp_f32_e32 v58, v10
	v_exp_f32_e32 v59, v11
	ds_read_b128 v[0:3], v179 offset:14336
	ds_read_b128 v[4:7], v179 offset:12800
	ds_read_b128 v[8:11], v179 offset:12288
	v_exp_f32_e32 v16, v16
	v_exp_f32_e32 v17, v17
	v_exp_f32_e32 v18, v18
	v_exp_f32_e32 v19, v19
	v_exp_f32_e32 v20, v20
	v_exp_f32_e32 v21, v21
	v_exp_f32_e32 v22, v22
	v_exp_f32_e32 v23, v23
	v_exp_f32_e32 v24, v24
	v_exp_f32_e32 v25, v25
	v_exp_f32_e32 v26, v26
	v_exp_f32_e32 v27, v27
	v_exp_f32_e32 v28, v28
	v_exp_f32_e32 v29, v29
	v_exp_f32_e32 v30, v30
	v_exp_f32_e32 v31, v31
	v_exp_f32_e32 v76, v12
	v_exp_f32_e32 v77, v13
	v_exp_f32_e32 v78, v14
	v_exp_f32_e32 v79, v15
	ds_read_b128 v[12:15], v179 offset:14848
	v_add_f32_e32 v32, v16, v17
	s_waitcnt lgkmcnt(1)
	v_mfma_f32_32x32x16_bf16 v[60:75], v[8:11], v[136:139], 0
	v_add_f32_e32 v32, v18, v32
	v_add_f32_e32 v32, v19, v32
	v_cvt_pk_bf16_f32 v112, v16, v17
	v_add_f32_e32 v32, v20, v32
	v_mov_b32_e32 v113, v112
	v_mov_b32_e32 v114, v112
	v_mov_b32_e32 v115, v112
	ds_read_b128 v[8:11], v179 offset:16384
	v_add_f32_e32 v16, v21, v32
	v_mfma_f32_32x32x16_bf16 v[32:47], v[4:7], v[136:139], 0
	v_add_f32_e32 v16, v22, v16
	v_add_f32_e32 v16, v23, v16
	v_cvt_pk_bf16_f32 v113, v18, v19
	ds_read_b128 v[4:7], v179 offset:16896
	v_mfma_f32_32x32x16_bf16 v[60:75], v[0:3], v[132:135], v[60:75]
	v_add_f32_e32 v16, v24, v16
	v_add_f32_e32 v16, v25, v16
	v_add_f32_e32 v16, v26, v16
	v_cvt_pk_bf16_f32 v114, v20, v21
	ds_read_b128 v[0:3], v179 offset:18432
	s_waitcnt lgkmcnt(3)
	v_mfma_f32_32x32x16_bf16 v[32:47], v[12:15], v[132:135], v[32:47]
	v_add_f32_e32 v16, v27, v16
	v_add_f32_e32 v16, v28, v16
	v_add_f32_e32 v16, v29, v16
	v_cvt_pk_bf16_f32 v115, v22, v23
	ds_read_b128 v[12:15], v179 offset:18944
	s_waitcnt lgkmcnt(3)
	v_mfma_f32_32x32x16_bf16 v[60:75], v[8:11], v[128:131], v[60:75]
	v_add_f32_e32 v16, v30, v16
	v_add_f32_e32 v16, v31, v16
	v_cvt_pk_bf16_f32 v116, v24, v25
	v_add_f32_e32 v16, v48, v16
	v_mov_b32_e32 v117, v116
	v_mov_b32_e32 v118, v116
	v_mov_b32_e32 v119, v116
	s_waitcnt lgkmcnt(2)
	v_mfma_f32_32x32x16_bf16 v[32:47], v[4:7], v[128:131], v[32:47]
	v_add_f32_e32 v8, v49, v16
	v_add_f32_e32 v8, v50, v8
	v_add_f32_e32 v8, v51, v8
	v_cvt_pk_bf16_f32 v117, v26, v27
	s_waitcnt lgkmcnt(1)
	v_mfma_f32_32x32x16_bf16 v[60:75], v[0:3], v[124:127], v[60:75]
	v_add_f32_e32 v4, v52, v8
	v_add_f32_e32 v4, v53, v4
	v_add_f32_e32 v4, v54, v4
	v_cvt_pk_bf16_f32 v118, v28, v29
	s_waitcnt lgkmcnt(0)
	v_mfma_f32_32x32x16_bf16 v[32:47], v[12:15], v[124:127], v[32:47]
	v_add_f32_e32 v0, v55, v4
	v_add_f32_e32 v0, v56, v0
	v_add_f32_e32 v0, v57, v0
	v_cvt_pk_bf16_f32 v119, v30, v31
	s_nop 0
	v_add_f32_e32 v0, v58, v0
	v_add_f32_e32 v4, v59, v0
	v_cvt_pk_bf16_f32 v120, v48, v49
	v_cvt_pk_bf16_f32 v121, v50, v51
	ds_read_b64_tr_b16 v[0:1], v180 offset:49152
	ds_read_b64_tr_b16 v[2:3], v180 offset:49664
	v_add_f32_e32 v4, v76, v4
	v_add_f32_e32 v4, v77, v4
	v_cvt_pk_bf16_f32 v122, v52, v53
	v_cvt_pk_bf16_f32 v123, v54, v55
	ds_read_b64_tr_b16 v[16:17], v180 offset:53248
	ds_read_b64_tr_b16 v[18:19], v180 offset:53760
	v_add_f32_e32 v4, v78, v4
	v_cvt_pk_bf16_f32 v108, v56, v57
	v_cvt_pk_bf16_f32 v109, v58, v59
	ds_read_b64_tr_b16 v[48:49], v180 offset:50176
	ds_read_b64_tr_b16 v[50:51], v180 offset:50688
	v_add_f32_e32 v4, v79, v4
	v_cvt_pk_bf16_f32 v110, v76, v77
	v_cvt_pk_bf16_f32 v111, v78, v79
	s_nop 0
	v_add_f32_e32 v97, 0, v4
	v_max_f32_e32 v4, v61, v61
	v_max_f32_e32 v5, v60, v60
	v_max_f32_e32 v4, v5, v4
	v_max3_f32 v5, v62, v63, v33
	v_max3_f32 v4, v4, v32, v34
	v_max3_f32 v4, v4, v35, v64
	v_max3_f32 v5, v5, v66, v67
	v_max3_f32 v4, v4, v65, v36
	v_max3_f32 v5, v5, v38, v39
	v_max3_f32 v4, v4, v37, v68
	v_max3_f32 v5, v5, v70, v71
	v_max3_f32 v4, v4, v69, v40
	v_max3_f32 v5, v5, v42, v43
	v_max3_f32 v4, v4, v41, v72
	v_max3_f32 v5, v5, v74, v75
	v_max3_f32 v4, v4, v73, v44
	v_max3_f32 v5, v5, v46, v47
	v_max3_f32 v4, v4, v45, v5
	v_readlane_b32 s84, v246, 28
	s_add_u32 s14, s8, 0x10000
	v_sub_f32_e32 v5, v4, v149
	v_readlane_b32 s85, v246, 29
	s_addc_u32 s15, s9, 0
	s_add_i32 s0, s0, 0x10000
	s_mov_b32 m0, s0
	s_nop 0
	global_load_lds_dwordx4 v96, s[14:15]
	v_cmp_lt_f32_e32 vcc, s10, v5
	v_readlane_b32 s86, v246, 30
	v_readlane_b32 s87, v246, 31
	v_readlane_b32 s88, v246, 32
	v_readlane_b32 s89, v246, 33
	s_mov_b64 s[80:81], s[84:85]
	s_cmp_lg_u64 vcc, 0
	v_readlane_b32 s91, v246, 35
	s_mov_b64 s[82:83], s[86:87]
	s_mov_b64 s[84:85], s[88:89]
	v_readlane_b32 s60, v246, 19
	v_readlane_b32 s88, v246, 36
	s_cselect_b64 s[10:11], -1, 0
	v_readlane_b32 s64, v246, 23
	v_readlane_b32 s65, v246, 24
	v_readlane_b32 s66, v246, 25
	v_readlane_b32 s67, v246, 26
	v_readlane_b32 s89, v246, 37
	v_readlane_b32 s91, v246, 54
	v_readlane_b32 s90, v246, 34
	v_readlane_b32 s61, v246, 20
	v_readlane_b32 s62, v246, 21
	v_readlane_b32 s63, v246, 22
	s_cbranch_vccnz .LBB0_1426
	v_readlane_b32 s90, v246, 60
	s_mov_b32 s73, s46
	s_andn2_b64 vcc, exec, s[6:7]
	s_cbranch_vccnz .LBB0_672

.LBB0_674:
	ds_read_b128 v[98:101], v179 offset:27136
	v_add_f32_e32 v56, v60, v61
	s_waitcnt lgkmcnt(3)
	v_mfma_f32_32x32x16_bf16 v[76:91], v[48:51], v[136:139], 0
	v_add_f32_e32 v56, v62, v56
	v_add_f32_e32 v56, v63, v56
	v_add_f32_e32 v56, v64, v56
	v_cvt_pk_bf16_f32 v112, v60, v61
	ds_read_b128 v[102:105], v179 offset:28672
	v_add_f32_e32 v48, v65, v56
	v_add_f32_e32 v48, v66, v48
	v_add_f32_e32 v116, v67, v48
	v_cvt_pk_bf16_f32 v113, v62, v63
	s_waitcnt lgkmcnt(3)
	v_mfma_f32_32x32x16_bf16 v[48:63], v[52:55], v[136:139], 0
	ds_read_b128 v[106:109], v179 offset:29184
	s_waitcnt lgkmcnt(3)
	v_mfma_f32_32x32x16_bf16 v[76:91], v[92:95], v[132:135], v[76:91]
	v_add_f32_e32 v114, v68, v116
	v_add_f32_e32 v114, v69, v114
	v_add_f32_e32 v116, v70, v114
	v_cvt_pk_bf16_f32 v114, v64, v65
	ds_read_b128 v[92:95], v179 offset:30720
	s_waitcnt lgkmcnt(3)
	v_mfma_f32_32x32x16_bf16 v[48:63], v[98:101], v[132:135], v[48:63]
	v_add_f32_e32 v64, v71, v116
	v_add_f32_e32 v64, v72, v64
	v_add_f32_e32 v116, v73, v64
	v_cvt_pk_bf16_f32 v115, v66, v67
	ds_read_b128 v[64:67], v179 offset:31232
	s_waitcnt lgkmcnt(3)
	v_mfma_f32_32x32x16_bf16 v[76:91], v[102:105], v[128:131], v[76:91]
	v_add_f32_e32 v98, v74, v116
	v_add_f32_e32 v98, v75, v98
	v_add_f32_e32 v98, v32, v98
	v_cvt_pk_bf16_f32 v116, v68, v69
	s_waitcnt lgkmcnt(2)
	v_mfma_f32_32x32x16_bf16 v[48:63], v[106:109], v[128:131], v[48:63]
	v_add_f32_e32 v68, v33, v98
	v_add_f32_e32 v68, v34, v68
	v_add_f32_e32 v68, v35, v68
	v_cvt_pk_bf16_f32 v117, v70, v71
	s_waitcnt lgkmcnt(1)
	v_mfma_f32_32x32x16_bf16 v[76:91], v[92:95], v[124:127], v[76:91]
	v_add_f32_e32 v68, v36, v68
	v_add_f32_e32 v68, v37, v68
	v_add_f32_e32 v68, v38, v68
	v_cvt_pk_bf16_f32 v118, v72, v73
	s_waitcnt lgkmcnt(0)
	v_mfma_f32_32x32x16_bf16 v[48:63], v[64:67], v[124:127], v[48:63]
	v_add_f32_e32 v68, v39, v68
	v_add_f32_e32 v68, v40, v68
	v_add_f32_e32 v68, v41, v68
	v_cvt_pk_bf16_f32 v119, v74, v75
	s_nop 0
	v_add_f32_e32 v64, v42, v68
	v_add_f32_e32 v68, v43, v64
	v_cvt_pk_bf16_f32 v120, v32, v33
	v_cvt_pk_bf16_f32 v121, v34, v35
	ds_read_b64_tr_b16 v[64:65], v180 offset:57344
	ds_read_b64_tr_b16 v[66:67], v180 offset:57856
	v_add_f32_e32 v32, v44, v68
	v_add_f32_e32 v32, v45, v32
	v_cvt_pk_bf16_f32 v122, v36, v37
	v_cvt_pk_bf16_f32 v123, v38, v39
	ds_read_b64_tr_b16 v[36:37], v180 offset:61440
	ds_read_b64_tr_b16 v[38:39], v180 offset:61952
	v_add_f32_e32 v68, v46, v32
	v_cvt_pk_bf16_f32 v108, v40, v41
	v_cvt_pk_bf16_f32 v109, v42, v43
	ds_read_b64_tr_b16 v[32:33], v180 offset:58368
	ds_read_b64_tr_b16 v[34:35], v180 offset:58880
	v_add_f32_e32 v40, v47, v68
	v_cvt_pk_bf16_f32 v110, v44, v45
	v_cvt_pk_bf16_f32 v111, v46, v47
	s_nop 0
	v_add_f32_e32 v68, v97, v40
	v_max_f32_e32 v40, v77, v77
	v_max_f32_e32 v41, v76, v76
	v_max_f32_e32 v40, v41, v40
	v_max3_f32 v41, v78, v79, v49
	v_max3_f32 v40, v40, v48, v50
	v_max3_f32 v40, v40, v51, v80
	v_max3_f32 v41, v41, v82, v83
	v_max3_f32 v40, v40, v81, v52
	v_max3_f32 v41, v41, v54, v55
	v_max3_f32 v40, v40, v53, v84
	v_max3_f32 v41, v41, v86, v87
	v_max3_f32 v40, v40, v85, v56
	v_max3_f32 v41, v41, v58, v59
	v_max3_f32 v40, v40, v57, v88
	v_max3_f32 v41, v41, v90, v91
	v_max3_f32 v40, v40, v89, v60
	v_max3_f32 v41, v41, v62, v63
	s_add_u32 s0, s8, 0x18000
	v_max3_f32 v40, v40, v61, v41
	s_addc_u32 s1, s9, 0
	s_mov_b32 m0, s33
	s_nop 0
	global_load_lds_dwordx4 v96, s[0:1]
	v_sub_f32_e32 v41, v40, v149
	s_mov_b32 s0, 0x41400000
	v_cmp_lt_f32_e32 vcc, s0, v41
	s_cmp_lg_u64 vcc, 0
	s_cselect_b64 s[8:9], -1, 0
	s_cbranch_vccnz .LBB0_1429
	s_andn2_b64 vcc, exec, s[6:7]
	s_cbranch_vccnz .LBB0_677

.LBB0_748:
	s_ashr_i32 s0, s3, 3
	s_add_u32 s31, s4, 0xd800000
	s_addc_u32 s33, s5, 0
	s_add_u32 s34, s4, 0x1400000
	s_addc_u32 s35, s5, 0
	s_lshl_b32 s1, s90, 10
	v_lshlrev_b32_e32 v0, 4, v196
	v_add_u32_e32 v1, s1, v0
	v_ashrrev_i32_e32 v2, 31, v1
	v_lshrrev_b32_e32 v2, 22, v2
	v_add_u32_e32 v2, v1, v2
	v_ashrrev_i32_e32 v2, 10, v2
	v_mul_i32_i24_e32 v3, 0x400, v2
	v_sub_u32_e32 v3, v1, v3
	v_lshrrev_b32_e32 v4, 4, v3
	v_bitop3_b32 v3, v4, v3, 32 bitop3:0x6c
	v_ashrrev_i32_e32 v5, 31, v3
	v_lshrrev_b32_e32 v5, 26, v5
	v_lshlrev_b32_e32 v4, 3, v2
	v_add_u32_e32 v5, v3, v5
	v_and_b32_e32 v4, -16, v4
	v_ashrrev_i32_e32 v6, 6, v5
	v_and_b32_e32 v5, 0xc0, v5
	v_add_u32_e32 v4, v6, v4
	v_sub_u32_e32 v3, v3, v5
	v_mov_b32_e32 v5, 1
	v_lshlrev_b32_e32 v2, 5, v2
	v_ashrrev_i16_sdwa v3, v5, sext(v3) dst_sel:DWORD dst_unused:UNUSED_PAD src0_sel:DWORD src1_sel:BYTE_0
	v_lshlrev_b32_e32 v7, 1, v4
	v_lshrrev_b32_e32 v8, 2, v4
	v_and_b32_e32 v6, 3, v6
	s_mov_b32 s3, 0x1fffe0
	v_and_b32_e32 v2, 32, v2
	v_bfe_i32 v3, v3, 0, 16
	v_and_b32_e32 v7, 24, v7
	v_and_b32_e32 v8, 4, v8
	v_and_or_b32 v6, v4, s3, v6
	v_or3_b32 v6, v6, v8, v7
	v_add_lshl_u32 v2, v2, v3, 1
	v_add_u32_e32 v1, 0x2000, v1
	v_lshl_add_u32 v132, v4, 11, v2
	v_lshl_add_u32 v133, v6, 11, v2
	v_ashrrev_i32_e32 v2, 31, v1
	v_lshrrev_b32_e32 v2, 22, v2
	v_add_u32_e32 v2, v1, v2
	v_ashrrev_i32_e32 v2, 10, v2
	v_mul_i32_i24_e32 v3, 0x400, v2
	v_sub_u32_e32 v1, v1, v3
	v_lshrrev_b32_e32 v3, 4, v1
	v_bitop3_b32 v1, v3, v1, 32 bitop3:0x6c
	v_ashrrev_i32_e32 v4, 31, v1
	v_lshrrev_b32_e32 v4, 26, v4
	s_add_i32 s0, s2, s0
	v_lshlrev_b32_e32 v3, 3, v2
	v_add_u32_e32 v4, v1, v4
	s_ashr_i32 s2, s0, 31
	v_and_b32_e32 v3, -16, v3
	v_ashrrev_i32_e32 v6, 6, v4
	s_lshr_b32 s2, s2, 27
	v_add_u32_e32 v3, v6, v3
	v_and_b32_e32 v6, 3, v6
	s_add_i32 s2, s0, s2
	v_and_or_b32 v6, v3, s3, v6
	s_ashr_i32 s3, s2, 5
	s_andn2_b32 s2, s2, 31
	s_sub_i32 s2, s0, s2
	s_bfe_i32 s0, s2, 0x80000
	s_bfe_u32 s0, s0, 0x3000c
	s_add_i32 s6, s2, s0
	s_bfe_i32 s0, s6, 0x80000
	s_and_b32 s6, s6, 0xf8
	v_and_b32_e32 v4, 0xffc0, v4
	s_sub_i32 s2, s2, s6
	v_sub_u32_e32 v1, v1, v4
	s_lshl_b32 s3, s3, 3
	s_sext_i32_i16 s0, s0
	s_sext_i32_i8 s2, s2
	v_lshrrev_b16_e32 v4, 7, v1
	s_lshr_b32 s0, s0, 3
	s_add_i32 s6, s3, s2
	v_and_b32_e32 v4, 1, v4
	s_ashr_i32 s7, s6, 31
	s_bfe_i64 s[10:11], s[0:1], 0x100000
	v_add_u16_e32 v1, v1, v4
	s_lshr_b32 s9, s91, 8
	s_lshl_b64 s[2:3], s[6:7], 19
	s_lshl_b64 s[10:11], s[10:11], 19
	v_lshlrev_b32_e32 v2, 5, v2
	v_ashrrev_i16_sdwa v1, v5, sext(v1) dst_sel:DWORD dst_unused:UNUSED_PAD src0_sel:DWORD src1_sel:BYTE_0
	v_lshlrev_b32_e32 v4, 1, v3
	v_lshrrev_b32_e32 v5, 2, v3
	s_add_u32 s10, s34, s10
	v_and_b32_e32 v2, 32, v2
	v_bfe_i32 v1, v1, 0, 16
	v_and_b32_e32 v4, 24, v4
	v_and_b32_e32 v5, 4, v5
	s_addc_u32 s11, s35, s11
	s_add_i32 s36, s1, 0
	v_or3_b32 v4, v6, v5, v4
	v_add_lshl_u32 v1, v2, v1, 1
	s_add_i32 s37, s36, 0x10000
	s_mov_b32 m0, s37
	s_nop 0
	global_load_lds_dwordx4 v133, s[10:11]
	s_add_i32 s38, s36, 0x12000
	v_lshl_add_u32 v135, v4, 11, v1
	s_mov_b32 m0, s38
	s_nop 0
	global_load_lds_dwordx4 v135, s[10:11]
	s_add_u32 s12, s10, 0x40000
	s_addc_u32 s13, s11, 0
	s_add_i32 s40, s36, 0x14000
	s_mov_b32 m0, s40
	s_nop 0
	global_load_lds_dwordx4 v133, s[12:13]
	s_add_i32 s41, s36, 0x16000
	s_mov_b32 m0, s41
	s_nop 0
	global_load_lds_dwordx4 v135, s[12:13]
	s_add_u32 s12, s31, s2
	s_addc_u32 s13, s33, s3
	s_mov_b32 m0, s36
	s_nop 0
	global_load_lds_dwordx4 v132, s[12:13]
	s_add_i32 s42, s36, 0x2000
	v_lshl_add_u32 v134, v3, 11, v1
	s_mov_b32 m0, s42
	s_nop 0
	global_load_lds_dwordx4 v134, s[12:13]
	s_add_u32 s2, s12, 0x40000
	s_addc_u32 s3, s13, 0
	s_add_i32 s43, s36, 0x4000
	s_mov_b32 m0, s43
	s_nop 0
	global_load_lds_dwordx4 v132, s[2:3]
	s_add_i32 s44, s36, 0x6000
	s_mov_b32 m0, s44
	s_nop 0
	global_load_lds_dwordx4 v134, s[2:3]
	s_mov_b32 s39, 0
	s_cmp_lg_u32 s9, 1
	s_cbranch_scc1 .LBB0_750
	s_barrier
.LBB0_750:
	s_bfe_u32 s7, s91, 0x20006
	s_sext_i32_i8 s8, s0
	s_add_u32 s0, s10, 0x80
	s_waitcnt vmcnt(2)
	s_barrier
	s_addc_u32 s1, s11, 0
	s_add_i32 s45, s36, 0x18000
	s_mov_b32 m0, s45
	s_nop 0
	global_load_lds_dwordx4 v133, s[0:1]
	s_add_i32 s46, s36, 0x1a000
	s_mov_b32 m0, s46
	s_nop 0
	global_load_lds_dwordx4 v135, s[0:1]
	s_add_u32 s0, s12, 0x80
	s_addc_u32 s1, s13, 0
	s_add_i32 s47, s36, 0x8000
	s_mov_b32 m0, s47
	s_nop 0
	global_load_lds_dwordx4 v132, s[0:1]
	s_add_i32 s48, s36, 0xa000
	s_mov_b32 m0, s48
	s_nop 0
	global_load_lds_dwordx4 v134, s[0:1]
	s_add_u32 s0, s10, 0x40080
	v_and_b32_e32 v1, 15, v196
	v_and_b32_e32 v2, 48, v196
	s_addc_u32 s1, s11, 0
	s_add_i32 s49, s36, 0x1c000
	s_mov_b32 m0, s49
	s_nop 0
	global_load_lds_dwordx4 v133, s[0:1]
	v_lshl_or_b32 v195, s9, 6, v1
	v_and_b32_e32 v0, 0xfffffc00, v0
	v_lshl_or_b32 v1, v1, 6, v2
	v_lshlrev_b32_e32 v2, 2, v196
	s_add_i32 s52, s36, 0x1e000
	s_mov_b32 m0, s52
	s_nop 0
	global_load_lds_dwordx4 v135, s[0:1]
	v_lshl_add_u32 v3, s9, 13, v0
	v_and_b32_e32 v2, 32, v2
	v_lshl_add_u32 v0, s7, 12, v0
	s_waitcnt vmcnt(6)
	v_bitop3_b32 v3, v1, v3, v2 bitop3:0xde
	v_bitop3_b32 v1, v1, v0, v2 bitop3:0xde
	v_mov_b32_e32 v0, 0
	s_add_i32 s53, s36, 0xc000
	s_add_i32 s54, s36, 0xe000
	v_mov_b64_e32 v[128:129], 0x100
	s_waitcnt lgkmcnt(0)
	v_mov_b64_e32 v[130:131], 0xff
	v_add_u32_e32 v136, 0, v1
	v_add_u32_e32 v137, 0, v3
	v_mov_b32_e32 v1, v0
	v_mov_b32_e32 v2, v0
	v_mov_b32_e32 v3, v0
	v_mov_b32_e32 v4, v0
	v_mov_b32_e32 v5, v0
	v_mov_b32_e32 v6, v0
	v_mov_b32_e32 v7, v0
	v_mov_b32_e32 v16, v0
	v_mov_b32_e32 v17, v0
	v_mov_b32_e32 v18, v0
	v_mov_b32_e32 v19, v0
	v_mov_b32_e32 v20, v0
	v_mov_b32_e32 v21, v0
	v_mov_b32_e32 v22, v0
	v_mov_b32_e32 v23, v0
	v_mov_b32_e32 v32, v0
	v_mov_b32_e32 v33, v0
	v_mov_b32_e32 v34, v0
	v_mov_b32_e32 v35, v0
	v_mov_b32_e32 v36, v0
	v_mov_b32_e32 v37, v0
	v_mov_b32_e32 v38, v0
	v_mov_b32_e32 v39, v0
	v_mov_b32_e32 v48, v0
	v_mov_b32_e32 v49, v0
	v_mov_b32_e32 v50, v0
	v_mov_b32_e32 v51, v0
	v_mov_b32_e32 v52, v0
	v_mov_b32_e32 v53, v0
	v_mov_b32_e32 v54, v0
	v_mov_b32_e32 v55, v0
	v_mov_b32_e32 v8, v0
	v_mov_b32_e32 v9, v0
	v_mov_b32_e32 v10, v0
	v_mov_b32_e32 v11, v0
	v_mov_b32_e32 v12, v0
	v_mov_b32_e32 v13, v0
	v_mov_b32_e32 v14, v0
	v_mov_b32_e32 v15, v0
	v_mov_b32_e32 v24, v0
	v_mov_b32_e32 v25, v0
	v_mov_b32_e32 v26, v0
	v_mov_b32_e32 v27, v0
	v_mov_b32_e32 v28, v0
	v_mov_b32_e32 v29, v0
	v_mov_b32_e32 v30, v0
	v_mov_b32_e32 v31, v0
	v_mov_b32_e32 v40, v0
	v_mov_b32_e32 v41, v0
	v_mov_b32_e32 v42, v0
	v_mov_b32_e32 v43, v0
	v_mov_b32_e32 v44, v0
	v_mov_b32_e32 v45, v0
	v_mov_b32_e32 v46, v0
	v_mov_b32_e32 v47, v0
	v_mov_b32_e32 v56, v0
	v_mov_b32_e32 v57, v0
	v_mov_b32_e32 v58, v0
	v_mov_b32_e32 v59, v0
	v_mov_b32_e32 v60, v0
	v_mov_b32_e32 v61, v0
	v_mov_b32_e32 v62, v0
	v_mov_b32_e32 v63, v0
	v_mov_b32_e32 v64, v0
	v_mov_b32_e32 v65, v0
	v_mov_b32_e32 v66, v0
	v_mov_b32_e32 v67, v0
	v_mov_b32_e32 v68, v0
	v_mov_b32_e32 v69, v0
	v_mov_b32_e32 v70, v0
	v_mov_b32_e32 v71, v0
	v_mov_b32_e32 v80, v0
	v_mov_b32_e32 v81, v0
	v_mov_b32_e32 v82, v0
	v_mov_b32_e32 v83, v0
	v_mov_b32_e32 v84, v0
	v_mov_b32_e32 v85, v0
	v_mov_b32_e32 v86, v0
	v_mov_b32_e32 v87, v0
	v_mov_b32_e32 v96, v0
	v_mov_b32_e32 v97, v0
	v_mov_b32_e32 v98, v0
	v_mov_b32_e32 v99, v0
	v_mov_b32_e32 v100, v0
	v_mov_b32_e32 v101, v0
	v_mov_b32_e32 v102, v0
	v_mov_b32_e32 v103, v0
	v_mov_b32_e32 v112, v0
	v_mov_b32_e32 v113, v0
	v_mov_b32_e32 v114, v0
	v_mov_b32_e32 v115, v0
	v_mov_b32_e32 v116, v0
	v_mov_b32_e32 v117, v0
	v_mov_b32_e32 v118, v0
	v_mov_b32_e32 v119, v0
	v_mov_b32_e32 v72, v0
	v_mov_b32_e32 v73, v0
	v_mov_b32_e32 v74, v0
	v_mov_b32_e32 v75, v0
	v_mov_b32_e32 v76, v0
	v_mov_b32_e32 v77, v0
	v_mov_b32_e32 v78, v0
	v_mov_b32_e32 v79, v0
	v_mov_b32_e32 v88, v0
	v_mov_b32_e32 v89, v0
	v_mov_b32_e32 v90, v0
	v_mov_b32_e32 v91, v0
	v_mov_b32_e32 v92, v0
	v_mov_b32_e32 v93, v0
	v_mov_b32_e32 v94, v0
	v_mov_b32_e32 v95, v0
	v_mov_b32_e32 v104, v0
	v_mov_b32_e32 v105, v0
	v_mov_b32_e32 v106, v0
	v_mov_b32_e32 v107, v0
	v_mov_b32_e32 v108, v0
	v_mov_b32_e32 v109, v0
	v_mov_b32_e32 v110, v0
	v_mov_b32_e32 v111, v0
	v_mov_b32_e32 v120, v0
	v_mov_b32_e32 v121, v0
	v_mov_b32_e32 v122, v0
	v_mov_b32_e32 v123, v0
	v_mov_b32_e32 v124, v0
	v_mov_b32_e32 v125, v0
	v_mov_b32_e32 v126, v0
	v_mov_b32_e32 v127, v0
	s_barrier
	s_branch .LBB0_752

.LBB0_759:
	s_add_u32 s59, s12, s22
	s_addc_u32 s61, s13, s23
	s_add_u32 s24, s59, 0x100
	s_addc_u32 s25, s61, 0
	v_add_u32_e32 v150, 0x10000, v136
	v_add_u32_e32 v166, 0x14000, v136
	s_add_u32 s26, s10, s22
	ds_read_b128 v[138:141], v150
	ds_read_b128 v[142:145], v150 offset:1024
	ds_read_b128 v[146:149], v150 offset:2048
	ds_read_b128 v[150:153], v150 offset:3072
	ds_read_b128 v[154:157], v166
	ds_read_b128 v[158:161], v166 offset:1024
	ds_read_b128 v[162:165], v166 offset:2048
	ds_read_b128 v[166:169], v166 offset:3072
	s_addc_u32 s27, s11, s23
	s_add_u32 s26, s26, 0x100
	s_addc_u32 s27, s27, 0
	s_cmp_eq_u32 s58, 12
	s_cselect_b32 s28, s56, s24
	s_cselect_b32 s29, s17, s25
	s_cselect_b32 s26, s57, s26
	s_cselect_b32 s27, s15, s27
	s_add_u32 s24, s28, 0x80
	s_addc_u32 s25, s29, 0
	ds_read_b128 v[170:173], v137
	ds_read_b128 v[174:177], v137 offset:1024
	ds_read_b128 v[178:181], v137 offset:2048
	ds_read_b128 v[182:185], v137 offset:3072
	ds_read_b128 v[186:189], v137 offset:4096
	ds_read_b128 v[190:193], v137 offset:5120
	ds_read_b128 v[198:201], v137 offset:6144
	ds_read_b128 v[202:205], v137 offset:7168
	s_add_u32 s60, s59, 0x40080
	s_addc_u32 s61, s61, 0
	s_mov_b32 m0, s53
	s_nop 0
	global_load_lds_dwordx4 v132, s[60:61]
	s_nop 0
	s_mov_b32 m0, s54
	s_nop 0
	global_load_lds_dwordx4 v134, s[60:61]
	s_waitcnt vmcnt(8)
	s_waitcnt lgkmcnt(0)
	s_barrier
	s_setprio 1
	s_waitcnt lgkmcnt(7)
	v_mfma_f32_16x16x32_bf16 v[124:127], v[138:141], v[170:173], v[124:127]
	v_mfma_f32_16x16x32_bf16 v[120:123], v[146:149], v[170:173], v[120:123]
	s_waitcnt lgkmcnt(5)
	v_mfma_f32_16x16x32_bf16 v[108:111], v[138:141], v[178:181], v[108:111]
	v_mfma_f32_16x16x32_bf16 v[104:107], v[146:149], v[178:181], v[104:107]
	s_waitcnt lgkmcnt(3)
	v_mfma_f32_16x16x32_bf16 v[92:95], v[138:141], v[186:189], v[92:95]
	v_mfma_f32_16x16x32_bf16 v[88:91], v[146:149], v[186:189], v[88:91]
	s_waitcnt lgkmcnt(1)
	v_mfma_f32_16x16x32_bf16 v[76:79], v[138:141], v[198:201], v[76:79]
	v_mfma_f32_16x16x32_bf16 v[72:75], v[146:149], v[198:201], v[72:75]
	v_mfma_f32_16x16x32_bf16 v[124:127], v[142:145], v[174:177], v[124:127]
	v_mfma_f32_16x16x32_bf16 v[120:123], v[150:153], v[174:177], v[120:123]
	v_mfma_f32_16x16x32_bf16 v[108:111], v[142:145], v[182:185], v[108:111]
	v_mfma_f32_16x16x32_bf16 v[104:107], v[150:153], v[182:185], v[104:107]
	v_mfma_f32_16x16x32_bf16 v[92:95], v[142:145], v[190:193], v[92:95]
	v_mfma_f32_16x16x32_bf16 v[88:91], v[150:153], v[190:193], v[88:91]
	s_waitcnt lgkmcnt(0)
	v_mfma_f32_16x16x32_bf16 v[76:79], v[142:145], v[202:205], v[76:79]
	v_mfma_f32_16x16x32_bf16 v[72:75], v[150:153], v[202:205], v[72:75]
	s_setprio 0
	s_setprio 1
	v_mfma_f32_16x16x32_bf16 v[116:119], v[154:157], v[170:173], v[116:119]
	v_mfma_f32_16x16x32_bf16 v[112:115], v[162:165], v[170:173], v[112:115]
	v_mfma_f32_16x16x32_bf16 v[100:103], v[154:157], v[178:181], v[100:103]
	v_mfma_f32_16x16x32_bf16 v[96:99], v[162:165], v[178:181], v[96:99]
	v_mfma_f32_16x16x32_bf16 v[84:87], v[154:157], v[186:189], v[84:87]
	v_mfma_f32_16x16x32_bf16 v[80:83], v[162:165], v[186:189], v[80:83]
	v_mfma_f32_16x16x32_bf16 v[68:71], v[154:157], v[198:201], v[68:71]
	v_mfma_f32_16x16x32_bf16 v[64:67], v[162:165], v[198:201], v[64:67]
	v_mfma_f32_16x16x32_bf16 v[116:119], v[158:161], v[174:177], v[116:119]
	v_mfma_f32_16x16x32_bf16 v[112:115], v[166:169], v[174:177], v[112:115]
	v_mfma_f32_16x16x32_bf16 v[100:103], v[158:161], v[182:185], v[100:103]
	v_mfma_f32_16x16x32_bf16 v[96:99], v[166:169], v[182:185], v[96:99]
	v_mfma_f32_16x16x32_bf16 v[84:87], v[158:161], v[190:193], v[84:87]
	v_mfma_f32_16x16x32_bf16 v[80:83], v[166:169], v[190:193], v[80:83]
	v_mfma_f32_16x16x32_bf16 v[68:71], v[158:161], v[202:205], v[68:71]
	v_mfma_f32_16x16x32_bf16 v[64:67], v[166:169], v[202:205], v[64:67]
	s_setprio 0
	s_barrier
	ds_read_b128 v[170:173], v137 offset:16384
	ds_read_b128 v[174:177], v137 offset:17408
	ds_read_b128 v[178:181], v137 offset:18432
	ds_read_b128 v[182:185], v137 offset:19456
	ds_read_b128 v[186:189], v137 offset:20480
	ds_read_b128 v[190:193], v137 offset:21504
	ds_read_b128 v[198:201], v137 offset:22528
	ds_read_b128 v[202:205], v137 offset:23552
	s_mov_b32 m0, s37
	s_nop 0
	global_load_lds_dwordx4 v133, s[26:27]
	s_add_u32 s60, s26, 0x40000
	s_mov_b32 m0, s38
	s_nop 0
	global_load_lds_dwordx4 v135, s[26:27]
	s_addc_u32 s61, s27, 0
	s_mov_b32 m0, s40
	s_nop 0
	global_load_lds_dwordx4 v133, s[60:61]
	s_nop 0
	s_mov_b32 m0, s41
	s_nop 0
	global_load_lds_dwordx4 v135, s[60:61]
	s_nop 0
	s_mov_b32 m0, s36
	s_nop 0
	global_load_lds_dwordx4 v132, s[28:29]
	s_nop 0
	s_mov_b32 m0, s42
	s_nop 0
	global_load_lds_dwordx4 v134, s[28:29]
	s_waitcnt vmcnt(8)
	s_waitcnt lgkmcnt(0)
	s_barrier
	s_setprio 1
	s_waitcnt lgkmcnt(7)
	v_mfma_f32_16x16x32_bf16 v[60:63], v[138:141], v[170:173], v[60:63]
	v_mfma_f32_16x16x32_bf16 v[56:59], v[146:149], v[170:173], v[56:59]
	s_waitcnt lgkmcnt(5)
	v_mfma_f32_16x16x32_bf16 v[44:47], v[138:141], v[178:181], v[44:47]
	v_mfma_f32_16x16x32_bf16 v[40:43], v[146:149], v[178:181], v[40:43]
	s_waitcnt lgkmcnt(3)
	v_mfma_f32_16x16x32_bf16 v[28:31], v[138:141], v[186:189], v[28:31]
	v_mfma_f32_16x16x32_bf16 v[24:27], v[146:149], v[186:189], v[24:27]
	s_waitcnt lgkmcnt(1)
	v_mfma_f32_16x16x32_bf16 v[12:15], v[138:141], v[198:201], v[12:15]
	v_mfma_f32_16x16x32_bf16 v[8:11], v[146:149], v[198:201], v[8:11]
	v_mfma_f32_16x16x32_bf16 v[60:63], v[142:145], v[174:177], v[60:63]
	v_mfma_f32_16x16x32_bf16 v[56:59], v[150:153], v[174:177], v[56:59]
	v_mfma_f32_16x16x32_bf16 v[44:47], v[142:145], v[182:185], v[44:47]
	v_mfma_f32_16x16x32_bf16 v[40:43], v[150:153], v[182:185], v[40:43]
	v_mfma_f32_16x16x32_bf16 v[28:31], v[142:145], v[190:193], v[28:31]
	v_mfma_f32_16x16x32_bf16 v[24:27], v[150:153], v[190:193], v[24:27]
	s_waitcnt lgkmcnt(0)
	v_mfma_f32_16x16x32_bf16 v[12:15], v[142:145], v[202:205], v[12:15]
	v_mfma_f32_16x16x32_bf16 v[8:11], v[150:153], v[202:205], v[8:11]
	s_setprio 0
	s_setprio 1
	v_mfma_f32_16x16x32_bf16 v[52:55], v[154:157], v[170:173], v[52:55]
	v_mfma_f32_16x16x32_bf16 v[48:51], v[162:165], v[170:173], v[48:51]
	v_mfma_f32_16x16x32_bf16 v[36:39], v[154:157], v[178:181], v[36:39]
	v_mfma_f32_16x16x32_bf16 v[32:35], v[162:165], v[178:181], v[32:35]
	v_mfma_f32_16x16x32_bf16 v[20:23], v[154:157], v[186:189], v[20:23]
	v_mfma_f32_16x16x32_bf16 v[16:19], v[162:165], v[186:189], v[16:19]
	v_mfma_f32_16x16x32_bf16 v[4:7], v[154:157], v[198:201], v[4:7]
	v_mfma_f32_16x16x32_bf16 v[0:3], v[162:165], v[198:201], v[0:3]
	v_mfma_f32_16x16x32_bf16 v[52:55], v[158:161], v[174:177], v[52:55]
	v_mfma_f32_16x16x32_bf16 v[48:51], v[166:169], v[174:177], v[48:51]
	v_mfma_f32_16x16x32_bf16 v[36:39], v[158:161], v[182:185], v[36:39]
	v_mfma_f32_16x16x32_bf16 v[32:35], v[166:169], v[182:185], v[32:35]
	v_mfma_f32_16x16x32_bf16 v[20:23], v[158:161], v[190:193], v[20:23]
	v_mfma_f32_16x16x32_bf16 v[16:19], v[166:169], v[190:193], v[16:19]
	v_mfma_f32_16x16x32_bf16 v[4:7], v[158:161], v[202:205], v[4:7]
	v_mfma_f32_16x16x32_bf16 v[0:3], v[166:169], v[202:205], v[0:3]
	s_setprio 0
	s_barrier
	v_add_u32_e32 v150, 0x18000, v136
	v_add_u32_e32 v166, 0x1c000, v136
	ds_read_b128 v[138:141], v150
	ds_read_b128 v[142:145], v150 offset:1024
	ds_read_b128 v[146:149], v150 offset:2048
	ds_read_b128 v[150:153], v150 offset:3072
	ds_read_b128 v[154:157], v166
	ds_read_b128 v[158:161], v166 offset:1024
	ds_read_b128 v[162:165], v166 offset:2048
	ds_read_b128 v[166:169], v166 offset:3072
	ds_read_b128 v[170:173], v137 offset:32768
	ds_read_b128 v[174:177], v137 offset:33792
	ds_read_b128 v[178:181], v137 offset:34816
	ds_read_b128 v[182:185], v137 offset:35840
	ds_read_b128 v[186:189], v137 offset:36864
	ds_read_b128 v[190:193], v137 offset:37888
	ds_read_b128 v[198:201], v137 offset:38912
	ds_read_b128 v[202:205], v137 offset:39936
	s_add_u32 s28, s28, 0x40000
	s_addc_u32 s29, s29, 0
	s_mov_b32 m0, s43
	s_nop 0
	global_load_lds_dwordx4 v132, s[28:29]
	s_nop 0
	s_mov_b32 m0, s44
	s_nop 0
	global_load_lds_dwordx4 v134, s[28:29]
	s_waitcnt vmcnt(8)
	s_waitcnt lgkmcnt(0)
	s_barrier
	s_setprio 1
	s_waitcnt lgkmcnt(7)
	v_mfma_f32_16x16x32_bf16 v[124:127], v[138:141], v[170:173], v[124:127]
	v_mfma_f32_16x16x32_bf16 v[120:123], v[146:149], v[170:173], v[120:123]
	s_waitcnt lgkmcnt(5)
	v_mfma_f32_16x16x32_bf16 v[108:111], v[138:141], v[178:181], v[108:111]
	v_mfma_f32_16x16x32_bf16 v[104:107], v[146:149], v[178:181], v[104:107]
	s_waitcnt lgkmcnt(3)
	v_mfma_f32_16x16x32_bf16 v[92:95], v[138:141], v[186:189], v[92:95]
	v_mfma_f32_16x16x32_bf16 v[88:91], v[146:149], v[186:189], v[88:91]
	s_waitcnt lgkmcnt(1)
	v_mfma_f32_16x16x32_bf16 v[76:79], v[138:141], v[198:201], v[76:79]
	v_mfma_f32_16x16x32_bf16 v[72:75], v[146:149], v[198:201], v[72:75]
	v_mfma_f32_16x16x32_bf16 v[124:127], v[142:145], v[174:177], v[124:127]
	v_mfma_f32_16x16x32_bf16 v[120:123], v[150:153], v[174:177], v[120:123]
	v_mfma_f32_16x16x32_bf16 v[108:111], v[142:145], v[182:185], v[108:111]
	v_mfma_f32_16x16x32_bf16 v[104:107], v[150:153], v[182:185], v[104:107]
	v_mfma_f32_16x16x32_bf16 v[92:95], v[142:145], v[190:193], v[92:95]
	v_mfma_f32_16x16x32_bf16 v[88:91], v[150:153], v[190:193], v[88:91]
	s_waitcnt lgkmcnt(0)
	v_mfma_f32_16x16x32_bf16 v[76:79], v[142:145], v[202:205], v[76:79]
	v_mfma_f32_16x16x32_bf16 v[72:75], v[150:153], v[202:205], v[72:75]
	s_setprio 0
	s_setprio 1
	v_mfma_f32_16x16x32_bf16 v[116:119], v[154:157], v[170:173], v[116:119]
	v_mfma_f32_16x16x32_bf16 v[112:115], v[162:165], v[170:173], v[112:115]
	v_mfma_f32_16x16x32_bf16 v[100:103], v[154:157], v[178:181], v[100:103]
	v_mfma_f32_16x16x32_bf16 v[96:99], v[162:165], v[178:181], v[96:99]
	v_mfma_f32_16x16x32_bf16 v[84:87], v[154:157], v[186:189], v[84:87]
	v_mfma_f32_16x16x32_bf16 v[80:83], v[162:165], v[186:189], v[80:83]
	v_mfma_f32_16x16x32_bf16 v[68:71], v[154:157], v[198:201], v[68:71]
	v_mfma_f32_16x16x32_bf16 v[64:67], v[162:165], v[198:201], v[64:67]
	v_mfma_f32_16x16x32_bf16 v[116:119], v[158:161], v[174:177], v[116:119]
	v_mfma_f32_16x16x32_bf16 v[112:115], v[166:169], v[174:177], v[112:115]
	v_mfma_f32_16x16x32_bf16 v[100:103], v[158:161], v[182:185], v[100:103]
	v_mfma_f32_16x16x32_bf16 v[96:99], v[166:169], v[182:185], v[96:99]
	v_mfma_f32_16x16x32_bf16 v[84:87], v[158:161], v[190:193], v[84:87]
	v_mfma_f32_16x16x32_bf16 v[80:83], v[166:169], v[190:193], v[80:83]
	v_mfma_f32_16x16x32_bf16 v[68:71], v[158:161], v[202:205], v[68:71]
	v_mfma_f32_16x16x32_bf16 v[64:67], v[166:169], v[202:205], v[64:67]
	s_setprio 0
	s_barrier
	ds_read_b128 v[170:173], v137 offset:49152
	ds_read_b128 v[174:177], v137 offset:50176
	ds_read_b128 v[178:181], v137 offset:51200
	ds_read_b128 v[182:185], v137 offset:52224
	ds_read_b128 v[186:189], v137 offset:53248
	ds_read_b128 v[190:193], v137 offset:54272
	ds_read_b128 v[198:201], v137 offset:55296
	ds_read_b128 v[202:205], v137 offset:56320
	s_add_u32 s28, s26, 0x80
	s_addc_u32 s29, s27, 0
	s_mov_b32 m0, s45
	s_nop 0
	global_load_lds_dwordx4 v133, s[28:29]
	s_add_u32 s26, s26, 0x40080
	s_mov_b32 m0, s46
	s_nop 0
	global_load_lds_dwordx4 v135, s[28:29]
	s_addc_u32 s27, s27, 0
	s_mov_b32 m0, s49
	s_nop 0
	global_load_lds_dwordx4 v133, s[26:27]
	s_nop 0
	s_mov_b32 m0, s52
	s_nop 0
	global_load_lds_dwordx4 v135, s[26:27]
	s_mov_b32 m0, s47
	s_nop 0
	global_load_lds_dwordx4 v132, s[24:25]
	s_nop 0
	s_mov_b32 m0, s48
	s_nop 0
	global_load_lds_dwordx4 v134, s[24:25]
	s_waitcnt vmcnt(8)
	s_waitcnt lgkmcnt(0)
	s_barrier
	s_setprio 1
	s_waitcnt lgkmcnt(7)
	v_mfma_f32_16x16x32_bf16 v[60:63], v[138:141], v[170:173], v[60:63]
	v_mfma_f32_16x16x32_bf16 v[56:59], v[146:149], v[170:173], v[56:59]
	s_waitcnt lgkmcnt(5)
	v_mfma_f32_16x16x32_bf16 v[44:47], v[138:141], v[178:181], v[44:47]
	v_mfma_f32_16x16x32_bf16 v[40:43], v[146:149], v[178:181], v[40:43]
	s_waitcnt lgkmcnt(3)
	v_mfma_f32_16x16x32_bf16 v[28:31], v[138:141], v[186:189], v[28:31]
	v_mfma_f32_16x16x32_bf16 v[24:27], v[146:149], v[186:189], v[24:27]
	s_waitcnt lgkmcnt(1)
	v_mfma_f32_16x16x32_bf16 v[12:15], v[138:141], v[198:201], v[12:15]
	v_mfma_f32_16x16x32_bf16 v[8:11], v[146:149], v[198:201], v[8:11]
	v_mfma_f32_16x16x32_bf16 v[60:63], v[142:145], v[174:177], v[60:63]
	v_mfma_f32_16x16x32_bf16 v[56:59], v[150:153], v[174:177], v[56:59]
	v_mfma_f32_16x16x32_bf16 v[44:47], v[142:145], v[182:185], v[44:47]
	v_mfma_f32_16x16x32_bf16 v[40:43], v[150:153], v[182:185], v[40:43]
	v_mfma_f32_16x16x32_bf16 v[28:31], v[142:145], v[190:193], v[28:31]
	v_mfma_f32_16x16x32_bf16 v[24:27], v[150:153], v[190:193], v[24:27]
	s_waitcnt lgkmcnt(0)
	v_mfma_f32_16x16x32_bf16 v[12:15], v[142:145], v[202:205], v[12:15]
	v_mfma_f32_16x16x32_bf16 v[8:11], v[150:153], v[202:205], v[8:11]
	s_setprio 0
	s_setprio 1
	v_mfma_f32_16x16x32_bf16 v[52:55], v[154:157], v[170:173], v[52:55]
	v_mfma_f32_16x16x32_bf16 v[48:51], v[162:165], v[170:173], v[48:51]
	v_mfma_f32_16x16x32_bf16 v[36:39], v[154:157], v[178:181], v[36:39]
	v_mfma_f32_16x16x32_bf16 v[32:35], v[162:165], v[178:181], v[32:35]
	v_mfma_f32_16x16x32_bf16 v[20:23], v[154:157], v[186:189], v[20:23]
	v_mfma_f32_16x16x32_bf16 v[16:19], v[162:165], v[186:189], v[16:19]
	v_mfma_f32_16x16x32_bf16 v[4:7], v[154:157], v[198:201], v[4:7]
	v_mfma_f32_16x16x32_bf16 v[0:3], v[162:165], v[198:201], v[0:3]
	v_mfma_f32_16x16x32_bf16 v[52:55], v[158:161], v[174:177], v[52:55]
	v_mfma_f32_16x16x32_bf16 v[48:51], v[166:169], v[174:177], v[48:51]
	v_mfma_f32_16x16x32_bf16 v[36:39], v[158:161], v[182:185], v[36:39]
	v_mfma_f32_16x16x32_bf16 v[32:35], v[166:169], v[182:185], v[32:35]
	v_mfma_f32_16x16x32_bf16 v[20:23], v[158:161], v[190:193], v[20:23]
	v_mfma_f32_16x16x32_bf16 v[16:19], v[166:169], v[190:193], v[16:19]
	v_mfma_f32_16x16x32_bf16 v[4:7], v[158:161], v[202:205], v[4:7]
	v_mfma_f32_16x16x32_bf16 v[0:3], v[166:169], v[202:205], v[0:3]
	s_setprio 0
	s_barrier
	s_add_i32 s58, s58, 2
	s_add_u32 s22, s22, 0x100
	s_addc_u32 s23, s23, 0
	s_cmp_gt_u32 s58, 13
	s_cbranch_scc0 .LBB0_759
	s_andn2_b64 vcc, exec, s[2:3]
	s_cbranch_vccnz .LBB0_751
	v_mov_b32_e32 v0, 0
	s_mov_b32 s8, s14
	s_mov_b32 s6, s16
	s_mov_b64 s[10:11], s[20:21]
	s_mov_b64 s[12:13], s[18:19]
	s_mov_b32 s39, s55
	v_mov_b32_e32 v1, v0
	v_mov_b32_e32 v2, v0
	v_mov_b32_e32 v3, v0
	v_mov_b32_e32 v4, v0
	v_mov_b32_e32 v5, v0
	v_mov_b32_e32 v6, v0
	v_mov_b32_e32 v7, v0
	v_mov_b32_e32 v16, v0
	v_mov_b32_e32 v17, v0
	v_mov_b32_e32 v18, v0
	v_mov_b32_e32 v19, v0
	v_mov_b32_e32 v20, v0
	v_mov_b32_e32 v21, v0
	v_mov_b32_e32 v22, v0
	v_mov_b32_e32 v23, v0
	v_mov_b32_e32 v32, v0
	v_mov_b32_e32 v33, v0
	v_mov_b32_e32 v34, v0
	v_mov_b32_e32 v35, v0
	v_mov_b32_e32 v36, v0
	v_mov_b32_e32 v37, v0
	v_mov_b32_e32 v38, v0
	v_mov_b32_e32 v39, v0
	v_mov_b32_e32 v48, v0
	v_mov_b32_e32 v49, v0
	v_mov_b32_e32 v50, v0
	v_mov_b32_e32 v51, v0
	v_mov_b32_e32 v52, v0
	v_mov_b32_e32 v53, v0
	v_mov_b32_e32 v54, v0
	v_mov_b32_e32 v55, v0
	v_mov_b32_e32 v8, v0
	v_mov_b32_e32 v9, v0
	v_mov_b32_e32 v10, v0
	v_mov_b32_e32 v11, v0
	v_mov_b32_e32 v12, v0
	v_mov_b32_e32 v13, v0
	v_mov_b32_e32 v14, v0
	v_mov_b32_e32 v15, v0
	v_mov_b32_e32 v24, v0
	v_mov_b32_e32 v25, v0
	v_mov_b32_e32 v26, v0
	v_mov_b32_e32 v27, v0
	v_mov_b32_e32 v28, v0
	v_mov_b32_e32 v29, v0
	v_mov_b32_e32 v30, v0
	v_mov_b32_e32 v31, v0
	v_mov_b32_e32 v40, v0
	v_mov_b32_e32 v41, v0
	v_mov_b32_e32 v42, v0
	v_mov_b32_e32 v43, v0
	v_mov_b32_e32 v44, v0
	v_mov_b32_e32 v45, v0
	v_mov_b32_e32 v46, v0
	v_mov_b32_e32 v47, v0
	v_mov_b32_e32 v56, v0
	v_mov_b32_e32 v57, v0
	v_mov_b32_e32 v58, v0
	v_mov_b32_e32 v59, v0
	v_mov_b32_e32 v60, v0
	v_mov_b32_e32 v61, v0
	v_mov_b32_e32 v62, v0
	v_mov_b32_e32 v63, v0
	v_mov_b32_e32 v64, v0
	v_mov_b32_e32 v65, v0
	v_mov_b32_e32 v66, v0
	v_mov_b32_e32 v67, v0
	v_mov_b32_e32 v68, v0
	v_mov_b32_e32 v69, v0
	v_mov_b32_e32 v70, v0
	v_mov_b32_e32 v71, v0
	v_mov_b32_e32 v80, v0
	v_mov_b32_e32 v81, v0
	v_mov_b32_e32 v82, v0
	v_mov_b32_e32 v83, v0
	v_mov_b32_e32 v84, v0
	v_mov_b32_e32 v85, v0
	v_mov_b32_e32 v86, v0
	v_mov_b32_e32 v87, v0
	v_mov_b32_e32 v96, v0
	v_mov_b32_e32 v97, v0
	v_mov_b32_e32 v98, v0
	v_mov_b32_e32 v99, v0
	v_mov_b32_e32 v100, v0
	v_mov_b32_e32 v101, v0
	v_mov_b32_e32 v102, v0
	v_mov_b32_e32 v103, v0
	v_mov_b32_e32 v112, v0
	v_mov_b32_e32 v113, v0
	v_mov_b32_e32 v114, v0
	v_mov_b32_e32 v115, v0
	v_mov_b32_e32 v116, v0
	v_mov_b32_e32 v117, v0
	v_mov_b32_e32 v118, v0
	v_mov_b32_e32 v119, v0
	v_mov_b32_e32 v72, v0
	v_mov_b32_e32 v73, v0
	v_mov_b32_e32 v74, v0
	v_mov_b32_e32 v75, v0
	v_mov_b32_e32 v76, v0
	v_mov_b32_e32 v77, v0
	v_mov_b32_e32 v78, v0
	v_mov_b32_e32 v79, v0
	v_mov_b32_e32 v88, v0
	v_mov_b32_e32 v89, v0
	v_mov_b32_e32 v90, v0
	v_mov_b32_e32 v91, v0
	v_mov_b32_e32 v92, v0
	v_mov_b32_e32 v93, v0
	v_mov_b32_e32 v94, v0
	v_mov_b32_e32 v95, v0
	v_mov_b32_e32 v104, v0
	v_mov_b32_e32 v105, v0
	v_mov_b32_e32 v106, v0
	v_mov_b32_e32 v107, v0
	v_mov_b32_e32 v108, v0
	v_mov_b32_e32 v109, v0
	v_mov_b32_e32 v110, v0
	v_mov_b32_e32 v111, v0
	v_mov_b32_e32 v120, v0
	v_mov_b32_e32 v121, v0
	v_mov_b32_e32 v122, v0
	v_mov_b32_e32 v123, v0
	v_mov_b32_e32 v124, v0
	v_mov_b32_e32 v125, v0
	v_mov_b32_e32 v126, v0
	v_mov_b32_e32 v127, v0
	s_branch .LBB0_751

.LBB0_879:
	s_lshl_b32 s8, s90, 10
	v_lshl_add_u32 v1, v0, 4, s8
	v_ashrrev_i32_e32 v2, 31, v1
	v_lshrrev_b32_e32 v2, 22, v2
	v_add_u32_e32 v2, v1, v2
	v_ashrrev_i32_e32 v2, 10, v2
	v_mul_i32_i24_e32 v3, 0x400, v2
	v_sub_u32_e32 v3, v1, v3
	v_lshrrev_b32_e32 v4, 4, v3
	v_bitop3_b32 v3, v4, v3, 32 bitop3:0x6c
	v_ashrrev_i32_e32 v5, 31, v3
	v_lshrrev_b32_e32 v5, 26, v5
	v_lshlrev_b32_e32 v4, 3, v2
	v_add_u32_e32 v5, v3, v5
	v_and_b32_e32 v4, -16, v4
	v_ashrrev_i32_e32 v6, 6, v5
	v_and_b32_e32 v5, 0xc0, v5
	v_add_u32_e32 v4, v6, v4
	v_sub_u32_e32 v3, v3, v5
	v_mov_b32_e32 v5, 1
	v_lshlrev_b32_e32 v2, 5, v2
	v_ashrrev_i16_sdwa v3, v5, sext(v3) dst_sel:DWORD dst_unused:UNUSED_PAD src0_sel:DWORD src1_sel:BYTE_0
	v_lshlrev_b32_e32 v7, 1, v4
	v_lshrrev_b32_e32 v8, 2, v4
	v_and_b32_e32 v6, 3, v6
	s_mov_b32 s3, 0x1fffe0
	v_and_b32_e32 v2, 32, v2
	v_bfe_i32 v3, v3, 0, 16
	v_and_b32_e32 v7, 24, v7
	v_and_b32_e32 v8, 4, v8
	v_and_or_b32 v6, v4, s3, v6
	v_or3_b32 v6, v6, v8, v7
	v_add_lshl_u32 v2, v2, v3, 1
	v_add_u32_e32 v1, 0x2000, v1
	v_lshl_add_u32 v140, v4, 11, v2
	v_lshl_add_u32 v141, v6, 11, v2
	v_ashrrev_i32_e32 v2, 31, v1
	v_lshrrev_b32_e32 v2, 22, v2
	v_add_u32_e32 v2, v1, v2
	v_ashrrev_i32_e32 v2, 10, v2
	v_mul_i32_i24_e32 v3, 0x400, v2
	v_sub_u32_e32 v1, v1, v3
	v_lshrrev_b32_e32 v3, 4, v1
	v_bitop3_b32 v1, v3, v1, 32 bitop3:0x6c
	s_lshr_b32 s4, s91, 8
	v_ashrrev_i32_e32 v4, 31, v1
	v_lshrrev_b32_e32 v4, 26, v4
	s_add_u32 s42, s0, 0x1800000
	v_lshlrev_b32_e32 v3, 3, v2
	v_add_u32_e32 v4, v1, v4
	s_addc_u32 s43, s1, 0
	v_and_b32_e32 v3, -16, v3
	v_ashrrev_i32_e32 v6, 6, v4
	s_add_u32 s44, s0, 0xe00000
	v_add_u32_e32 v3, v6, v3
	v_and_b32_e32 v6, 3, v6
	s_addc_u32 s45, s1, 0
	s_add_i32 s2, s5, s2
	v_and_or_b32 v6, v3, s3, v6
	s_ashr_i32 s3, s2, 31
	v_and_b32_e32 v4, 0xffc0, v4
	s_lshr_b32 s3, s3, 26
	v_sub_u32_e32 v1, v1, v4
	s_add_i32 s3, s2, s3
	v_lshrrev_b16_e32 v4, 7, v1
	s_ashr_i32 s5, s3, 6
	v_and_b32_e32 v4, 1, v4
	s_lshl_b32 s5, s5, 3
	v_add_u16_e32 v1, v1, v4
	s_sub_i32 s6, 64, s5
	v_lshlrev_b32_e32 v2, 5, v2
	v_ashrrev_i16_sdwa v1, v5, sext(v1) dst_sel:DWORD dst_unused:UNUSED_PAD src0_sel:DWORD src1_sel:BYTE_0
	s_min_i32 s6, s6, 8
	v_and_b32_e32 v2, 32, v2
	v_bfe_i32 v1, v1, 0, 16
	s_abs_i32 s7, s6
	v_add_lshl_u32 v1, v2, v1, 1
	v_cvt_f32_u32_e32 v2, s7
	v_lshlrev_b32_e32 v4, 1, v3
	v_lshrrev_b32_e32 v5, 2, v3
	v_and_b32_e32 v4, 24, v4
	v_and_b32_e32 v5, 4, v5
	v_or3_b32 v4, v6, v5, v4
	v_lshl_add_u32 v142, v3, 11, v1
	v_lshl_add_u32 v143, v4, 11, v1
	v_rcp_iflag_f32_e32 v1, v2
	s_sub_i32 s10, 0, s7
	s_andn2_b32 s3, s3, 63
	s_sub_i32 s2, s2, s3
	v_mul_f32_e32 v1, 0x4f7ffffe, v1
	v_cvt_u32_f32_e32 v1, v1
	s_abs_i32 s9, s2
	s_xor_b32 s3, s2, s6
	s_ashr_i32 s3, s3, 31
	v_readfirstlane_b32 s11, v1
	s_mul_i32 s10, s10, s11
	s_mul_hi_u32 s10, s11, s10
	s_add_i32 s11, s11, s10
	s_mul_hi_u32 s10, s9, s11
	s_mul_i32 s11, s10, s7
	s_sub_i32 s9, s9, s11
	s_add_i32 s11, s10, 1
	s_sub_i32 s12, s9, s7
	s_cmp_ge_u32 s9, s7
	s_cselect_b32 s10, s11, s10
	s_cselect_b32 s9, s12, s9
	s_add_i32 s11, s10, 1
	s_cmp_ge_u32 s9, s7
	s_cselect_b32 s7, s11, s10
	s_xor_b32 s7, s7, s3
	s_sub_i32 s26, s7, s3
	s_mul_i32 s3, s26, s6
	s_sub_i32 s2, s2, s3
	s_add_i32 s28, s5, s2
	s_ashr_i32 s29, s28, 31
	s_ashr_i32 s27, s26, 31
	s_lshl_b64 s[2:3], s[28:29], 19
	s_lshl_b64 s[6:7], s[26:27], 19
	s_add_u32 s34, s44, s6
	s_addc_u32 s35, s45, s7
	s_add_i32 s27, s8, 0
	s_add_i32 s47, s27, 0x10000
	s_mov_b32 m0, s47
	s_nop 0
	global_load_lds_dwordx4 v141, s[34:35]
	s_add_i32 s48, s27, 0x12000
	s_mov_b32 m0, s48
	s_nop 0
	global_load_lds_dwordx4 v143, s[34:35]
	s_add_u32 s6, s34, 0x40000
	s_addc_u32 s7, s35, 0
	s_add_i32 s49, s27, 0x14000
	s_mov_b32 m0, s49
	s_nop 0
	global_load_lds_dwordx4 v141, s[6:7]
	s_add_i32 s52, s27, 0x16000
	s_mov_b32 m0, s52
	s_nop 0
	global_load_lds_dwordx4 v143, s[6:7]
	s_add_u32 s30, s42, s2
	s_addc_u32 s31, s43, s3
	s_mov_b32 m0, s27
	s_nop 0
	global_load_lds_dwordx4 v140, s[30:31]
	s_add_i32 s53, s27, 0x2000
	s_mov_b32 m0, s53
	s_nop 0
	global_load_lds_dwordx4 v142, s[30:31]
	s_add_u32 s6, s30, 0x40000
	s_addc_u32 s7, s31, 0
	s_add_i32 s54, s27, 0x4000
	s_mov_b32 m0, s54
	s_nop 0
	global_load_lds_dwordx4 v140, s[6:7]
	s_add_i32 s55, s27, 0x6000
	s_mov_b32 m0, s55
	s_nop 0
	global_load_lds_dwordx4 v142, s[6:7]
	s_cmp_eq_u32 s4, 1
	s_mov_b32 s46, 0
	s_cselect_b64 s[2:3], -1, 0
	s_cmp_lg_u32 s4, 1
	s_cbranch_scc1 .LBB0_881
	s_barrier
.LBB0_881:
	s_lshl_b32 s56, s4, 6
	v_ashrrev_i32_e32 v1, 6, v0
	s_lshl_b32 s4, s4, 13
	v_and_b32_e32 v2, 48, v0
	v_lshl_add_u32 v3, v1, 10, s4
	v_lshlrev_b32_e32 v4, 6, v0
	s_movk_i32 s4, 0x3c0
	v_and_or_b32 v2, v4, s4, v2
	s_lshl_b32 s4, s90, 5
	s_and_b32 s57, s4, 0x60
	s_lshr_b32 s4, s57, 3
	v_add_lshl_u32 v1, v1, s4, 10
	s_add_u32 s4, s0, 0x3800000
	s_addc_u32 s5, s1, 0
	s_add_u32 s6, s0, 0xb000000
	s_addc_u32 s7, s1, 0
	s_add_u32 s8, s0, 0xd000000
	s_addc_u32 s9, s1, 0
	s_add_u32 s0, s34, 0x80
	s_waitcnt vmcnt(2)
	s_barrier
	s_addc_u32 s1, s35, 0
	s_add_i32 s58, s27, 0x18000
	s_mov_b32 m0, s58
	s_nop 0
	global_load_lds_dwordx4 v141, s[0:1]
	s_add_i32 s59, s27, 0x1a000
	s_mov_b32 m0, s59
	s_nop 0
	global_load_lds_dwordx4 v143, s[0:1]
	s_add_u32 s0, s30, 0x80
	s_addc_u32 s1, s31, 0
	s_add_i32 s60, s27, 0x8000
	s_mov_b32 m0, s60
	s_nop 0
	global_load_lds_dwordx4 v140, s[0:1]
	s_add_i32 s61, s27, 0xa000
	s_mov_b32 m0, s61
	s_nop 0
	global_load_lds_dwordx4 v142, s[0:1]
	s_add_u32 s0, s34, 0x40080
	v_lshlrev_b32_e32 v0, 2, v0
	s_addc_u32 s1, s35, 0
	s_add_i32 s62, s27, 0x1c000
	s_mov_b32 m0, s62
	s_nop 0
	global_load_lds_dwordx4 v141, s[0:1]
	v_and_b32_e32 v0, 32, v0
	s_add_i32 s63, s27, 0x1e000
	s_mov_b32 m0, s63
	s_nop 0
	global_load_lds_dwordx4 v143, s[0:1]
	v_bitop3_b32 v3, v2, v3, v0 bitop3:0xde
	v_bitop3_b32 v0, v2, v1, v0 bitop3:0xde
	s_waitcnt vmcnt(6)
	s_add_i32 s64, s27, 0xc000
	s_cmpk_lt_u32 s91, 0x100
	v_add_u32_e32 v0, 0, v0
	s_cselect_b64 s[10:11], -1, 0
	s_or_b32 s65, s57, 0xfffffd00
	s_add_i32 s66, s27, 0xe000
	v_mov_b64_e32 v[128:129], 0x200
	s_waitcnt lgkmcnt(0)
	v_mov_b64_e32 v[130:131], 0x1ff
	s_mov_b64 s[12:13], 0x100
	v_add_u32_e32 v144, 0x10000, v0
	v_add_u32_e32 v145, 0x14000, v0
	v_add_u32_e32 v146, 0, v3
	v_add_u32_e32 v147, 0x18000, v0
	v_add_u32_e32 v148, 0x1c000, v0
	s_mov_b32 s14, 0x3e38aa3b
	s_mov_b32 s16, 0xbfb8aa3b
	s_movk_i32 s67, 0x600
	s_barrier
	s_branch .LBB0_884

.LBB0_891:
	ds_read_b128 v[132:135], v144
	ds_read_b128 v[136:139], v144 offset:1024
	ds_read_b128 v[150:153], v144 offset:2048
	ds_read_b128 v[154:157], v144 offset:3072
	ds_read_b128 v[158:161], v145
	ds_read_b128 v[162:165], v145 offset:1024
	ds_read_b128 v[166:169], v145 offset:2048
	ds_read_b128 v[170:173], v145 offset:3072
	s_add_u32 s34, s30, 0x100
	s_addc_u32 s35, s31, 0
	s_cmp_eq_u32 s71, 12
	s_cselect_b32 s40, s29, s34
	s_cselect_b32 s41, s21, s35
	s_cselect_b32 s38, s68, s69
	s_cselect_b32 s39, s19, s70
	s_add_u32 s36, s40, 0x80
	s_addc_u32 s37, s41, 0
	ds_read_b128 v[174:177], v146
	ds_read_b128 v[178:181], v146 offset:1024
	ds_read_b128 v[182:185], v146 offset:2048
	ds_read_b128 v[186:189], v146 offset:3072
	ds_read_b128 v[190:193], v146 offset:4096
	s_waitcnt vmcnt(0)
	ds_read_b128 v[194:197], v146 offset:5120
	ds_read_b128 v[198:201], v146 offset:6144
	ds_read_b128 v[202:205], v146 offset:7168
	s_add_u32 s30, s30, 0x40080
	s_addc_u32 s31, s31, 0
	s_mov_b32 m0, s64
	s_nop 0
	global_load_lds_dwordx4 v140, s[30:31]
	s_nop 0
	s_mov_b32 m0, s66
	s_nop 0
	global_load_lds_dwordx4 v142, s[30:31]
	s_waitcnt vmcnt(8)
	s_waitcnt lgkmcnt(0)
	s_barrier
	s_setprio 1
	s_waitcnt lgkmcnt(7)
	v_mfma_f32_16x16x32_f16 v[124:127], v[132:135], v[174:177], v[124:127]
	v_mfma_f32_16x16x32_f16 v[120:123], v[150:153], v[174:177], v[120:123]
	s_waitcnt lgkmcnt(5)
	v_mfma_f32_16x16x32_f16 v[116:119], v[132:135], v[182:185], v[116:119]
	v_mfma_f32_16x16x32_f16 v[108:111], v[150:153], v[182:185], v[108:111]
	s_waitcnt lgkmcnt(3)
	v_mfma_f32_16x16x32_f16 v[100:103], v[132:135], v[190:193], v[100:103]
	v_mfma_f32_16x16x32_f16 v[92:95], v[150:153], v[190:193], v[92:95]
	s_waitcnt lgkmcnt(1)
	v_mfma_f32_16x16x32_f16 v[84:87], v[132:135], v[198:201], v[84:87]
	v_mfma_f32_16x16x32_f16 v[76:79], v[150:153], v[198:201], v[76:79]
	v_mfma_f32_16x16x32_f16 v[124:127], v[136:139], v[178:181], v[124:127]
	v_mfma_f32_16x16x32_f16 v[120:123], v[154:157], v[178:181], v[120:123]
	v_mfma_f32_16x16x32_f16 v[116:119], v[136:139], v[186:189], v[116:119]
	v_mfma_f32_16x16x32_f16 v[108:111], v[154:157], v[186:189], v[108:111]
	v_mfma_f32_16x16x32_f16 v[100:103], v[136:139], v[194:197], v[100:103]
	v_mfma_f32_16x16x32_f16 v[92:95], v[154:157], v[194:197], v[92:95]
	s_waitcnt lgkmcnt(0)
	v_mfma_f32_16x16x32_f16 v[84:87], v[136:139], v[202:205], v[84:87]
	v_mfma_f32_16x16x32_f16 v[76:79], v[154:157], v[202:205], v[76:79]
	s_setprio 0
	s_setprio 1
	v_mfma_f32_16x16x32_f16 v[112:115], v[158:161], v[174:177], v[112:115]
	v_mfma_f32_16x16x32_f16 v[104:107], v[166:169], v[174:177], v[104:107]
	v_mfma_f32_16x16x32_f16 v[96:99], v[158:161], v[182:185], v[96:99]
	v_mfma_f32_16x16x32_f16 v[88:91], v[166:169], v[182:185], v[88:91]
	v_mfma_f32_16x16x32_f16 v[80:83], v[158:161], v[190:193], v[80:83]
	v_mfma_f32_16x16x32_f16 v[72:75], v[166:169], v[190:193], v[72:75]
	v_mfma_f32_16x16x32_f16 v[68:71], v[158:161], v[198:201], v[68:71]
	v_mfma_f32_16x16x32_f16 v[64:67], v[166:169], v[198:201], v[64:67]
	v_mfma_f32_16x16x32_f16 v[112:115], v[162:165], v[178:181], v[112:115]
	v_mfma_f32_16x16x32_f16 v[104:107], v[170:173], v[178:181], v[104:107]
	v_mfma_f32_16x16x32_f16 v[96:99], v[162:165], v[186:189], v[96:99]
	v_mfma_f32_16x16x32_f16 v[88:91], v[170:173], v[186:189], v[88:91]
	v_mfma_f32_16x16x32_f16 v[80:83], v[162:165], v[194:197], v[80:83]
	v_mfma_f32_16x16x32_f16 v[72:75], v[170:173], v[194:197], v[72:75]
	v_mfma_f32_16x16x32_f16 v[68:71], v[162:165], v[202:205], v[68:71]
	v_mfma_f32_16x16x32_f16 v[64:67], v[170:173], v[202:205], v[64:67]
	s_setprio 0
	s_barrier
	ds_read_b128 v[174:177], v146 offset:16384
	ds_read_b128 v[178:181], v146 offset:17408
	ds_read_b128 v[182:185], v146 offset:18432
	ds_read_b128 v[186:189], v146 offset:19456
	ds_read_b128 v[190:193], v146 offset:20480
	ds_read_b128 v[194:197], v146 offset:21504
	ds_read_b128 v[198:201], v146 offset:22528
	ds_read_b128 v[202:205], v146 offset:23552
	s_mov_b32 m0, s47
	s_nop 0
	global_load_lds_dwordx4 v141, s[38:39]
	s_nop 0
	s_mov_b32 m0, s48
	s_nop 0
	global_load_lds_dwordx4 v143, s[38:39]
	s_add_u32 s30, s38, 0x40000
	s_addc_u32 s31, s39, 0
	s_mov_b32 m0, s49
	s_nop 0
	global_load_lds_dwordx4 v141, s[30:31]
	s_nop 0
	s_mov_b32 m0, s52
	s_nop 0
	global_load_lds_dwordx4 v143, s[30:31]
	s_mov_b32 m0, s27
	s_nop 0
	global_load_lds_dwordx4 v140, s[40:41]
	s_nop 0
	s_mov_b32 m0, s53
	s_nop 0
	global_load_lds_dwordx4 v142, s[40:41]
	s_waitcnt vmcnt(8)
	s_waitcnt lgkmcnt(0)
	s_barrier
	s_setprio 1
	s_waitcnt lgkmcnt(7)
	v_mfma_f32_16x16x32_f16 v[60:63], v[132:135], v[174:177], v[60:63]
	v_mfma_f32_16x16x32_f16 v[56:59], v[150:153], v[174:177], v[56:59]
	s_waitcnt lgkmcnt(5)
	v_mfma_f32_16x16x32_f16 v[52:55], v[132:135], v[182:185], v[52:55]
	v_mfma_f32_16x16x32_f16 v[44:47], v[150:153], v[182:185], v[44:47]
	s_waitcnt lgkmcnt(3)
	v_mfma_f32_16x16x32_f16 v[36:39], v[132:135], v[190:193], v[36:39]
	v_mfma_f32_16x16x32_f16 v[28:31], v[150:153], v[190:193], v[28:31]
	s_waitcnt lgkmcnt(1)
	v_mfma_f32_16x16x32_f16 v[20:23], v[132:135], v[198:201], v[20:23]
	v_mfma_f32_16x16x32_f16 v[12:15], v[150:153], v[198:201], v[12:15]
	v_mfma_f32_16x16x32_f16 v[60:63], v[136:139], v[178:181], v[60:63]
	v_mfma_f32_16x16x32_f16 v[56:59], v[154:157], v[178:181], v[56:59]
	v_mfma_f32_16x16x32_f16 v[52:55], v[136:139], v[186:189], v[52:55]
	v_mfma_f32_16x16x32_f16 v[44:47], v[154:157], v[186:189], v[44:47]
	v_mfma_f32_16x16x32_f16 v[36:39], v[136:139], v[194:197], v[36:39]
	v_mfma_f32_16x16x32_f16 v[28:31], v[154:157], v[194:197], v[28:31]
	s_waitcnt lgkmcnt(0)
	v_mfma_f32_16x16x32_f16 v[20:23], v[136:139], v[202:205], v[20:23]
	v_mfma_f32_16x16x32_f16 v[12:15], v[154:157], v[202:205], v[12:15]
	s_setprio 0
	s_setprio 1
	v_mfma_f32_16x16x32_f16 v[48:51], v[158:161], v[174:177], v[48:51]
	v_mfma_f32_16x16x32_f16 v[40:43], v[166:169], v[174:177], v[40:43]
	v_mfma_f32_16x16x32_f16 v[32:35], v[158:161], v[182:185], v[32:35]
	v_mfma_f32_16x16x32_f16 v[24:27], v[166:169], v[182:185], v[24:27]
	v_mfma_f32_16x16x32_f16 v[16:19], v[158:161], v[190:193], v[16:19]
	v_mfma_f32_16x16x32_f16 v[8:11], v[166:169], v[190:193], v[8:11]
	v_mfma_f32_16x16x32_f16 v[4:7], v[158:161], v[198:201], v[4:7]
	v_mfma_f32_16x16x32_f16 v[0:3], v[166:169], v[198:201], v[0:3]
	v_mfma_f32_16x16x32_f16 v[48:51], v[162:165], v[178:181], v[48:51]
	v_mfma_f32_16x16x32_f16 v[40:43], v[170:173], v[178:181], v[40:43]
	v_mfma_f32_16x16x32_f16 v[32:35], v[162:165], v[186:189], v[32:35]
	v_mfma_f32_16x16x32_f16 v[24:27], v[170:173], v[186:189], v[24:27]
	v_mfma_f32_16x16x32_f16 v[16:19], v[162:165], v[194:197], v[16:19]
	v_mfma_f32_16x16x32_f16 v[8:11], v[170:173], v[194:197], v[8:11]
	v_mfma_f32_16x16x32_f16 v[4:7], v[162:165], v[202:205], v[4:7]
	v_mfma_f32_16x16x32_f16 v[0:3], v[170:173], v[202:205], v[0:3]
	s_setprio 0
	s_barrier
	ds_read_b128 v[132:135], v147
	ds_read_b128 v[136:139], v147 offset:1024
	ds_read_b128 v[150:153], v147 offset:2048
	ds_read_b128 v[154:157], v147 offset:3072
	ds_read_b128 v[158:161], v148
	ds_read_b128 v[162:165], v148 offset:1024
	ds_read_b128 v[166:169], v148 offset:2048
	ds_read_b128 v[170:173], v148 offset:3072
	ds_read_b128 v[174:177], v146 offset:32768
	ds_read_b128 v[178:181], v146 offset:33792
	ds_read_b128 v[182:185], v146 offset:34816
	ds_read_b128 v[186:189], v146 offset:35840
	ds_read_b128 v[190:193], v146 offset:36864
	ds_read_b128 v[194:197], v146 offset:37888
	ds_read_b128 v[198:201], v146 offset:38912
	ds_read_b128 v[202:205], v146 offset:39936
	s_add_u32 s30, s40, 0x40000
	s_addc_u32 s31, s41, 0
	s_mov_b32 m0, s54
	s_nop 0
	global_load_lds_dwordx4 v140, s[30:31]
	s_nop 0
	s_mov_b32 m0, s55
	s_nop 0
	global_load_lds_dwordx4 v142, s[30:31]
	s_waitcnt vmcnt(8)
	s_waitcnt lgkmcnt(0)
	s_barrier
	s_setprio 1
	s_waitcnt lgkmcnt(7)
	v_mfma_f32_16x16x32_f16 v[124:127], v[132:135], v[174:177], v[124:127]
	v_mfma_f32_16x16x32_f16 v[120:123], v[150:153], v[174:177], v[120:123]
	s_waitcnt lgkmcnt(5)
	v_mfma_f32_16x16x32_f16 v[116:119], v[132:135], v[182:185], v[116:119]
	v_mfma_f32_16x16x32_f16 v[108:111], v[150:153], v[182:185], v[108:111]
	s_waitcnt lgkmcnt(3)
	v_mfma_f32_16x16x32_f16 v[100:103], v[132:135], v[190:193], v[100:103]
	v_mfma_f32_16x16x32_f16 v[92:95], v[150:153], v[190:193], v[92:95]
	s_waitcnt lgkmcnt(1)
	v_mfma_f32_16x16x32_f16 v[84:87], v[132:135], v[198:201], v[84:87]
	v_mfma_f32_16x16x32_f16 v[76:79], v[150:153], v[198:201], v[76:79]
	v_mfma_f32_16x16x32_f16 v[124:127], v[136:139], v[178:181], v[124:127]
	v_mfma_f32_16x16x32_f16 v[120:123], v[154:157], v[178:181], v[120:123]
	v_mfma_f32_16x16x32_f16 v[116:119], v[136:139], v[186:189], v[116:119]
	v_mfma_f32_16x16x32_f16 v[108:111], v[154:157], v[186:189], v[108:111]
	v_mfma_f32_16x16x32_f16 v[100:103], v[136:139], v[194:197], v[100:103]
	v_mfma_f32_16x16x32_f16 v[92:95], v[154:157], v[194:197], v[92:95]
	s_waitcnt lgkmcnt(0)
	v_mfma_f32_16x16x32_f16 v[84:87], v[136:139], v[202:205], v[84:87]
	v_mfma_f32_16x16x32_f16 v[76:79], v[154:157], v[202:205], v[76:79]
	s_setprio 0
	s_setprio 1
	v_mfma_f32_16x16x32_f16 v[112:115], v[158:161], v[174:177], v[112:115]
	v_mfma_f32_16x16x32_f16 v[104:107], v[166:169], v[174:177], v[104:107]
	v_mfma_f32_16x16x32_f16 v[96:99], v[158:161], v[182:185], v[96:99]
	v_mfma_f32_16x16x32_f16 v[88:91], v[166:169], v[182:185], v[88:91]
	v_mfma_f32_16x16x32_f16 v[80:83], v[158:161], v[190:193], v[80:83]
	v_mfma_f32_16x16x32_f16 v[72:75], v[166:169], v[190:193], v[72:75]
	v_mfma_f32_16x16x32_f16 v[68:71], v[158:161], v[198:201], v[68:71]
	v_mfma_f32_16x16x32_f16 v[64:67], v[166:169], v[198:201], v[64:67]
	v_mfma_f32_16x16x32_f16 v[112:115], v[162:165], v[178:181], v[112:115]
	v_mfma_f32_16x16x32_f16 v[104:107], v[170:173], v[178:181], v[104:107]
	v_mfma_f32_16x16x32_f16 v[96:99], v[162:165], v[186:189], v[96:99]
	v_mfma_f32_16x16x32_f16 v[88:91], v[170:173], v[186:189], v[88:91]
	v_mfma_f32_16x16x32_f16 v[80:83], v[162:165], v[194:197], v[80:83]
	v_mfma_f32_16x16x32_f16 v[72:75], v[170:173], v[194:197], v[72:75]
	v_mfma_f32_16x16x32_f16 v[68:71], v[162:165], v[202:205], v[68:71]
	v_mfma_f32_16x16x32_f16 v[64:67], v[170:173], v[202:205], v[64:67]
	s_setprio 0
	s_barrier
	ds_read_b128 v[174:177], v146 offset:49152
	ds_read_b128 v[178:181], v146 offset:50176
	ds_read_b128 v[182:185], v146 offset:51200
	ds_read_b128 v[186:189], v146 offset:52224
	ds_read_b128 v[190:193], v146 offset:53248
	ds_read_b128 v[194:197], v146 offset:54272
	ds_read_b128 v[198:201], v146 offset:55296
	ds_read_b128 v[202:205], v146 offset:56320
	s_add_u32 s30, s38, 0x80
	s_addc_u32 s31, s39, 0
	s_mov_b32 m0, s58
	s_nop 0
	global_load_lds_dwordx4 v141, s[30:31]
	s_nop 0
	s_mov_b32 m0, s59
	s_nop 0
	global_load_lds_dwordx4 v143, s[30:31]
	s_add_u32 s30, s38, 0x40080
	s_addc_u32 s31, s39, 0
	s_mov_b32 m0, s62
	s_nop 0
	global_load_lds_dwordx4 v141, s[30:31]
	s_nop 0
	s_mov_b32 m0, s63
	s_nop 0
	global_load_lds_dwordx4 v143, s[30:31]
	s_mov_b32 m0, s60
	s_nop 0
	global_load_lds_dwordx4 v140, s[36:37]
	s_nop 0
	s_mov_b32 m0, s61
	s_nop 0
	global_load_lds_dwordx4 v142, s[36:37]
	s_waitcnt vmcnt(8)
	s_waitcnt lgkmcnt(0)
	s_barrier
	s_setprio 1
	s_waitcnt lgkmcnt(7)
	v_mfma_f32_16x16x32_f16 v[60:63], v[132:135], v[174:177], v[60:63]
	v_mfma_f32_16x16x32_f16 v[56:59], v[150:153], v[174:177], v[56:59]
	s_waitcnt lgkmcnt(5)
	v_mfma_f32_16x16x32_f16 v[52:55], v[132:135], v[182:185], v[52:55]
	v_mfma_f32_16x16x32_f16 v[44:47], v[150:153], v[182:185], v[44:47]
	s_waitcnt lgkmcnt(3)
	v_mfma_f32_16x16x32_f16 v[36:39], v[132:135], v[190:193], v[36:39]
	v_mfma_f32_16x16x32_f16 v[28:31], v[150:153], v[190:193], v[28:31]
	s_waitcnt lgkmcnt(1)
	v_mfma_f32_16x16x32_f16 v[20:23], v[132:135], v[198:201], v[20:23]
	v_mfma_f32_16x16x32_f16 v[12:15], v[150:153], v[198:201], v[12:15]
	v_mfma_f32_16x16x32_f16 v[60:63], v[136:139], v[178:181], v[60:63]
	v_mfma_f32_16x16x32_f16 v[56:59], v[154:157], v[178:181], v[56:59]
	v_mfma_f32_16x16x32_f16 v[52:55], v[136:139], v[186:189], v[52:55]
	v_mfma_f32_16x16x32_f16 v[44:47], v[154:157], v[186:189], v[44:47]
	v_mfma_f32_16x16x32_f16 v[36:39], v[136:139], v[194:197], v[36:39]
	v_mfma_f32_16x16x32_f16 v[28:31], v[154:157], v[194:197], v[28:31]
	s_waitcnt lgkmcnt(0)
	v_mfma_f32_16x16x32_f16 v[20:23], v[136:139], v[202:205], v[20:23]
	v_mfma_f32_16x16x32_f16 v[12:15], v[154:157], v[202:205], v[12:15]
	s_setprio 0
	s_setprio 1
	v_mfma_f32_16x16x32_f16 v[48:51], v[158:161], v[174:177], v[48:51]
	v_mfma_f32_16x16x32_f16 v[40:43], v[166:169], v[174:177], v[40:43]
	v_mfma_f32_16x16x32_f16 v[32:35], v[158:161], v[182:185], v[32:35]
	v_mfma_f32_16x16x32_f16 v[24:27], v[166:169], v[182:185], v[24:27]
	v_mfma_f32_16x16x32_f16 v[16:19], v[158:161], v[190:193], v[16:19]
	v_mfma_f32_16x16x32_f16 v[8:11], v[166:169], v[190:193], v[8:11]
	v_mfma_f32_16x16x32_f16 v[4:7], v[158:161], v[198:201], v[4:7]
	v_mfma_f32_16x16x32_f16 v[0:3], v[166:169], v[198:201], v[0:3]
	v_mfma_f32_16x16x32_f16 v[48:51], v[162:165], v[178:181], v[48:51]
	v_mfma_f32_16x16x32_f16 v[40:43], v[170:173], v[178:181], v[40:43]
	v_mfma_f32_16x16x32_f16 v[32:35], v[162:165], v[186:189], v[32:35]
	v_mfma_f32_16x16x32_f16 v[24:27], v[170:173], v[186:189], v[24:27]
	v_mfma_f32_16x16x32_f16 v[16:19], v[162:165], v[194:197], v[16:19]
	v_mfma_f32_16x16x32_f16 v[8:11], v[170:173], v[194:197], v[8:11]
	v_mfma_f32_16x16x32_f16 v[4:7], v[162:165], v[202:205], v[4:7]
	v_mfma_f32_16x16x32_f16 v[0:3], v[170:173], v[202:205], v[0:3]
	s_setprio 0
	s_barrier
	s_add_i32 s71, s71, 2
	s_add_u32 s69, s69, 0x100
	s_addc_u32 s70, s70, 0
	s_cmp_gt_u32 s71, 13
	s_mov_b64 s[30:31], s[34:35]
	s_cbranch_scc0 .LBB0_891
	s_and_b64 vcc, exec, s[10:11]
	s_cbranch_vccz .LBB0_894
	s_barrier

.LBB0_962:
	s_cmp_lt_i32 s84, 7
	s_cselect_b64 s[0:1], -1, 0
	s_cmp_gt_i32 s85, 6
	s_cselect_b64 s[2:3], -1, 0
	s_and_b64 s[0:1], s[0:1], s[2:3]
	s_andn2_b64 vcc, exec, s[0:1]
	s_mul_i32 s70, s90, 0x3c00
	s_cbranch_vccnz .LBB0_1163
	s_ashr_i32 s6, s94, 7
	s_ashr_i32 s7, s6, 31
	s_mov_b64 s[4:5], s[82:83]
	s_lshl_b64 s[0:1], s[6:7], 22
	s_add_u32 s0, s4, s0
	s_addc_u32 s1, s5, s1
	s_lshl_b32 s2, s94, 1
	s_and_b32 s2, s2, 0xc0
	s_lshl_b32 s14, s2, 1
	s_add_u32 s12, s0, s14
	s_addc_u32 s13, s1, 0
	s_lshl_b64 s[0:1], s[6:7], 17
	s_add_u32 s0, s4, s0
	s_addc_u32 s1, s5, s1
	s_add_u32 s15, s0, s14
	s_addc_u32 s17, s1, 0
	s_add_u32 s0, s15, 0x680000
	s_addc_u32 s1, s17, 0
	s_add_u32 s10, s15, 0x6c0000
	s_addc_u32 s11, s17, 0
	s_lshl_b32 s2, s94, 8
	s_and_b32 s2, s2, 0x1f00
	s_lshl_b32 s8, s90, 5
	s_mov_b32 s3, 0
	s_add_i32 s2, s2, s8
	s_lshl_b64 s[8:9], s[2:3], 9
	s_add_u32 s8, s12, s8
	v_mbcnt_lo_u32_b32 v184, -1, 0
	v_mbcnt_hi_u32_b32 v184, -1, v184
	s_addc_u32 s9, s13, s9
	s_lshl_b32 s13, s90, 3
	v_lshlrev_b32_e32 v134, 3, v184
	s_lshl_b32 s12, s90, 4
	s_and_b32 s13, s13, 0x1fffffe0
	v_and_b32_e32 v137, 24, v134
	v_lshl_add_u32 v33, v184, 9, s12
	s_and_b32 s12, s12, 48
	v_lshrrev_b32_e32 v0, 2, v184
	v_or_b32_e32 v1, s13, v137
	s_lshl_b32 s13, s90, 10
	v_and_b32_e32 v135, 31, v184
	v_ashrrev_i32_e32 v136, 5, v184
	v_add_lshl_u32 v0, v0, s12, 9
	s_cmp_lg_u32 0, -1
	v_lshl_add_u32 v95, v1, 1, v0
	s_cselect_b32 s12, 0, 0
	v_lshlrev_b32_e32 v0, 3, v136
	v_lshlrev_b32_e32 v132, 9, v135
	v_mov_b32_e32 v133, 0
	s_add_i32 s12, s12, s13
	s_mov_b32 m0, s12
	s_nop 0
	global_load_lds_dwordx4 v33, s[0:1]
	v_ashrrev_i32_e32 v1, 31, v0
	v_lshl_add_u64 v[2:3], s[8:9], 0, v[132:133]
	s_add_i32 s16, s12, 0xc000
	s_mov_b32 m0, s16
	s_nop 0
	global_load_lds_dwordx4 v95, s[10:11]
	v_lshl_add_u64 v[0:1], v[0:1], 1, v[2:3]
	s_mov_b32 s8, 0xd000000
	s_add_u32 s18, s15, 0x688000
	v_add_co_u32_e32 v2, vcc, s8, v0
	s_addc_u32 s19, s17, 0
	s_add_i32 s20, s12, 0x3000
	s_mov_b32 m0, s20
	s_nop 0
	global_load_lds_dwordx4 v33, s[18:19]
	v_addc_co_u32_e32 v3, vcc, 0, v1, vcc
	global_load_dwordx4 v[124:127], v[2:3], off
	s_mov_b64 s[8:9], 0xd000000
	v_lshl_add_u64 v[0:1], v[0:1], 0, s[8:9]
	global_load_dwordx4 v[120:123], v[0:1], off offset:32
	global_load_dwordx4 v[116:119], v[0:1], off offset:64
	global_load_dwordx4 v[104:107], v[0:1], off offset:96
	s_add_u32 s8, s15, 0x690000
	v_lshlrev_b32_e32 v0, 4, v135
	v_lshl_add_u32 v1, v136, 10, 0
	s_addc_u32 s9, s17, 0
	s_addk_i32 s12, 0x6000
	s_mov_b32 m0, s12
	s_nop 0
	global_load_lds_dwordx4 v33, s[8:9]
	v_add_u32_e32 v139, v1, v0
	s_waitcnt vmcnt(3) lgkmcnt(0)
	s_barrier
	ds_read_b128 v[0:3], v139
	ds_read_b128 v[34:37], v139 offset:2048
	s_mov_b32 s12, 0x41400000
	s_waitcnt vmcnt(3) lgkmcnt(1)
	v_mfma_f32_32x32x16_bf16 v[16:31], v[0:3], v[124:127], 0
	ds_read_b128 v[0:3], v139 offset:512
	s_waitcnt vmcnt(2) lgkmcnt(1)
	v_mfma_f32_32x32x16_bf16 v[16:31], v[34:37], v[120:123], v[16:31]
	ds_read_b128 v[34:37], v139 offset:2560
	s_waitcnt lgkmcnt(1)
	v_mfma_f32_32x32x16_bf16 v[0:15], v[0:3], v[124:127], 0
	s_waitcnt lgkmcnt(0)
	v_mfma_f32_32x32x16_bf16 v[0:15], v[34:37], v[120:123], v[0:15]
	ds_read_b128 v[34:37], v139 offset:4096
	s_waitcnt vmcnt(1) lgkmcnt(0)
	v_mfma_f32_32x32x16_bf16 v[16:31], v[34:37], v[116:119], v[16:31]
	ds_read_b128 v[34:37], v139 offset:4608
	s_waitcnt lgkmcnt(0)
	v_mfma_f32_32x32x16_bf16 v[0:15], v[34:37], v[116:119], v[0:15]
	ds_read_b128 v[34:37], v139 offset:6144
	s_waitcnt vmcnt(0) lgkmcnt(0)
	v_mfma_f32_32x32x16_bf16 v[16:31], v[34:37], v[104:107], v[16:31]
	ds_read_b128 v[34:37], v139 offset:6656
	s_waitcnt lgkmcnt(0)
	v_mfma_f32_32x32x16_bf16 v[0:15], v[34:37], v[104:107], v[0:15]
	s_nop 8
	v_max_f32_e32 v32, v17, v17
	v_max_f32_e32 v34, v16, v16
	v_max_f32_e32 v32, v34, v32
	v_max3_f32 v35, v18, v19, v1
	v_max3_f32 v32, v32, v0, v2
	v_max3_f32 v34, v35, v22, v23
	v_max3_f32 v32, v32, v3, v20
	v_max3_f32 v34, v34, v6, v7
	v_max3_f32 v32, v32, v21, v4
	v_max3_f32 v34, v34, v26, v27
	v_max3_f32 v32, v32, v5, v24
	v_max3_f32 v34, v34, v10, v11
	v_max3_f32 v32, v32, v25, v8
	v_max3_f32 v34, v34, v30, v31
	v_max3_f32 v32, v32, v9, v28
	v_max3_f32 v34, v34, v14, v15
	v_max3_f32 v32, v32, v29, v12
	v_max3_f32 v32, v32, v13, v34
	v_mov_b32_e32 v34, v32
	s_nop 1
	v_permlane32_swap_b32_e32 v32, v34
	v_max_f32_e32 v34, v34, v34
	v_max_f32_e32 v32, v32, v32
	v_max_f32_e32 v32, v32, v34
	v_cmp_gt_f32_e64 vcc, |v32|, s12
	s_cmp_lg_u64 vcc, 0
	s_cselect_b64 s[8:9], -1, 0
	s_cbranch_vccnz .LBB0_1435
.LBB0_964:
	s_lshl_b32 s15, s90, 8
	s_add_i32 s15, s15, 0
	s_add_i32 s15, s15, 0x12000
	s_add_u32 s0, s0, 0x18000
	s_addc_u32 s1, s1, 0
	s_cmp_lg_u32 0, -1
	s_cselect_b32 s17, 0, 0
	s_add_i32 s13, s17, s13
	s_waitcnt vmcnt(0) lgkmcnt(0)
	s_barrier
	s_add_i32 s17, s13, 0x9000
	s_mov_b32 m0, s17
	s_nop 0
	global_load_lds_dwordx4 v33, s[0:1]
	s_add_u32 s0, s10, 0x8000
	s_addc_u32 s1, s11, 0
	s_add_i32 s17, s13, 0xe000
	s_mov_b32 m0, s17
	s_nop 0
	global_load_lds_dwordx4 v95, s[0:1]
	v_exp_f32_e32 v34, v0
	v_exp_f32_e32 v35, v1
	v_exp_f32_e32 v36, v2
	v_exp_f32_e32 v37, v3
	v_exp_f32_e32 v38, v4
	v_exp_f32_e32 v39, v5
	v_exp_f32_e32 v40, v6
	v_exp_f32_e32 v41, v7
	v_exp_f32_e32 v42, v8
	v_exp_f32_e32 v43, v9
	v_exp_f32_e32 v44, v10
	v_exp_f32_e32 v45, v11
	ds_read_b128 v[0:3], v139 offset:14336
	ds_read_b128 v[4:7], v139 offset:12800
	ds_read_b128 v[8:11], v139 offset:12288
	v_lshlrev_b32_e32 v32, 1, v184
	v_lshlrev_b32_e32 v144, 4, v184
	v_exp_f32_e32 v16, v16
	v_exp_f32_e32 v17, v17
	v_exp_f32_e32 v18, v18
	v_exp_f32_e32 v19, v19
	v_and_b32_e32 v132, 32, v32
	v_and_b32_e32 v32, 0xc0, v144
	v_lshl_or_b32 v138, v136, 8, v32
	v_add_u32_e32 v32, 0, v132
	v_add3_u32 v94, v32, v137, v138
	v_cmp_gt_u32_e64 s[0:1], 32, v184
	v_lshl_add_u32 v141, v135, 2, s15
	v_exp_f32_e32 v20, v20
	v_exp_f32_e32 v21, v21
	v_exp_f32_e32 v22, v22
	v_exp_f32_e32 v23, v23
	v_exp_f32_e32 v24, v24
	v_exp_f32_e32 v25, v25
	v_exp_f32_e32 v26, v26
	v_exp_f32_e32 v27, v27
	v_exp_f32_e32 v28, v28
	v_exp_f32_e32 v29, v29
	v_exp_f32_e32 v30, v30
	v_exp_f32_e32 v31, v31
	v_exp_f32_e32 v46, v12
	v_exp_f32_e32 v47, v13
	v_exp_f32_e32 v64, v14
	v_exp_f32_e32 v65, v15
	ds_read_b128 v[12:15], v139 offset:14848
	v_add_f32_e32 v32, v16, v17
	s_waitcnt lgkmcnt(1)
	v_mfma_f32_32x32x16_bf16 v[78:93], v[8:11], v[124:127], 0
	v_add_f32_e32 v32, v18, v32
	v_add_f32_e32 v32, v19, v32
	v_cvt_pk_bf16_f32 v100, v16, v17
	v_add_f32_e32 v32, v20, v32
	v_mov_b32_e32 v101, v100
	v_mov_b32_e32 v102, v100
	v_mov_b32_e32 v103, v100
	ds_read_b128 v[8:11], v139 offset:16384
	v_mfma_f32_32x32x16_bf16 v[48:63], v[4:7], v[124:127], 0
	v_add_f32_e32 v16, v21, v32
	v_add_f32_e32 v16, v22, v16
	v_add_f32_e32 v16, v23, v16
	v_cvt_pk_bf16_f32 v101, v18, v19
	ds_read_b128 v[4:7], v139 offset:16896
	v_mfma_f32_32x32x16_bf16 v[78:93], v[0:3], v[120:123], v[78:93]
	v_add_f32_e32 v16, v24, v16
	v_add_f32_e32 v16, v25, v16
	v_add_f32_e32 v16, v26, v16
	v_cvt_pk_bf16_f32 v102, v20, v21
	ds_read_b128 v[0:3], v139 offset:18432
	s_waitcnt lgkmcnt(3)
	v_mfma_f32_32x32x16_bf16 v[48:63], v[12:15], v[120:123], v[48:63]
	v_add_f32_e32 v16, v27, v16
	v_add_f32_e32 v16, v28, v16
	v_add_f32_e32 v16, v29, v16
	v_cvt_pk_bf16_f32 v103, v22, v23
	ds_read_b128 v[12:15], v139 offset:18944
	s_waitcnt lgkmcnt(3)
	v_mfma_f32_32x32x16_bf16 v[78:93], v[8:11], v[116:119], v[78:93]
	v_add_f32_e32 v16, v30, v16
	v_add_f32_e32 v16, v31, v16
	v_cvt_pk_bf16_f32 v108, v24, v25
	v_add_f32_e32 v16, v34, v16
	v_mov_b32_e32 v109, v108
	v_mov_b32_e32 v110, v108
	v_mov_b32_e32 v111, v108
	s_waitcnt lgkmcnt(2)
	v_mfma_f32_32x32x16_bf16 v[48:63], v[4:7], v[116:119], v[48:63]
	v_add_f32_e32 v8, v35, v16
	v_add_f32_e32 v8, v36, v8
	v_add_f32_e32 v8, v37, v8
	v_cvt_pk_bf16_f32 v109, v26, v27
	s_waitcnt lgkmcnt(1)
	v_mfma_f32_32x32x16_bf16 v[78:93], v[0:3], v[104:107], v[78:93]
	v_add_f32_e32 v4, v38, v8
	v_add_f32_e32 v4, v39, v4
	v_add_f32_e32 v4, v40, v4
	v_cvt_pk_bf16_f32 v110, v28, v29
	s_waitcnt lgkmcnt(0)
	v_mfma_f32_32x32x16_bf16 v[48:63], v[12:15], v[104:107], v[48:63]
	v_add_f32_e32 v0, v41, v4
	v_add_f32_e32 v0, v42, v0
	v_add_f32_e32 v0, v43, v0
	v_cvt_pk_bf16_f32 v111, v30, v31
	s_nop 0
	v_add_f32_e32 v0, v44, v0
	v_add_f32_e32 v4, v45, v0
	v_cvt_pk_bf16_f32 v112, v34, v35
	v_cvt_pk_bf16_f32 v113, v36, v37
	ds_read_b64_tr_b16 v[0:1], v94 offset:49152
	ds_read_b64_tr_b16 v[2:3], v94 offset:49664
	v_add_f32_e32 v4, v46, v4
	v_add_f32_e32 v4, v47, v4
	v_cvt_pk_bf16_f32 v114, v38, v39
	v_cvt_pk_bf16_f32 v115, v40, v41
	ds_read_b64_tr_b16 v[16:17], v94 offset:53248
	ds_read_b64_tr_b16 v[18:19], v94 offset:53760
	v_add_f32_e32 v4, v64, v4
	v_cvt_pk_bf16_f32 v96, v42, v43
	v_cvt_pk_bf16_f32 v97, v44, v45
	ds_read_b64_tr_b16 v[32:33], v94 offset:50176
	ds_read_b64_tr_b16 v[34:35], v94 offset:50688
	v_add_f32_e32 v4, v65, v4
	v_cvt_pk_bf16_f32 v98, v46, v47
	v_cvt_pk_bf16_f32 v99, v64, v65
	s_nop 0
	v_add_f32_e32 v142, 0, v4
	v_max_f32_e32 v4, v79, v79
	v_max_f32_e32 v5, v78, v78
	v_max_f32_e32 v4, v5, v4
	v_max3_f32 v5, v80, v81, v49
	v_max3_f32 v4, v4, v48, v50
	v_max3_f32 v4, v4, v51, v82
	v_max3_f32 v5, v5, v84, v85
	v_max3_f32 v4, v4, v83, v52
	v_max3_f32 v5, v5, v54, v55
	v_max3_f32 v4, v4, v53, v86
	v_max3_f32 v5, v5, v88, v89
	v_max3_f32 v4, v4, v87, v56
	v_max3_f32 v5, v5, v58, v59
	v_max3_f32 v4, v4, v57, v90
	v_max3_f32 v5, v5, v92, v93
	v_max3_f32 v4, v4, v91, v60
	v_max3_f32 v5, v5, v62, v63
	v_max3_f32 v4, v4, v61, v5
	s_add_u32 s18, s10, 0x10000
	v_sub_f32_e32 v5, v4, v133
	s_addc_u32 s19, s11, 0
	s_add_i32 s13, s13, 0x10000
	s_mov_b32 m0, s13
	s_nop 0
	global_load_lds_dwordx4 v95, s[18:19]
	v_cmp_lt_f32_e32 vcc, s12, v5
	s_cmp_lg_u64 vcc, 0
	s_cselect_b64 s[12:13], -1, 0
	s_cbranch_vccnz .LBB0_1436
	s_andn2_b64 vcc, exec, s[8:9]
	s_cbranch_vccnz .LBB0_967

.LBB0_969:
	ds_read_b128 v[146:149], v139 offset:27136
	v_add_f32_e32 v40, v78, v79
	v_cvt_pk_bf16_f32 v100, v78, v79
	s_waitcnt lgkmcnt(3)
	v_mfma_f32_32x32x16_bf16 v[64:79], v[32:35], v[124:127], 0
	v_add_f32_e32 v40, v80, v40
	v_add_f32_e32 v40, v81, v40
	v_add_f32_e32 v40, v82, v40
	ds_read_b128 v[150:153], v139 offset:28672
	v_add_f32_e32 v32, v83, v40
	v_add_f32_e32 v32, v84, v32
	v_add_f32_e32 v96, v85, v32
	s_waitcnt lgkmcnt(3)
	v_mfma_f32_32x32x16_bf16 v[32:47], v[36:39], v[124:127], 0
	v_cvt_pk_bf16_f32 v101, v80, v81
	ds_read_b128 v[154:157], v139 offset:29184
	s_waitcnt lgkmcnt(3)
	v_mfma_f32_32x32x16_bf16 v[64:79], v[128:131], v[120:123], v[64:79]
	v_add_f32_e32 v80, v86, v96
	v_add_f32_e32 v80, v87, v80
	v_add_f32_e32 v96, v88, v80
	v_cvt_pk_bf16_f32 v102, v82, v83
	ds_read_b128 v[80:83], v139 offset:30720
	s_waitcnt lgkmcnt(3)
	v_mfma_f32_32x32x16_bf16 v[32:47], v[146:149], v[120:123], v[32:47]
	v_add_f32_e32 v96, v89, v96
	v_add_f32_e32 v96, v90, v96
	v_add_f32_e32 v96, v91, v96
	v_cvt_pk_bf16_f32 v103, v84, v85
	ds_read_b128 v[128:131], v139 offset:31232
	s_waitcnt lgkmcnt(3)
	v_mfma_f32_32x32x16_bf16 v[64:79], v[150:153], v[116:119], v[64:79]
	v_add_f32_e32 v84, v92, v96
	v_add_f32_e32 v84, v93, v84
	v_add_f32_e32 v84, v48, v84
	v_cvt_pk_bf16_f32 v108, v86, v87
	s_waitcnt lgkmcnt(2)
	v_mfma_f32_32x32x16_bf16 v[32:47], v[154:157], v[116:119], v[32:47]
	v_add_f32_e32 v84, v49, v84
	v_add_f32_e32 v84, v50, v84
	v_add_f32_e32 v84, v51, v84
	v_cvt_pk_bf16_f32 v109, v88, v89
	s_waitcnt lgkmcnt(1)
	v_mfma_f32_32x32x16_bf16 v[64:79], v[80:83], v[104:107], v[64:79]
	v_add_f32_e32 v84, v52, v84
	v_add_f32_e32 v84, v53, v84
	v_add_f32_e32 v84, v54, v84
	v_cvt_pk_bf16_f32 v110, v90, v91
	s_waitcnt lgkmcnt(0)
	v_mfma_f32_32x32x16_bf16 v[32:47], v[128:131], v[104:107], v[32:47]
	v_add_f32_e32 v80, v55, v84
	v_add_f32_e32 v80, v56, v80
	v_add_f32_e32 v80, v57, v80
	v_cvt_pk_bf16_f32 v111, v92, v93
	s_nop 0
	v_add_f32_e32 v80, v58, v80
	v_add_f32_e32 v84, v59, v80
	v_cvt_pk_bf16_f32 v112, v48, v49
	v_cvt_pk_bf16_f32 v113, v50, v51
	ds_read_b64_tr_b16 v[80:81], v94 offset:57344
	ds_read_b64_tr_b16 v[82:83], v94 offset:57856
	v_add_f32_e32 v48, v60, v84
	v_add_f32_e32 v48, v61, v48
	v_cvt_pk_bf16_f32 v114, v52, v53
	v_cvt_pk_bf16_f32 v115, v54, v55
	ds_read_b64_tr_b16 v[52:53], v94 offset:61440
	ds_read_b64_tr_b16 v[54:55], v94 offset:61952
	v_add_f32_e32 v84, v62, v48
	v_cvt_pk_bf16_f32 v96, v56, v57
	v_cvt_pk_bf16_f32 v97, v58, v59
	ds_read_b64_tr_b16 v[48:49], v94 offset:58368
	ds_read_b64_tr_b16 v[50:51], v94 offset:58880
	v_add_f32_e32 v56, v63, v84
	v_cvt_pk_bf16_f32 v98, v60, v61
	v_cvt_pk_bf16_f32 v99, v62, v63
	s_nop 0
	v_add_f32_e32 v142, v142, v56
	v_max_f32_e32 v56, v65, v65
	v_max_f32_e32 v57, v64, v64
	v_max_f32_e32 v56, v57, v56
	v_max3_f32 v57, v66, v67, v33
	v_max3_f32 v56, v56, v32, v34
	v_max3_f32 v56, v56, v35, v68
	v_max3_f32 v57, v57, v70, v71
	v_max3_f32 v56, v56, v69, v36
	v_max3_f32 v57, v57, v38, v39
	v_max3_f32 v56, v56, v37, v72
	v_max3_f32 v57, v57, v74, v75
	v_max3_f32 v56, v56, v73, v40
	v_max3_f32 v57, v57, v42, v43
	v_max3_f32 v56, v56, v41, v76
	v_max3_f32 v57, v57, v78, v79
	v_max3_f32 v56, v56, v77, v44
	v_max3_f32 v57, v57, v46, v47
	s_add_u32 s10, s10, 0x18000
	v_max3_f32 v56, v56, v45, v57
	s_addc_u32 s11, s11, 0
	s_mov_b32 m0, s16
	s_nop 0
	global_load_lds_dwordx4 v95, s[10:11]
	v_sub_f32_e32 v57, v56, v133
	s_mov_b32 s10, 0x41400000
	v_cmp_lt_f32_e32 vcc, s10, v57
	s_cmp_lg_u64 vcc, 0
	s_cselect_b64 s[10:11], -1, 0
	s_cbranch_vccnz .LBB0_1439
	s_andn2_b64 vcc, exec, s[8:9]
	s_cbranch_vccnz .LBB0_972

.LBB0_1368:
	s_add_u32 s31, s6, 0xd800000
	s_addc_u32 s33, s7, 0
	s_add_u32 s34, s6, 0x1600000
	s_addc_u32 s35, s7, 0
	s_lshl_b32 s1, s90, 10
	v_lshlrev_b32_e32 v0, 4, v190
	v_add_u32_e32 v1, s1, v0
	v_ashrrev_i32_e32 v2, 31, v1
	v_lshrrev_b32_e32 v2, 22, v2
	v_add_u32_e32 v2, v1, v2
	v_ashrrev_i32_e32 v2, 10, v2
	v_mul_i32_i24_e32 v3, 0x400, v2
	v_sub_u32_e32 v3, v1, v3
	v_lshrrev_b32_e32 v4, 4, v3
	v_bitop3_b32 v3, v4, v3, 32 bitop3:0x6c
	v_ashrrev_i32_e32 v5, 31, v3
	v_lshrrev_b32_e32 v5, 26, v5
	v_lshlrev_b32_e32 v4, 3, v2
	v_add_u32_e32 v5, v3, v5
	v_and_b32_e32 v4, -16, v4
	v_ashrrev_i32_e32 v6, 6, v5
	v_and_b32_e32 v5, 0xc0, v5
	v_add_u32_e32 v4, v6, v4
	v_sub_u32_e32 v3, v3, v5
	v_mov_b32_e32 v5, 1
	v_lshlrev_b32_e32 v2, 5, v2
	v_ashrrev_i16_sdwa v3, v5, sext(v3) dst_sel:DWORD dst_unused:UNUSED_PAD src0_sel:DWORD src1_sel:BYTE_0
	v_lshlrev_b32_e32 v7, 1, v4
	v_lshrrev_b32_e32 v8, 2, v4
	v_and_b32_e32 v6, 3, v6
	s_mov_b32 s3, 0x1fffe0
	v_and_b32_e32 v2, 32, v2
	v_bfe_i32 v3, v3, 0, 16
	v_and_b32_e32 v7, 24, v7
	v_and_b32_e32 v8, 4, v8
	v_and_or_b32 v6, v4, s3, v6
	v_or3_b32 v6, v6, v8, v7
	v_add_lshl_u32 v2, v2, v3, 1
	v_add_u32_e32 v1, 0x2000, v1
	v_lshl_add_u32 v132, v4, 11, v2
	v_lshl_add_u32 v133, v6, 11, v2
	v_ashrrev_i32_e32 v2, 31, v1
	v_lshrrev_b32_e32 v2, 22, v2
	v_add_u32_e32 v2, v1, v2
	v_ashrrev_i32_e32 v2, 10, v2
	v_mul_i32_i24_e32 v3, 0x400, v2
	v_sub_u32_e32 v1, v1, v3
	v_lshrrev_b32_e32 v3, 4, v1
	v_bitop3_b32 v1, v3, v1, 32 bitop3:0x6c
	v_ashrrev_i32_e32 v4, 31, v1
	v_lshrrev_b32_e32 v4, 26, v4
	s_add_i32 s0, s2, s0
	v_lshlrev_b32_e32 v3, 3, v2
	v_add_u32_e32 v4, v1, v4
	s_ashr_i32 s2, s0, 31
	v_and_b32_e32 v3, -16, v3
	v_ashrrev_i32_e32 v6, 6, v4
	s_lshr_b32 s2, s2, 27
	v_add_u32_e32 v3, v6, v3
	v_and_b32_e32 v6, 3, v6
	s_add_i32 s2, s0, s2
	v_and_or_b32 v6, v3, s3, v6
	s_ashr_i32 s3, s2, 5
	s_and_b32 s2, s2, 0xffe0
	s_sub_i32 s2, s0, s2
	s_bfe_i32 s0, s2, 0x80000
	s_bfe_u32 s0, s0, 0x3000c
	s_add_i32 s4, s2, s0
	s_bfe_i32 s0, s4, 0x80000
	s_and_b32 s4, s4, 0xf8
	v_and_b32_e32 v4, 0xffc0, v4
	s_sub_i32 s2, s2, s4
	v_sub_u32_e32 v1, v1, v4
	s_lshl_b32 s3, s3, 3
	s_sext_i32_i16 s0, s0
	s_sext_i32_i8 s2, s2
	v_lshrrev_b16_e32 v4, 7, v1
	s_lshr_b32 s0, s0, 3
	s_add_i32 s4, s3, s2
	v_and_b32_e32 v4, 1, v4
	s_ashr_i32 s5, s4, 31
	s_bfe_i64 s[10:11], s[0:1], 0x100000
	v_add_u16_e32 v1, v1, v4
	s_lshr_b32 s9, s91, 8
	s_lshl_b64 s[2:3], s[4:5], 19
	s_lshl_b64 s[10:11], s[10:11], 19
	v_lshlrev_b32_e32 v2, 5, v2
	v_ashrrev_i16_sdwa v1, v5, sext(v1) dst_sel:DWORD dst_unused:UNUSED_PAD src0_sel:DWORD src1_sel:BYTE_0
	v_lshlrev_b32_e32 v4, 1, v3
	v_lshrrev_b32_e32 v5, 2, v3
	s_add_u32 s10, s34, s10
	v_and_b32_e32 v2, 32, v2
	v_bfe_i32 v1, v1, 0, 16
	v_and_b32_e32 v4, 24, v4
	v_and_b32_e32 v5, 4, v5
	s_addc_u32 s11, s35, s11
	s_add_i32 s36, s1, 0
	v_or3_b32 v4, v6, v5, v4
	v_add_lshl_u32 v1, v2, v1, 1
	s_add_i32 s37, s36, 0x10000
	s_mov_b32 m0, s37
	s_nop 0
	global_load_lds_dwordx4 v133, s[10:11]
	s_add_i32 s38, s36, 0x12000
	v_lshl_add_u32 v135, v4, 11, v1
	s_mov_b32 m0, s38
	s_nop 0
	global_load_lds_dwordx4 v135, s[10:11]
	s_add_u32 s12, s10, 0x40000
	s_addc_u32 s13, s11, 0
	s_add_i32 s40, s36, 0x14000
	s_mov_b32 m0, s40
	s_nop 0
	global_load_lds_dwordx4 v133, s[12:13]
	s_add_i32 s41, s36, 0x16000
	s_mov_b32 m0, s41
	s_nop 0
	global_load_lds_dwordx4 v135, s[12:13]
	s_add_u32 s12, s31, s2
	s_addc_u32 s13, s33, s3
	s_mov_b32 m0, s36
	s_nop 0
	global_load_lds_dwordx4 v132, s[12:13]
	s_add_i32 s42, s36, 0x2000
	v_lshl_add_u32 v134, v3, 11, v1
	s_mov_b32 m0, s42
	s_nop 0
	global_load_lds_dwordx4 v134, s[12:13]
	s_add_u32 s2, s12, 0x40000
	s_addc_u32 s3, s13, 0
	s_add_i32 s44, s36, 0x4000
	s_mov_b32 m0, s44
	s_nop 0
	global_load_lds_dwordx4 v132, s[2:3]
	s_add_i32 s45, s36, 0x6000
	s_mov_b32 m0, s45
	s_nop 0
	global_load_lds_dwordx4 v134, s[2:3]
	s_mov_b32 s39, 0
	s_cmp_lg_u32 s9, 1
	s_cbranch_scc1 .LBB0_1370
	s_barrier
.LBB0_1370:
	s_bfe_u32 s5, s91, 0x20006
	s_lshl_b32 s43, s9, 6
	s_sext_i32_i8 s8, s0
	s_add_u32 s0, s10, 0x80
	s_waitcnt vmcnt(2)
	s_barrier
	s_addc_u32 s1, s11, 0
	s_add_i32 s46, s36, 0x18000
	s_mov_b32 m0, s46
	s_nop 0
	global_load_lds_dwordx4 v133, s[0:1]
	s_add_i32 s47, s36, 0x1a000
	s_mov_b32 m0, s47
	s_nop 0
	global_load_lds_dwordx4 v135, s[0:1]
	s_add_u32 s0, s12, 0x80
	s_addc_u32 s1, s13, 0
	s_add_i32 s48, s36, 0x8000
	s_mov_b32 m0, s48
	s_nop 0
	global_load_lds_dwordx4 v132, s[0:1]
	s_add_i32 s49, s36, 0xa000
	s_mov_b32 m0, s49
	s_nop 0
	global_load_lds_dwordx4 v134, s[0:1]
	s_add_u32 s0, s10, 0x40080
	s_addc_u32 s1, s11, 0
	s_add_i32 s50, s36, 0x1c000
	s_mov_b32 m0, s50
	s_nop 0
	global_load_lds_dwordx4 v133, s[0:1]
	v_and_b32_e32 v136, 15, v190
	v_and_b32_e32 v1, 48, v190
	v_and_b32_e32 v0, 0xfffffc00, v0
	v_lshlrev_b32_e32 v3, 2, v190
	s_add_i32 s51, s36, 0x1e000
	s_mov_b32 m0, s51
	s_nop 0
	global_load_lds_dwordx4 v135, s[0:1]
	v_lshl_add_u32 v2, s9, 13, v0
	v_lshl_or_b32 v1, v136, 6, v1
	v_and_b32_e32 v3, 32, v3
	v_lshl_add_u32 v0, s5, 12, v0
	s_waitcnt vmcnt(6)
	v_bitop3_b32 v2, v1, v2, v3 bitop3:0xde
	v_bitop3_b32 v1, v1, v0, v3 bitop3:0xde
	v_mov_b32_e32 v0, 0
	v_or_b32_e32 v189, s43, v136
	s_add_i32 s52, s36, 0xc000
	s_add_i32 s53, s36, 0xe000
	v_mov_b64_e32 v[128:129], 0x100
	s_waitcnt lgkmcnt(0)
	v_mov_b64_e32 v[130:131], 0xff
	v_add_u32_e32 v137, 0, v1
	v_add_u32_e32 v138, 0, v2
	v_mov_b32_e32 v1, v0
	v_mov_b32_e32 v2, v0
	v_mov_b32_e32 v3, v0
	v_mov_b32_e32 v4, v0
	v_mov_b32_e32 v5, v0
	v_mov_b32_e32 v6, v0
	v_mov_b32_e32 v7, v0
	v_mov_b32_e32 v16, v0
	v_mov_b32_e32 v17, v0
	v_mov_b32_e32 v18, v0
	v_mov_b32_e32 v19, v0
	v_mov_b32_e32 v20, v0
	v_mov_b32_e32 v21, v0
	v_mov_b32_e32 v22, v0
	v_mov_b32_e32 v23, v0
	v_mov_b32_e32 v32, v0
	v_mov_b32_e32 v33, v0
	v_mov_b32_e32 v34, v0
	v_mov_b32_e32 v35, v0
	v_mov_b32_e32 v36, v0
	v_mov_b32_e32 v37, v0
	v_mov_b32_e32 v38, v0
	v_mov_b32_e32 v39, v0
	v_mov_b32_e32 v48, v0
	v_mov_b32_e32 v49, v0
	v_mov_b32_e32 v50, v0
	v_mov_b32_e32 v51, v0
	v_mov_b32_e32 v52, v0
	v_mov_b32_e32 v53, v0
	v_mov_b32_e32 v54, v0
	v_mov_b32_e32 v55, v0
	v_mov_b32_e32 v8, v0
	v_mov_b32_e32 v9, v0
	v_mov_b32_e32 v10, v0
	v_mov_b32_e32 v11, v0
	v_mov_b32_e32 v12, v0
	v_mov_b32_e32 v13, v0
	v_mov_b32_e32 v14, v0
	v_mov_b32_e32 v15, v0
	v_mov_b32_e32 v24, v0
	v_mov_b32_e32 v25, v0
	v_mov_b32_e32 v26, v0
	v_mov_b32_e32 v27, v0
	v_mov_b32_e32 v28, v0
	v_mov_b32_e32 v29, v0
	v_mov_b32_e32 v30, v0
	v_mov_b32_e32 v31, v0
	v_mov_b32_e32 v40, v0
	v_mov_b32_e32 v41, v0
	v_mov_b32_e32 v42, v0
	v_mov_b32_e32 v43, v0
	v_mov_b32_e32 v44, v0
	v_mov_b32_e32 v45, v0
	v_mov_b32_e32 v46, v0
	v_mov_b32_e32 v47, v0
	v_mov_b32_e32 v56, v0
	v_mov_b32_e32 v57, v0
	v_mov_b32_e32 v58, v0
	v_mov_b32_e32 v59, v0
	v_mov_b32_e32 v60, v0
	v_mov_b32_e32 v61, v0
	v_mov_b32_e32 v62, v0
	v_mov_b32_e32 v63, v0
	v_mov_b32_e32 v64, v0
	v_mov_b32_e32 v65, v0
	v_mov_b32_e32 v66, v0
	v_mov_b32_e32 v67, v0
	v_mov_b32_e32 v68, v0
	v_mov_b32_e32 v69, v0
	v_mov_b32_e32 v70, v0
	v_mov_b32_e32 v71, v0
	v_mov_b32_e32 v80, v0
	v_mov_b32_e32 v81, v0
	v_mov_b32_e32 v82, v0
	v_mov_b32_e32 v83, v0
	v_mov_b32_e32 v84, v0
	v_mov_b32_e32 v85, v0
	v_mov_b32_e32 v86, v0
	v_mov_b32_e32 v87, v0
	v_mov_b32_e32 v96, v0
	v_mov_b32_e32 v97, v0
	v_mov_b32_e32 v98, v0
	v_mov_b32_e32 v99, v0
	v_mov_b32_e32 v100, v0
	v_mov_b32_e32 v101, v0
	v_mov_b32_e32 v102, v0
	v_mov_b32_e32 v103, v0
	v_mov_b32_e32 v112, v0
	v_mov_b32_e32 v113, v0
	v_mov_b32_e32 v114, v0
	v_mov_b32_e32 v115, v0
	v_mov_b32_e32 v116, v0
	v_mov_b32_e32 v117, v0
	v_mov_b32_e32 v118, v0
	v_mov_b32_e32 v119, v0
	v_mov_b32_e32 v72, v0
	v_mov_b32_e32 v73, v0
	v_mov_b32_e32 v74, v0
	v_mov_b32_e32 v75, v0
	v_mov_b32_e32 v76, v0
	v_mov_b32_e32 v77, v0
	v_mov_b32_e32 v78, v0
	v_mov_b32_e32 v79, v0
	v_mov_b32_e32 v88, v0
	v_mov_b32_e32 v89, v0
	v_mov_b32_e32 v90, v0
	v_mov_b32_e32 v91, v0
	v_mov_b32_e32 v92, v0
	v_mov_b32_e32 v93, v0
	v_mov_b32_e32 v94, v0
	v_mov_b32_e32 v95, v0
	v_mov_b32_e32 v104, v0
	v_mov_b32_e32 v105, v0
	v_mov_b32_e32 v106, v0
	v_mov_b32_e32 v107, v0
	v_mov_b32_e32 v108, v0
	v_mov_b32_e32 v109, v0
	v_mov_b32_e32 v110, v0
	v_mov_b32_e32 v111, v0
	v_mov_b32_e32 v120, v0
	v_mov_b32_e32 v121, v0
	v_mov_b32_e32 v122, v0
	v_mov_b32_e32 v123, v0
	v_mov_b32_e32 v124, v0
	v_mov_b32_e32 v125, v0
	v_mov_b32_e32 v126, v0
	v_mov_b32_e32 v127, v0
	s_barrier
	s_branch .LBB0_1372

.LBB0_1379:
	s_add_u32 s58, s12, s22
	s_addc_u32 s59, s13, s23
	s_add_u32 s24, s58, 0x100
	v_add_u32_e32 v139, 0x10000, v137
	s_addc_u32 s25, s59, 0
	ds_read_b128 v[140:143], v139
	ds_read_b128 v[144:147], v139 offset:1024
	ds_read_b128 v[148:151], v139 offset:2048
	ds_read_b128 v[152:155], v139 offset:3072
	v_add_u32_e32 v139, 0x14000, v137
	s_add_u32 s26, s10, s22
	ds_read_b128 v[156:159], v139
	ds_read_b128 v[160:163], v139 offset:1024
	ds_read_b128 v[164:167], v139 offset:2048
	ds_read_b128 v[168:171], v139 offset:3072
	s_addc_u32 s27, s11, s23
	s_add_u32 s26, s26, 0x100
	s_addc_u32 s27, s27, 0
	s_cmp_eq_u32 s57, 12
	s_cselect_b32 s28, s55, s24
	s_cselect_b32 s29, s17, s25
	s_cselect_b32 s26, s56, s26
	s_cselect_b32 s27, s15, s27
	s_add_u32 s24, s28, 0x80
	s_addc_u32 s25, s29, 0
	ds_read_b128 v[172:175], v138
	ds_read_b128 v[176:179], v138 offset:1024
	ds_read_b128 v[180:183], v138 offset:2048
	ds_read_b128 v[184:187], v138 offset:3072
	s_waitcnt vmcnt(1)
	ds_read_b128 v[192:195], v138 offset:4096
	ds_read_b128 v[196:199], v138 offset:5120
	ds_read_b128 v[200:203], v138 offset:6144
	ds_read_b128 v[204:207], v138 offset:7168
	s_add_u32 s58, s58, 0x40080
	s_addc_u32 s59, s59, 0
	s_mov_b32 m0, s52
	s_nop 0
	global_load_lds_dwordx4 v132, s[58:59]
	s_nop 0
	s_mov_b32 m0, s53
	s_nop 0
	global_load_lds_dwordx4 v134, s[58:59]
	s_waitcnt vmcnt(8)
	s_waitcnt lgkmcnt(0)
	s_barrier
	s_setprio 1
	s_waitcnt lgkmcnt(7)
	v_mfma_f32_16x16x32_bf16 v[124:127], v[140:143], v[172:175], v[124:127]
	v_mfma_f32_16x16x32_bf16 v[120:123], v[148:151], v[172:175], v[120:123]
	s_waitcnt lgkmcnt(5)
	v_mfma_f32_16x16x32_bf16 v[108:111], v[140:143], v[180:183], v[108:111]
	v_mfma_f32_16x16x32_bf16 v[104:107], v[148:151], v[180:183], v[104:107]
	s_waitcnt lgkmcnt(3)
	v_mfma_f32_16x16x32_bf16 v[92:95], v[140:143], v[192:195], v[92:95]
	v_mfma_f32_16x16x32_bf16 v[88:91], v[148:151], v[192:195], v[88:91]
	s_waitcnt lgkmcnt(1)
	v_mfma_f32_16x16x32_bf16 v[76:79], v[140:143], v[200:203], v[76:79]
	v_mfma_f32_16x16x32_bf16 v[72:75], v[148:151], v[200:203], v[72:75]
	v_mfma_f32_16x16x32_bf16 v[124:127], v[144:147], v[176:179], v[124:127]
	v_mfma_f32_16x16x32_bf16 v[120:123], v[152:155], v[176:179], v[120:123]
	v_mfma_f32_16x16x32_bf16 v[108:111], v[144:147], v[184:187], v[108:111]
	v_mfma_f32_16x16x32_bf16 v[104:107], v[152:155], v[184:187], v[104:107]
	v_mfma_f32_16x16x32_bf16 v[92:95], v[144:147], v[196:199], v[92:95]
	v_mfma_f32_16x16x32_bf16 v[88:91], v[152:155], v[196:199], v[88:91]
	s_waitcnt lgkmcnt(0)
	v_mfma_f32_16x16x32_bf16 v[76:79], v[144:147], v[204:207], v[76:79]
	v_mfma_f32_16x16x32_bf16 v[72:75], v[152:155], v[204:207], v[72:75]
	s_setprio 0
	s_setprio 1
	v_mfma_f32_16x16x32_bf16 v[116:119], v[156:159], v[172:175], v[116:119]
	v_mfma_f32_16x16x32_bf16 v[112:115], v[164:167], v[172:175], v[112:115]
	v_mfma_f32_16x16x32_bf16 v[100:103], v[156:159], v[180:183], v[100:103]
	v_mfma_f32_16x16x32_bf16 v[96:99], v[164:167], v[180:183], v[96:99]
	v_mfma_f32_16x16x32_bf16 v[84:87], v[156:159], v[192:195], v[84:87]
	v_mfma_f32_16x16x32_bf16 v[80:83], v[164:167], v[192:195], v[80:83]
	v_mfma_f32_16x16x32_bf16 v[68:71], v[156:159], v[200:203], v[68:71]
	v_mfma_f32_16x16x32_bf16 v[64:67], v[164:167], v[200:203], v[64:67]
	v_mfma_f32_16x16x32_bf16 v[116:119], v[160:163], v[176:179], v[116:119]
	v_mfma_f32_16x16x32_bf16 v[112:115], v[168:171], v[176:179], v[112:115]
	v_mfma_f32_16x16x32_bf16 v[100:103], v[160:163], v[184:187], v[100:103]
	v_mfma_f32_16x16x32_bf16 v[96:99], v[168:171], v[184:187], v[96:99]
	v_mfma_f32_16x16x32_bf16 v[84:87], v[160:163], v[196:199], v[84:87]
	v_mfma_f32_16x16x32_bf16 v[80:83], v[168:171], v[196:199], v[80:83]
	v_mfma_f32_16x16x32_bf16 v[68:71], v[160:163], v[204:207], v[68:71]
	v_mfma_f32_16x16x32_bf16 v[64:67], v[168:171], v[204:207], v[64:67]
	s_setprio 0
	s_barrier
	ds_read_b128 v[172:175], v138 offset:16384
	ds_read_b128 v[176:179], v138 offset:17408
	ds_read_b128 v[180:183], v138 offset:18432
	ds_read_b128 v[184:187], v138 offset:19456
	ds_read_b128 v[192:195], v138 offset:20480
	ds_read_b128 v[196:199], v138 offset:21504
	ds_read_b128 v[200:203], v138 offset:22528
	ds_read_b128 v[204:207], v138 offset:23552
	s_mov_b32 m0, s37
	s_nop 0
	global_load_lds_dwordx4 v133, s[26:27]
	s_nop 0
	s_mov_b32 m0, s38
	s_nop 0
	global_load_lds_dwordx4 v135, s[26:27]
	s_add_u32 s58, s26, 0x40000
	s_addc_u32 s59, s27, 0
	s_mov_b32 m0, s40
	s_nop 0
	global_load_lds_dwordx4 v133, s[58:59]
	s_nop 0
	s_mov_b32 m0, s41
	s_nop 0
	global_load_lds_dwordx4 v135, s[58:59]
	s_mov_b32 m0, s36
	s_nop 0
	global_load_lds_dwordx4 v132, s[28:29]
	s_nop 0
	s_mov_b32 m0, s42
	s_nop 0
	global_load_lds_dwordx4 v134, s[28:29]
	s_waitcnt vmcnt(8)
	s_waitcnt lgkmcnt(0)
	s_barrier
	s_setprio 1
	s_waitcnt lgkmcnt(7)
	v_mfma_f32_16x16x32_bf16 v[60:63], v[140:143], v[172:175], v[60:63]
	v_mfma_f32_16x16x32_bf16 v[56:59], v[148:151], v[172:175], v[56:59]
	s_waitcnt lgkmcnt(5)
	v_mfma_f32_16x16x32_bf16 v[44:47], v[140:143], v[180:183], v[44:47]
	v_mfma_f32_16x16x32_bf16 v[40:43], v[148:151], v[180:183], v[40:43]
	s_waitcnt lgkmcnt(3)
	v_mfma_f32_16x16x32_bf16 v[28:31], v[140:143], v[192:195], v[28:31]
	v_mfma_f32_16x16x32_bf16 v[24:27], v[148:151], v[192:195], v[24:27]
	s_waitcnt lgkmcnt(1)
	v_mfma_f32_16x16x32_bf16 v[12:15], v[140:143], v[200:203], v[12:15]
	v_mfma_f32_16x16x32_bf16 v[8:11], v[148:151], v[200:203], v[8:11]
	v_mfma_f32_16x16x32_bf16 v[60:63], v[144:147], v[176:179], v[60:63]
	v_mfma_f32_16x16x32_bf16 v[56:59], v[152:155], v[176:179], v[56:59]
	v_mfma_f32_16x16x32_bf16 v[44:47], v[144:147], v[184:187], v[44:47]
	v_mfma_f32_16x16x32_bf16 v[40:43], v[152:155], v[184:187], v[40:43]
	v_mfma_f32_16x16x32_bf16 v[28:31], v[144:147], v[196:199], v[28:31]
	v_mfma_f32_16x16x32_bf16 v[24:27], v[152:155], v[196:199], v[24:27]
	s_waitcnt lgkmcnt(0)
	v_mfma_f32_16x16x32_bf16 v[12:15], v[144:147], v[204:207], v[12:15]
	v_mfma_f32_16x16x32_bf16 v[8:11], v[152:155], v[204:207], v[8:11]
	s_setprio 0
	s_setprio 1
	v_mfma_f32_16x16x32_bf16 v[52:55], v[156:159], v[172:175], v[52:55]
	v_mfma_f32_16x16x32_bf16 v[48:51], v[164:167], v[172:175], v[48:51]
	v_mfma_f32_16x16x32_bf16 v[36:39], v[156:159], v[180:183], v[36:39]
	v_mfma_f32_16x16x32_bf16 v[32:35], v[164:167], v[180:183], v[32:35]
	v_mfma_f32_16x16x32_bf16 v[20:23], v[156:159], v[192:195], v[20:23]
	v_mfma_f32_16x16x32_bf16 v[16:19], v[164:167], v[192:195], v[16:19]
	v_mfma_f32_16x16x32_bf16 v[4:7], v[156:159], v[200:203], v[4:7]
	v_mfma_f32_16x16x32_bf16 v[0:3], v[164:167], v[200:203], v[0:3]
	v_mfma_f32_16x16x32_bf16 v[52:55], v[160:163], v[176:179], v[52:55]
	v_mfma_f32_16x16x32_bf16 v[48:51], v[168:171], v[176:179], v[48:51]
	v_mfma_f32_16x16x32_bf16 v[36:39], v[160:163], v[184:187], v[36:39]
	v_mfma_f32_16x16x32_bf16 v[32:35], v[168:171], v[184:187], v[32:35]
	v_mfma_f32_16x16x32_bf16 v[20:23], v[160:163], v[196:199], v[20:23]
	v_mfma_f32_16x16x32_bf16 v[16:19], v[168:171], v[196:199], v[16:19]
	v_mfma_f32_16x16x32_bf16 v[4:7], v[160:163], v[204:207], v[4:7]
	v_mfma_f32_16x16x32_bf16 v[0:3], v[168:171], v[204:207], v[0:3]
	s_setprio 0
	s_barrier
	v_add_u32_e32 v139, 0x18000, v137
	ds_read_b128 v[140:143], v139
	ds_read_b128 v[144:147], v139 offset:1024
	ds_read_b128 v[148:151], v139 offset:2048
	ds_read_b128 v[152:155], v139 offset:3072
	v_add_u32_e32 v139, 0x1c000, v137
	ds_read_b128 v[156:159], v139
	ds_read_b128 v[160:163], v139 offset:1024
	ds_read_b128 v[164:167], v139 offset:2048
	ds_read_b128 v[168:171], v139 offset:3072
	ds_read_b128 v[172:175], v138 offset:32768
	ds_read_b128 v[176:179], v138 offset:33792
	ds_read_b128 v[180:183], v138 offset:34816
	ds_read_b128 v[184:187], v138 offset:35840
	ds_read_b128 v[192:195], v138 offset:36864
	ds_read_b128 v[196:199], v138 offset:37888
	ds_read_b128 v[200:203], v138 offset:38912
	ds_read_b128 v[204:207], v138 offset:39936
	s_add_u32 s28, s28, 0x40000
	s_addc_u32 s29, s29, 0
	s_mov_b32 m0, s44
	s_nop 0
	global_load_lds_dwordx4 v132, s[28:29]
	s_nop 0
	s_mov_b32 m0, s45
	s_nop 0
	global_load_lds_dwordx4 v134, s[28:29]
	s_waitcnt vmcnt(8)
	s_waitcnt lgkmcnt(0)
	s_barrier
	s_setprio 1
	s_waitcnt lgkmcnt(7)
	v_mfma_f32_16x16x32_bf16 v[124:127], v[140:143], v[172:175], v[124:127]
	v_mfma_f32_16x16x32_bf16 v[120:123], v[148:151], v[172:175], v[120:123]
	s_waitcnt lgkmcnt(5)
	v_mfma_f32_16x16x32_bf16 v[108:111], v[140:143], v[180:183], v[108:111]
	v_mfma_f32_16x16x32_bf16 v[104:107], v[148:151], v[180:183], v[104:107]
	s_waitcnt lgkmcnt(3)
	v_mfma_f32_16x16x32_bf16 v[92:95], v[140:143], v[192:195], v[92:95]
	v_mfma_f32_16x16x32_bf16 v[88:91], v[148:151], v[192:195], v[88:91]
	s_waitcnt lgkmcnt(1)
	v_mfma_f32_16x16x32_bf16 v[76:79], v[140:143], v[200:203], v[76:79]
	v_mfma_f32_16x16x32_bf16 v[72:75], v[148:151], v[200:203], v[72:75]
	v_mfma_f32_16x16x32_bf16 v[124:127], v[144:147], v[176:179], v[124:127]
	v_mfma_f32_16x16x32_bf16 v[120:123], v[152:155], v[176:179], v[120:123]
	v_mfma_f32_16x16x32_bf16 v[108:111], v[144:147], v[184:187], v[108:111]
	v_mfma_f32_16x16x32_bf16 v[104:107], v[152:155], v[184:187], v[104:107]
	v_mfma_f32_16x16x32_bf16 v[92:95], v[144:147], v[196:199], v[92:95]
	v_mfma_f32_16x16x32_bf16 v[88:91], v[152:155], v[196:199], v[88:91]
	s_waitcnt lgkmcnt(0)
	v_mfma_f32_16x16x32_bf16 v[76:79], v[144:147], v[204:207], v[76:79]
	v_mfma_f32_16x16x32_bf16 v[72:75], v[152:155], v[204:207], v[72:75]
	s_setprio 0
	s_setprio 1
	v_mfma_f32_16x16x32_bf16 v[116:119], v[156:159], v[172:175], v[116:119]
	v_mfma_f32_16x16x32_bf16 v[112:115], v[164:167], v[172:175], v[112:115]
	v_mfma_f32_16x16x32_bf16 v[100:103], v[156:159], v[180:183], v[100:103]
	v_mfma_f32_16x16x32_bf16 v[96:99], v[164:167], v[180:183], v[96:99]
	v_mfma_f32_16x16x32_bf16 v[84:87], v[156:159], v[192:195], v[84:87]
	v_mfma_f32_16x16x32_bf16 v[80:83], v[164:167], v[192:195], v[80:83]
	v_mfma_f32_16x16x32_bf16 v[68:71], v[156:159], v[200:203], v[68:71]
	v_mfma_f32_16x16x32_bf16 v[64:67], v[164:167], v[200:203], v[64:67]
	v_mfma_f32_16x16x32_bf16 v[116:119], v[160:163], v[176:179], v[116:119]
	v_mfma_f32_16x16x32_bf16 v[112:115], v[168:171], v[176:179], v[112:115]
	v_mfma_f32_16x16x32_bf16 v[100:103], v[160:163], v[184:187], v[100:103]
	v_mfma_f32_16x16x32_bf16 v[96:99], v[168:171], v[184:187], v[96:99]
	v_mfma_f32_16x16x32_bf16 v[84:87], v[160:163], v[196:199], v[84:87]
	v_mfma_f32_16x16x32_bf16 v[80:83], v[168:171], v[196:199], v[80:83]
	v_mfma_f32_16x16x32_bf16 v[68:71], v[160:163], v[204:207], v[68:71]
	v_mfma_f32_16x16x32_bf16 v[64:67], v[168:171], v[204:207], v[64:67]
	s_setprio 0
	s_barrier
	ds_read_b128 v[172:175], v138 offset:49152
	ds_read_b128 v[176:179], v138 offset:50176
	ds_read_b128 v[180:183], v138 offset:51200
	ds_read_b128 v[184:187], v138 offset:52224
	ds_read_b128 v[192:195], v138 offset:53248
	ds_read_b128 v[196:199], v138 offset:54272
	ds_read_b128 v[200:203], v138 offset:55296
	ds_read_b128 v[204:207], v138 offset:56320
	s_add_u32 s28, s26, 0x80
	s_addc_u32 s29, s27, 0
	s_mov_b32 m0, s46
	s_nop 0
	global_load_lds_dwordx4 v133, s[28:29]
	s_add_u32 s26, s26, 0x40080
	s_mov_b32 m0, s47
	s_nop 0
	global_load_lds_dwordx4 v135, s[28:29]
	s_addc_u32 s27, s27, 0
	s_mov_b32 m0, s50
	s_nop 0
	global_load_lds_dwordx4 v133, s[26:27]
	s_nop 0
	s_mov_b32 m0, s51
	s_nop 0
	global_load_lds_dwordx4 v135, s[26:27]
	s_mov_b32 m0, s48
	s_nop 0
	global_load_lds_dwordx4 v132, s[24:25]
	s_nop 0
	s_mov_b32 m0, s49
	s_nop 0
	global_load_lds_dwordx4 v134, s[24:25]
	s_waitcnt vmcnt(8)
	s_waitcnt lgkmcnt(0)
	s_barrier
	s_setprio 1
	s_waitcnt lgkmcnt(7)
	v_mfma_f32_16x16x32_bf16 v[60:63], v[140:143], v[172:175], v[60:63]
	v_mfma_f32_16x16x32_bf16 v[56:59], v[148:151], v[172:175], v[56:59]
	s_waitcnt lgkmcnt(5)
	v_mfma_f32_16x16x32_bf16 v[44:47], v[140:143], v[180:183], v[44:47]
	v_mfma_f32_16x16x32_bf16 v[40:43], v[148:151], v[180:183], v[40:43]
	s_waitcnt lgkmcnt(3)
	v_mfma_f32_16x16x32_bf16 v[28:31], v[140:143], v[192:195], v[28:31]
	v_mfma_f32_16x16x32_bf16 v[24:27], v[148:151], v[192:195], v[24:27]
	s_waitcnt lgkmcnt(1)
	v_mfma_f32_16x16x32_bf16 v[12:15], v[140:143], v[200:203], v[12:15]
	v_mfma_f32_16x16x32_bf16 v[8:11], v[148:151], v[200:203], v[8:11]
	v_mfma_f32_16x16x32_bf16 v[60:63], v[144:147], v[176:179], v[60:63]
	v_mfma_f32_16x16x32_bf16 v[56:59], v[152:155], v[176:179], v[56:59]
	v_mfma_f32_16x16x32_bf16 v[44:47], v[144:147], v[184:187], v[44:47]
	v_mfma_f32_16x16x32_bf16 v[40:43], v[152:155], v[184:187], v[40:43]
	v_mfma_f32_16x16x32_bf16 v[28:31], v[144:147], v[196:199], v[28:31]
	v_mfma_f32_16x16x32_bf16 v[24:27], v[152:155], v[196:199], v[24:27]
	s_waitcnt lgkmcnt(0)
	v_mfma_f32_16x16x32_bf16 v[12:15], v[144:147], v[204:207], v[12:15]
	v_mfma_f32_16x16x32_bf16 v[8:11], v[152:155], v[204:207], v[8:11]
	s_setprio 0
	s_setprio 1
	v_mfma_f32_16x16x32_bf16 v[52:55], v[156:159], v[172:175], v[52:55]
	v_mfma_f32_16x16x32_bf16 v[48:51], v[164:167], v[172:175], v[48:51]
	v_mfma_f32_16x16x32_bf16 v[36:39], v[156:159], v[180:183], v[36:39]
	v_mfma_f32_16x16x32_bf16 v[32:35], v[164:167], v[180:183], v[32:35]
	v_mfma_f32_16x16x32_bf16 v[20:23], v[156:159], v[192:195], v[20:23]
	v_mfma_f32_16x16x32_bf16 v[16:19], v[164:167], v[192:195], v[16:19]
	v_mfma_f32_16x16x32_bf16 v[4:7], v[156:159], v[200:203], v[4:7]
	v_mfma_f32_16x16x32_bf16 v[0:3], v[164:167], v[200:203], v[0:3]
	v_mfma_f32_16x16x32_bf16 v[52:55], v[160:163], v[176:179], v[52:55]
	v_mfma_f32_16x16x32_bf16 v[48:51], v[168:171], v[176:179], v[48:51]
	v_mfma_f32_16x16x32_bf16 v[36:39], v[160:163], v[184:187], v[36:39]
	v_mfma_f32_16x16x32_bf16 v[32:35], v[168:171], v[184:187], v[32:35]
	v_mfma_f32_16x16x32_bf16 v[20:23], v[160:163], v[196:199], v[20:23]
	v_mfma_f32_16x16x32_bf16 v[16:19], v[168:171], v[196:199], v[16:19]
	v_mfma_f32_16x16x32_bf16 v[4:7], v[160:163], v[204:207], v[4:7]
	v_mfma_f32_16x16x32_bf16 v[0:3], v[168:171], v[204:207], v[0:3]
	s_setprio 0
	s_barrier
	s_add_i32 s57, s57, 2
	s_add_u32 s22, s22, 0x100
	s_addc_u32 s23, s23, 0
	s_cmp_gt_u32 s57, 13
	s_cbranch_scc0 .LBB0_1379
	s_andn2_b64 vcc, exec, s[2:3]
	s_cbranch_vccnz .LBB0_1371
	v_mov_b32_e32 v0, 0
	s_mov_b32 s8, s14
	s_mov_b32 s4, s16
	s_mov_b64 s[10:11], s[20:21]
	s_mov_b64 s[12:13], s[18:19]
	s_mov_b32 s39, s54
	v_mov_b32_e32 v1, v0
	v_mov_b32_e32 v2, v0
	v_mov_b32_e32 v3, v0
	v_mov_b32_e32 v4, v0
	v_mov_b32_e32 v5, v0
	v_mov_b32_e32 v6, v0
	v_mov_b32_e32 v7, v0
	v_mov_b32_e32 v16, v0
	v_mov_b32_e32 v17, v0
	v_mov_b32_e32 v18, v0
	v_mov_b32_e32 v19, v0
	v_mov_b32_e32 v20, v0
	v_mov_b32_e32 v21, v0
	v_mov_b32_e32 v22, v0
	v_mov_b32_e32 v23, v0
	v_mov_b32_e32 v32, v0
	v_mov_b32_e32 v33, v0
	v_mov_b32_e32 v34, v0
	v_mov_b32_e32 v35, v0
	v_mov_b32_e32 v36, v0
	v_mov_b32_e32 v37, v0
	v_mov_b32_e32 v38, v0
	v_mov_b32_e32 v39, v0
	v_mov_b32_e32 v48, v0
	v_mov_b32_e32 v49, v0
	v_mov_b32_e32 v50, v0
	v_mov_b32_e32 v51, v0
	v_mov_b32_e32 v52, v0
	v_mov_b32_e32 v53, v0
	v_mov_b32_e32 v54, v0
	v_mov_b32_e32 v55, v0
	v_mov_b32_e32 v8, v0
	v_mov_b32_e32 v9, v0
	v_mov_b32_e32 v10, v0
	v_mov_b32_e32 v11, v0
	v_mov_b32_e32 v12, v0
	v_mov_b32_e32 v13, v0
	v_mov_b32_e32 v14, v0
	v_mov_b32_e32 v15, v0
	v_mov_b32_e32 v24, v0
	v_mov_b32_e32 v25, v0
	v_mov_b32_e32 v26, v0
	v_mov_b32_e32 v27, v0
	v_mov_b32_e32 v28, v0
	v_mov_b32_e32 v29, v0
	v_mov_b32_e32 v30, v0
	v_mov_b32_e32 v31, v0
	v_mov_b32_e32 v40, v0
	v_mov_b32_e32 v41, v0
	v_mov_b32_e32 v42, v0
	v_mov_b32_e32 v43, v0
	v_mov_b32_e32 v44, v0
	v_mov_b32_e32 v45, v0
	v_mov_b32_e32 v46, v0
	v_mov_b32_e32 v47, v0
	v_mov_b32_e32 v56, v0
	v_mov_b32_e32 v57, v0
	v_mov_b32_e32 v58, v0
	v_mov_b32_e32 v59, v0
	v_mov_b32_e32 v60, v0
	v_mov_b32_e32 v61, v0
	v_mov_b32_e32 v62, v0
	v_mov_b32_e32 v63, v0
	v_mov_b32_e32 v64, v0
	v_mov_b32_e32 v65, v0
	v_mov_b32_e32 v66, v0
	v_mov_b32_e32 v67, v0
	v_mov_b32_e32 v68, v0
	v_mov_b32_e32 v69, v0
	v_mov_b32_e32 v70, v0
	v_mov_b32_e32 v71, v0
	v_mov_b32_e32 v80, v0
	v_mov_b32_e32 v81, v0
	v_mov_b32_e32 v82, v0
	v_mov_b32_e32 v83, v0
	v_mov_b32_e32 v84, v0
	v_mov_b32_e32 v85, v0
	v_mov_b32_e32 v86, v0
	v_mov_b32_e32 v87, v0
	v_mov_b32_e32 v96, v0
	v_mov_b32_e32 v97, v0
	v_mov_b32_e32 v98, v0
	v_mov_b32_e32 v99, v0
	v_mov_b32_e32 v100, v0
	v_mov_b32_e32 v101, v0
	v_mov_b32_e32 v102, v0
	v_mov_b32_e32 v103, v0
	v_mov_b32_e32 v112, v0
	v_mov_b32_e32 v113, v0
	v_mov_b32_e32 v114, v0
	v_mov_b32_e32 v115, v0
	v_mov_b32_e32 v116, v0
	v_mov_b32_e32 v117, v0
	v_mov_b32_e32 v118, v0
	v_mov_b32_e32 v119, v0
	v_mov_b32_e32 v72, v0
	v_mov_b32_e32 v73, v0
	v_mov_b32_e32 v74, v0
	v_mov_b32_e32 v75, v0
	v_mov_b32_e32 v76, v0
	v_mov_b32_e32 v77, v0
	v_mov_b32_e32 v78, v0
	v_mov_b32_e32 v79, v0
	v_mov_b32_e32 v88, v0
	v_mov_b32_e32 v89, v0
	v_mov_b32_e32 v90, v0
	v_mov_b32_e32 v91, v0
	v_mov_b32_e32 v92, v0
	v_mov_b32_e32 v93, v0
	v_mov_b32_e32 v94, v0
	v_mov_b32_e32 v95, v0
	v_mov_b32_e32 v104, v0
	v_mov_b32_e32 v105, v0
	v_mov_b32_e32 v106, v0
	v_mov_b32_e32 v107, v0
	v_mov_b32_e32 v108, v0
	v_mov_b32_e32 v109, v0
	v_mov_b32_e32 v110, v0
	v_mov_b32_e32 v111, v0
	v_mov_b32_e32 v120, v0
	v_mov_b32_e32 v121, v0
	v_mov_b32_e32 v122, v0
	v_mov_b32_e32 v123, v0
	v_mov_b32_e32 v124, v0
	v_mov_b32_e32 v125, v0
	v_mov_b32_e32 v126, v0
	v_mov_b32_e32 v127, v0
	s_branch .LBB0_1371
